# v34 + SALU rebalanced out of the heaviest load segment: next-tile address select group moved Ph1-L->Ph2-L, loop-counter updates moved into Ph8-L; bit-identical
# speedup vs baseline: 1.0046x; 1.0046x over previous
; #define PG8_WAIT_L(n) asm volatile("s_waitcnt lgkmcnt(" #n ")" ::: "memory")
; #define PG8_BAR __builtin_amdgcn_s_barrier()
; #define PG8_SCHED __builtin_amdgcn_sched_barrier(0)
; template <class Epi, class AddrA, class AddrB>
; __device__ __forceinline__ void gemm_phase(const Sched S, const int lda, const int ldb, const int K, const AddrA addrA,
;                                            const AddrB addrB, const Epi E) {
;     ...
;   for (;;) {
;     const bool has_next = S.next(ui + 1, nxt);
;     const char* nA = has_next ? addrA(nxt) : cA;
;     const char* nB = has_next ? addrB(nxt) : cB;
;     for (int t = 0; t < nt; t += 2) {
;       const bool last = (t == nt - 2);
;       const char* a1 = cA + (size_t)(t + 1) * kstep;
;       const char* a2 = last ? nA : cA + (size_t)(t + 2) * kstep;
;       const char* b2 = last ? nB : cB + (size_t)(t + 2) * kstep;
;       const char* a3 = a2 + kstep;
;       const char* b3 = b2 + kstep;
;       PG8_LDB(B0, 0, 0); PG8_SCHED; PG8_LDA(At, 0, 0); PG8_STAGE(PG8_SA(1, 1), a1 + hstepA, voffA);
;       PG8_WAIT_L(8); PG8_BAR; PG8_WAIT_L(0); PG8_MMA(0, 0, At, B0); PG8_BAR; PG8_SCHED;
;       PG8_LDB(B1, 0, 1); PG8_STAGE(PG8_SB(0, 0), b2, voffB);
;       PG8_BAR; PG8_WAIT_L(0); PG8_MMA(0, 1, At, B1); PG8_BAR;
;       PG8_LDA(At, 0, 1); PG8_STAGE(PG8_SA(0, 0), a2, voffA);
;       PG8_BAR; PG8_WAIT_L(0); PG8_MMA(1, 0, At, B0); PG8_BAR; PG8_SCHED;
.LBB0_108:
	s_ashr_i32 s1, s0, 31
	s_lshl_b64 s[6:7], s[0:1], 20
	s_add_u32 s6, s20, s6
	s_addc_u32 s7, s21, s7
	s_and_b64 s[8:9], s[16:17], exec
	s_cselect_b32 s1, s7, s15
	s_cselect_b32 s11, s6, s14
	s_ashr_i32 s3, s2, 31
	s_lshl_b64 s[8:9], s[2:3], 20
	s_add_u32 s8, s22, s8
	s_addc_u32 s9, s23, s9
	s_and_b64 s[16:17], s[16:17], exec
	s_cselect_b32 s3, s9, s13
	s_cselect_b32 s36, s8, s12
	s_add_u32 s37, s12, 0x100
	s_addc_u32 s38, s13, 0
	s_add_u32 s12, s14, 0x80080
	s_addc_u32 s13, s15, 0
	s_mov_b32 s39, -2
	s_add_i32 s40, 0, 0x10000
	v_add_u32_e32 v142, s40, v145
	ds_read_b128 v[148:151], v142
	ds_read_b128 v[152:155], v142 offset:1024
	ds_read_b128 v[156:159], v142 offset:2048
	ds_read_b128 v[160:163], v142 offset:3072
	v_lshl_add_u64 v[142:143], s[12:13], 0, v[140:141]
	s_add_i32 m0, s24, 0xc000
	ds_read_b128 v[168:171], v146
	ds_read_b128 v[172:175], v146 offset:1024
	ds_read_b128 v[176:179], v146 offset:2048
	ds_read_b128 v[180:183], v146 offset:3072
	ds_read_b128 v[184:187], v146 offset:4096
	ds_read_b128 v[188:191], v146 offset:5120
	ds_read_b128 v[192:195], v146 offset:6144
	ds_read_b128 v[212:215], v146 offset:7168
	global_load_lds_dwordx4 v[142:143], off
	v_lshl_add_u64 v[142:143], s[12:13], 0, v[138:139]
	s_add_i32 m0, s24, 0xe000
	s_nop 0
	global_load_lds_dwordx4 v[142:143], off
	s_waitcnt lgkmcnt(8)
	s_setprio 1
	s_barrier
	s_waitcnt lgkmcnt(0)
	v_mfma_f32_16x16x32_bf16 v[128:131], v[148:151], v[168:171], 0
	v_mfma_f32_16x16x32_bf16 v[128:131], v[152:155], v[172:175], v[128:131]
	v_mfma_f32_16x16x32_bf16 v[120:123], v[148:151], v[176:179], 0
	v_mfma_f32_16x16x32_bf16 v[120:123], v[152:155], v[180:183], v[120:123]
	v_mfma_f32_16x16x32_bf16 v[104:107], v[148:151], v[184:187], 0
	v_mfma_f32_16x16x32_bf16 v[104:107], v[152:155], v[188:191], v[104:107]
	v_mfma_f32_16x16x32_bf16 v[88:91], v[148:151], v[192:195], 0
	v_mfma_f32_16x16x32_bf16 v[88:91], v[152:155], v[212:215], v[88:91]
	v_mfma_f32_16x16x32_bf16 v[124:127], v[156:159], v[168:171], 0
	v_mfma_f32_16x16x32_bf16 v[124:127], v[160:163], v[172:175], v[124:127]
	v_mfma_f32_16x16x32_bf16 v[112:115], v[156:159], v[176:179], 0
	v_mfma_f32_16x16x32_bf16 v[112:115], v[160:163], v[180:183], v[112:115]
	v_mfma_f32_16x16x32_bf16 v[96:99], v[156:159], v[184:187], 0
	v_mfma_f32_16x16x32_bf16 v[96:99], v[160:163], v[188:191], v[96:99]
	v_mfma_f32_16x16x32_bf16 v[80:83], v[156:159], v[192:195], 0
	v_mfma_f32_16x16x32_bf16 v[80:83], v[160:163], v[212:215], v[80:83]
	s_barrier
	s_setprio 0
	s_add_u32 s14, s12, 0xfff80080
	s_addc_u32 s15, s13, -1
	s_cmp_eq_u32 s39, 28
	s_cselect_b32 s17, s1, s15
	s_cselect_b32 s16, s11, s14
	s_cselect_b32 s15, s3, s38
	s_cselect_b32 s14, s36, s37
	s_add_i32 s42, 0, 0x14000
	v_add_u32_e32 v142, s42, v145
	s_add_i32 s40, s40, s19
	ds_read_b128 v[216:219], v142
	ds_read_b128 v[220:223], v142 offset:1024
	ds_read_b128 v[224:227], v142 offset:2048
	ds_read_b128 v[228:231], v142 offset:3072
	v_lshl_add_u64 v[142:143], s[14:15], 0, v[134:135]
	s_mov_b32 m0, s40
	v_lshl_add_u64 v[196:197], s[14:15], 0, v[0:1]
	global_load_lds_dwordx4 v[142:143], off
	s_add_i32 m0, s40, 0x2000
	s_nop 0
	global_load_lds_dwordx4 v[196:197], off
	s_setprio 1
	s_barrier
	s_waitcnt lgkmcnt(0)
	v_mfma_f32_16x16x32_bf16 v[116:119], v[216:219], v[168:171], 0
	v_mfma_f32_16x16x32_bf16 v[116:119], v[220:223], v[172:175], v[116:119]
	v_mfma_f32_16x16x32_bf16 v[100:103], v[216:219], v[176:179], 0
	v_mfma_f32_16x16x32_bf16 v[100:103], v[220:223], v[180:183], v[100:103]
	v_mfma_f32_16x16x32_bf16 v[84:87], v[216:219], v[184:187], 0
	v_mfma_f32_16x16x32_bf16 v[84:87], v[220:223], v[188:191], v[84:87]
	v_mfma_f32_16x16x32_bf16 v[72:75], v[216:219], v[192:195], 0
	v_mfma_f32_16x16x32_bf16 v[72:75], v[220:223], v[212:215], v[72:75]
	v_mfma_f32_16x16x32_bf16 v[108:111], v[224:227], v[168:171], 0
	v_mfma_f32_16x16x32_bf16 v[108:111], v[228:231], v[172:175], v[108:111]
	v_mfma_f32_16x16x32_bf16 v[92:95], v[224:227], v[176:179], 0
	v_mfma_f32_16x16x32_bf16 v[92:95], v[228:231], v[180:183], v[92:95]
	v_mfma_f32_16x16x32_bf16 v[76:79], v[224:227], v[184:187], 0
	v_mfma_f32_16x16x32_bf16 v[76:79], v[228:231], v[188:191], v[76:79]
	v_mfma_f32_16x16x32_bf16 v[68:71], v[224:227], v[192:195], 0
	v_mfma_f32_16x16x32_bf16 v[68:71], v[228:231], v[212:215], v[68:71]
	s_barrier
	s_setprio 0
	s_mov_b32 m0, s24
	v_lshl_add_u64 v[232:233], s[16:17], 0, v[136:137]
	ds_read_b128 v[168:171], v146 offset:16384
	ds_read_b128 v[172:175], v146 offset:17408
	ds_read_b128 v[176:179], v146 offset:18432
	ds_read_b128 v[180:183], v146 offset:19456
	ds_read_b128 v[184:187], v146 offset:20480
	ds_read_b128 v[188:191], v146 offset:21504
	ds_read_b128 v[192:195], v146 offset:22528
	ds_read_b128 v[212:215], v146 offset:23552
	global_load_lds_dwordx4 v[232:233], off
	v_lshl_add_u64 v[234:235], s[16:17], 0, v[132:133]
	s_mov_b32 m0, s25
	s_nop 0
	global_load_lds_dwordx4 v[234:235], off
	s_setprio 1
	s_barrier
	s_waitcnt lgkmcnt(0)
	v_mfma_f32_16x16x32_bf16 v[64:67], v[148:151], v[168:171], 0
	v_mfma_f32_16x16x32_bf16 v[64:67], v[152:155], v[172:175], v[64:67]
	v_mfma_f32_16x16x32_bf16 v[56:59], v[148:151], v[176:179], 0
	v_mfma_f32_16x16x32_bf16 v[56:59], v[152:155], v[180:183], v[56:59]
	v_mfma_f32_16x16x32_bf16 v[40:43], v[148:151], v[184:187], 0
	v_mfma_f32_16x16x32_bf16 v[40:43], v[152:155], v[188:191], v[40:43]
	v_mfma_f32_16x16x32_bf16 v[24:27], v[148:151], v[192:195], 0
	v_mfma_f32_16x16x32_bf16 v[24:27], v[152:155], v[212:215], v[24:27]
	v_mfma_f32_16x16x32_bf16 v[60:63], v[156:159], v[168:171], 0
	v_mfma_f32_16x16x32_bf16 v[60:63], v[160:163], v[172:175], v[60:63]
	v_mfma_f32_16x16x32_bf16 v[48:51], v[156:159], v[176:179], 0
	v_mfma_f32_16x16x32_bf16 v[48:51], v[160:163], v[180:183], v[48:51]
	v_mfma_f32_16x16x32_bf16 v[32:35], v[156:159], v[184:187], 0
	v_mfma_f32_16x16x32_bf16 v[32:35], v[160:163], v[188:191], v[32:35]
	v_mfma_f32_16x16x32_bf16 v[16:19], v[156:159], v[192:195], 0
	v_mfma_f32_16x16x32_bf16 v[16:19], v[160:163], v[212:215], v[16:19]
	s_barrier
; #define PG8_WAIT_V(n) asm volatile("s_waitcnt vmcnt(" #n ")" ::: "memory")
; #define PG8_WAIT_L(n) asm volatile("s_waitcnt lgkmcnt(" #n ")" ::: "memory")
; #define PG8_BAR __builtin_amdgcn_s_barrier()
; #define PG8_SCHED __builtin_amdgcn_sched_barrier(0)
; template <class Epi, class AddrA, class AddrB>
; __device__ __forceinline__ void gemm_phase(const Sched S, const int lda, const int ldb, const int K, const AddrA addrA,
;                                            const AddrB addrB, const Epi E) {
;     ...
;       PG8_BAR; PG8_WAIT_L(0); PG8_MMA(1, 0, At, B0); PG8_BAR; PG8_SCHED;
;       PG8_STAGE(PG8_SB(0, 1), b2 + hstepB, voffB);
;       PG8_WAIT_V(6); PG8_BAR; PG8_MMA(1, 1, At, B1); PG8_BAR;
;       PG8_LDB(B0, 1, 0); PG8_SCHED; PG8_LDA(At, 1, 0); PG8_STAGE(PG8_SA(0, 1), a2 + hstepA, voffA);
;       PG8_WAIT_L(8); PG8_BAR; PG8_WAIT_L(0); PG8_MMA(0, 0, At, B0); PG8_BAR; PG8_SCHED;
;       PG8_LDB(B1, 1, 1); PG8_STAGE(PG8_SB(1, 0), b3, voffB);
;       PG8_BAR; PG8_WAIT_L(0); PG8_MMA(0, 1, At, B1); PG8_BAR;
;       PG8_LDA(At, 1, 1); PG8_STAGE(PG8_SA(1, 0), a3, voffA);
;       PG8_BAR; PG8_WAIT_L(0); PG8_MMA(1, 0, At, B0); PG8_BAR; PG8_SCHED;
	s_setprio 0
	s_add_u32 s40, s14, 0x80000
	s_addc_u32 s41, s15, 0
	s_add_i32 s42, s42, s19
	v_lshl_add_u64 v[148:149], s[40:41], 0, v[134:135]
	s_mov_b32 m0, s42
	s_nop 0
	global_load_lds_dwordx4 v[148:149], off
	v_lshl_add_u64 v[148:149], s[40:41], 0, v[0:1]
	s_add_i32 m0, s42, 0x2000
	s_nop 0
	global_load_lds_dwordx4 v[148:149], off
	s_waitcnt vmcnt(6)
	s_setprio 1
	s_barrier
	v_mfma_f32_16x16x32_bf16 v[52:55], v[216:219], v[168:171], 0
	v_mfma_f32_16x16x32_bf16 v[52:55], v[220:223], v[172:175], v[52:55]
	v_mfma_f32_16x16x32_bf16 v[36:39], v[216:219], v[176:179], 0
	v_mfma_f32_16x16x32_bf16 v[36:39], v[220:223], v[180:183], v[36:39]
	v_mfma_f32_16x16x32_bf16 v[20:23], v[216:219], v[184:187], 0
	v_mfma_f32_16x16x32_bf16 v[20:23], v[220:223], v[188:191], v[20:23]
	v_mfma_f32_16x16x32_bf16 v[8:11], v[216:219], v[192:195], 0
	v_mfma_f32_16x16x32_bf16 v[8:11], v[220:223], v[212:215], v[8:11]
	v_mfma_f32_16x16x32_bf16 v[44:47], v[224:227], v[168:171], 0
	v_mfma_f32_16x16x32_bf16 v[44:47], v[228:231], v[172:175], v[44:47]
	v_mfma_f32_16x16x32_bf16 v[28:31], v[224:227], v[176:179], 0
	v_mfma_f32_16x16x32_bf16 v[28:31], v[228:231], v[180:183], v[28:31]
	v_mfma_f32_16x16x32_bf16 v[12:15], v[224:227], v[184:187], 0
	v_mfma_f32_16x16x32_bf16 v[12:15], v[228:231], v[188:191], v[12:15]
	v_mfma_f32_16x16x32_bf16 v[4:7], v[224:227], v[192:195], 0
	v_mfma_f32_16x16x32_bf16 v[4:7], v[228:231], v[212:215], v[4:7]
	s_barrier
	s_setprio 0
	s_add_i32 s40, 0, 0x18000
	v_add_u32_e32 v147, s40, v145
	ds_read_b128 v[148:151], v147
	ds_read_b128 v[152:155], v147 offset:1024
	ds_read_b128 v[156:159], v147 offset:2048
	ds_read_b128 v[160:163], v147 offset:3072
	s_add_u32 s16, s16, 0x80000
	s_addc_u32 s17, s17, 0
	s_mov_b32 m0, s26
	v_lshl_add_u64 v[216:217], s[16:17], 0, v[136:137]
	ds_read_b128 v[168:171], v146 offset:32768
	ds_read_b128 v[172:175], v146 offset:33792
	ds_read_b128 v[176:179], v146 offset:34816
	ds_read_b128 v[180:183], v146 offset:35840
	ds_read_b128 v[184:187], v146 offset:36864
	ds_read_b128 v[188:191], v146 offset:37888
	ds_read_b128 v[192:195], v146 offset:38912
	ds_read_b128 v[212:215], v146 offset:39936
	global_load_lds_dwordx4 v[216:217], off
	v_lshl_add_u64 v[216:217], s[16:17], 0, v[132:133]
	s_mov_b32 m0, s27
	s_nop 0
	global_load_lds_dwordx4 v[216:217], off
	s_waitcnt lgkmcnt(8)
	s_setprio 1
	s_barrier
	s_waitcnt lgkmcnt(0)
	v_mfma_f32_16x16x32_bf16 v[128:131], v[148:151], v[168:171], v[128:131]
	v_mfma_f32_16x16x32_bf16 v[128:131], v[152:155], v[172:175], v[128:131]
	v_mfma_f32_16x16x32_bf16 v[120:123], v[148:151], v[176:179], v[120:123]
	v_mfma_f32_16x16x32_bf16 v[120:123], v[152:155], v[180:183], v[120:123]
	v_mfma_f32_16x16x32_bf16 v[104:107], v[148:151], v[184:187], v[104:107]
	v_mfma_f32_16x16x32_bf16 v[104:107], v[152:155], v[188:191], v[104:107]
	v_mfma_f32_16x16x32_bf16 v[88:91], v[148:151], v[192:195], v[88:91]
	v_mfma_f32_16x16x32_bf16 v[88:91], v[152:155], v[212:215], v[88:91]
	v_mfma_f32_16x16x32_bf16 v[124:127], v[156:159], v[168:171], v[124:127]
	v_mfma_f32_16x16x32_bf16 v[124:127], v[160:163], v[172:175], v[124:127]
	v_mfma_f32_16x16x32_bf16 v[112:115], v[156:159], v[176:179], v[112:115]
	v_mfma_f32_16x16x32_bf16 v[112:115], v[160:163], v[180:183], v[112:115]
	v_mfma_f32_16x16x32_bf16 v[96:99], v[156:159], v[184:187], v[96:99]
	v_mfma_f32_16x16x32_bf16 v[96:99], v[160:163], v[188:191], v[96:99]
	v_mfma_f32_16x16x32_bf16 v[80:83], v[156:159], v[192:195], v[80:83]
	v_mfma_f32_16x16x32_bf16 v[80:83], v[160:163], v[212:215], v[80:83]
	s_barrier
	s_setprio 0
	s_add_i32 s16, 0, 0x1c000
	s_add_i32 s17, s40, s19
	v_add_u32_e32 v147, s16, v145
	v_lshl_add_u64 v[142:143], v[142:143], 0, s[52:53]
	s_mov_b32 m0, s17
	ds_read_b128 v[216:219], v147
	ds_read_b128 v[220:223], v147 offset:1024
	ds_read_b128 v[224:227], v147 offset:2048
	ds_read_b128 v[228:231], v147 offset:3072
	global_load_lds_dwordx4 v[142:143], off
	v_lshl_add_u64 v[142:143], v[196:197], 0, s[52:53]
	s_add_i32 m0, s17, 0x2000
	s_nop 0
	global_load_lds_dwordx4 v[142:143], off
	s_setprio 1
	s_barrier
	s_waitcnt lgkmcnt(0)
	v_mfma_f32_16x16x32_bf16 v[116:119], v[216:219], v[168:171], v[116:119]
	v_mfma_f32_16x16x32_bf16 v[116:119], v[220:223], v[172:175], v[116:119]
	v_mfma_f32_16x16x32_bf16 v[100:103], v[216:219], v[176:179], v[100:103]
	v_mfma_f32_16x16x32_bf16 v[100:103], v[220:223], v[180:183], v[100:103]
	v_mfma_f32_16x16x32_bf16 v[84:87], v[216:219], v[184:187], v[84:87]
	v_mfma_f32_16x16x32_bf16 v[84:87], v[220:223], v[188:191], v[84:87]
	v_mfma_f32_16x16x32_bf16 v[72:75], v[216:219], v[192:195], v[72:75]
	v_mfma_f32_16x16x32_bf16 v[72:75], v[220:223], v[212:215], v[72:75]
	v_mfma_f32_16x16x32_bf16 v[108:111], v[224:227], v[168:171], v[108:111]
	v_mfma_f32_16x16x32_bf16 v[108:111], v[228:231], v[172:175], v[108:111]
	v_mfma_f32_16x16x32_bf16 v[92:95], v[224:227], v[176:179], v[92:95]
	v_mfma_f32_16x16x32_bf16 v[92:95], v[228:231], v[180:183], v[92:95]
	v_mfma_f32_16x16x32_bf16 v[76:79], v[224:227], v[184:187], v[76:79]
	v_mfma_f32_16x16x32_bf16 v[76:79], v[228:231], v[188:191], v[76:79]
	v_mfma_f32_16x16x32_bf16 v[68:71], v[224:227], v[192:195], v[68:71]
	v_mfma_f32_16x16x32_bf16 v[68:71], v[228:231], v[212:215], v[68:71]
	s_barrier
	s_setprio 0
	s_mov_b32 m0, s30
	v_lshl_add_u64 v[142:143], v[232:233], 0, s[52:53]
	ds_read_b128 v[168:171], v146 offset:49152
	ds_read_b128 v[172:175], v146 offset:50176
	ds_read_b128 v[176:179], v146 offset:51200
	ds_read_b128 v[180:183], v146 offset:52224
	ds_read_b128 v[184:187], v146 offset:53248
	ds_read_b128 v[188:191], v146 offset:54272
	ds_read_b128 v[192:195], v146 offset:55296
	ds_read_b128 v[212:215], v146 offset:56320
	global_load_lds_dwordx4 v[142:143], off
	v_lshl_add_u64 v[142:143], v[234:235], 0, s[52:53]
	s_mov_b32 m0, s31
	s_nop 0
	global_load_lds_dwordx4 v[142:143], off
	s_setprio 1
	s_barrier
; #define PG8_WAIT_V(n) asm volatile("s_waitcnt vmcnt(" #n ")" ::: "memory")
; #define PG8_WAIT_L(n) asm volatile("s_waitcnt lgkmcnt(" #n ")" ::: "memory")
; #define PG8_BAR __builtin_amdgcn_s_barrier()
; #define PG8_SCHED __builtin_amdgcn_sched_barrier(0)
; template <class Epi, class AddrA, class AddrB>
; __device__ __forceinline__ void gemm_phase(const Sched S, const int lda, const int ldb, const int K, const AddrA addrA,
;                                            const AddrB addrB, const Epi E) {
;     ...
;     for (int t = 0; t < nt; t += 2) {
;       const bool last = (t == nt - 2);
;       const char* a1 = cA + (size_t)(t + 1) * kstep;
;       const char* a2 = last ? nA : cA + (size_t)(t + 2) * kstep;
;       const char* b2 = last ? nB : cB + (size_t)(t + 2) * kstep;
;       const char* a3 = a2 + kstep;
;       const char* b3 = b2 + kstep;
;       PG8_LDB(B0, 0, 0); PG8_SCHED; PG8_LDA(At, 0, 0); PG8_STAGE(PG8_SA(1, 1), a1 + hstepA, voffA);
;       PG8_WAIT_L(8); PG8_BAR; PG8_WAIT_L(0); PG8_MMA(0, 0, At, B0); PG8_BAR; PG8_SCHED;
;     ...
;       PG8_WAIT_V(6); PG8_BAR; PG8_MMA(1, 1, At, B1); PG8_BAR;
;       PG8_LDB(B0, 1, 0); PG8_SCHED; PG8_LDA(At, 1, 0); PG8_STAGE(PG8_SA(0, 1), a2 + hstepA, voffA);
;       PG8_WAIT_L(8); PG8_BAR; PG8_WAIT_L(0); PG8_MMA(0, 0, At, B0); PG8_BAR; PG8_SCHED;
;       PG8_LDB(B1, 1, 1); PG8_STAGE(PG8_SB(1, 0), b3, voffB);
;       PG8_BAR; PG8_WAIT_L(0); PG8_MMA(0, 1, At, B1); PG8_BAR;
;       PG8_LDA(At, 1, 1); PG8_STAGE(PG8_SA(1, 0), a3, voffA);
;       PG8_BAR; PG8_WAIT_L(0); PG8_MMA(1, 0, At, B0); PG8_BAR; PG8_SCHED;
;       PG8_STAGE(PG8_SB(1, 1), b3 + hstepB, voffB);
;       PG8_WAIT_V(6); PG8_BAR; PG8_MMA(1, 1, At, B1); PG8_BAR;
;     }
	s_waitcnt lgkmcnt(0)
	v_mfma_f32_16x16x32_bf16 v[64:67], v[148:151], v[168:171], v[64:67]
	v_mfma_f32_16x16x32_bf16 v[64:67], v[152:155], v[172:175], v[64:67]
	v_mfma_f32_16x16x32_bf16 v[56:59], v[148:151], v[176:179], v[56:59]
	v_mfma_f32_16x16x32_bf16 v[56:59], v[152:155], v[180:183], v[56:59]
	v_mfma_f32_16x16x32_bf16 v[40:43], v[148:151], v[184:187], v[40:43]
	v_mfma_f32_16x16x32_bf16 v[40:43], v[152:155], v[188:191], v[40:43]
	v_mfma_f32_16x16x32_bf16 v[24:27], v[148:151], v[192:195], v[24:27]
	v_mfma_f32_16x16x32_bf16 v[24:27], v[152:155], v[212:215], v[24:27]
	v_mfma_f32_16x16x32_bf16 v[60:63], v[156:159], v[168:171], v[60:63]
	v_mfma_f32_16x16x32_bf16 v[60:63], v[160:163], v[172:175], v[60:63]
	v_mfma_f32_16x16x32_bf16 v[48:51], v[156:159], v[176:179], v[48:51]
	v_mfma_f32_16x16x32_bf16 v[48:51], v[160:163], v[180:183], v[48:51]
	v_mfma_f32_16x16x32_bf16 v[32:35], v[156:159], v[184:187], v[32:35]
	v_mfma_f32_16x16x32_bf16 v[32:35], v[160:163], v[188:191], v[32:35]
	v_mfma_f32_16x16x32_bf16 v[16:19], v[156:159], v[192:195], v[16:19]
	v_mfma_f32_16x16x32_bf16 v[16:19], v[160:163], v[212:215], v[16:19]
	s_barrier
	s_setprio 0
	s_add_u32 s14, s14, 0x80080
	s_addc_u32 s15, s15, 0
	s_add_i32 s16, s16, s19
	v_lshl_add_u64 v[142:143], s[14:15], 0, v[134:135]
	s_mov_b32 m0, s16
	s_nop 0
	global_load_lds_dwordx4 v[142:143], off
	v_lshl_add_u64 v[142:143], s[14:15], 0, v[0:1]
	s_add_i32 m0, s16, 0x2000
	s_nop 0
	global_load_lds_dwordx4 v[142:143], off
	s_add_i32 s39, s39, 2
	s_add_u32 s37, s37, 0x100
	s_addc_u32 s38, s38, 0
	s_add_u32 s12, s12, 0x100
	s_addc_u32 s13, s13, 0
	s_waitcnt vmcnt(6)
	s_setprio 1
	s_barrier
	v_mfma_f32_16x16x32_bf16 v[52:55], v[216:219], v[168:171], v[52:55]
	v_mfma_f32_16x16x32_bf16 v[52:55], v[220:223], v[172:175], v[52:55]
	v_mfma_f32_16x16x32_bf16 v[36:39], v[216:219], v[176:179], v[36:39]
	v_mfma_f32_16x16x32_bf16 v[36:39], v[220:223], v[180:183], v[36:39]
	v_mfma_f32_16x16x32_bf16 v[20:23], v[216:219], v[184:187], v[20:23]
	v_mfma_f32_16x16x32_bf16 v[20:23], v[220:223], v[188:191], v[20:23]
	v_mfma_f32_16x16x32_bf16 v[8:11], v[216:219], v[192:195], v[8:11]
	v_mfma_f32_16x16x32_bf16 v[8:11], v[220:223], v[212:215], v[8:11]
	v_mfma_f32_16x16x32_bf16 v[44:47], v[224:227], v[168:171], v[44:47]
	v_mfma_f32_16x16x32_bf16 v[44:47], v[228:231], v[172:175], v[44:47]
	v_mfma_f32_16x16x32_bf16 v[28:31], v[224:227], v[176:179], v[28:31]
	v_mfma_f32_16x16x32_bf16 v[28:31], v[228:231], v[180:183], v[28:31]
	v_mfma_f32_16x16x32_bf16 v[12:15], v[224:227], v[184:187], v[12:15]
	v_mfma_f32_16x16x32_bf16 v[12:15], v[228:231], v[188:191], v[12:15]
	v_mfma_f32_16x16x32_bf16 v[4:7], v[224:227], v[192:195], v[4:7]
	v_mfma_f32_16x16x32_bf16 v[4:7], v[228:231], v[212:215], v[4:7]
	s_barrier
	s_setprio 0
	s_cmp_gt_u32 s39, 29
.LBB0_109:
	s_add_i32 s40, 0, 0x10000
	v_add_u32_e32 v142, s40, v145
	ds_read_b128 v[148:151], v142
	ds_read_b128 v[152:155], v142 offset:1024
	ds_read_b128 v[156:159], v142 offset:2048
	ds_read_b128 v[160:163], v142 offset:3072
	v_lshl_add_u64 v[142:143], s[12:13], 0, v[140:141]
	s_add_i32 m0, s24, 0xc000
	ds_read_b128 v[168:171], v146
	ds_read_b128 v[172:175], v146 offset:1024
	ds_read_b128 v[176:179], v146 offset:2048
	ds_read_b128 v[180:183], v146 offset:3072
	ds_read_b128 v[184:187], v146 offset:4096
	ds_read_b128 v[188:191], v146 offset:5120
	ds_read_b128 v[192:195], v146 offset:6144
	ds_read_b128 v[212:215], v146 offset:7168
	global_load_lds_dwordx4 v[142:143], off
	v_lshl_add_u64 v[142:143], s[12:13], 0, v[138:139]
	s_add_i32 m0, s24, 0xe000
	s_nop 0
	global_load_lds_dwordx4 v[142:143], off
	s_waitcnt lgkmcnt(8)
	s_setprio 1
	s_barrier
	s_waitcnt lgkmcnt(0)
	v_mfma_f32_16x16x32_bf16 v[128:131], v[148:151], v[168:171], v[128:131]
	v_mfma_f32_16x16x32_bf16 v[128:131], v[152:155], v[172:175], v[128:131]
	v_mfma_f32_16x16x32_bf16 v[120:123], v[148:151], v[176:179], v[120:123]
	v_mfma_f32_16x16x32_bf16 v[120:123], v[152:155], v[180:183], v[120:123]
	v_mfma_f32_16x16x32_bf16 v[104:107], v[148:151], v[184:187], v[104:107]
	v_mfma_f32_16x16x32_bf16 v[104:107], v[152:155], v[188:191], v[104:107]
	v_mfma_f32_16x16x32_bf16 v[88:91], v[148:151], v[192:195], v[88:91]
	v_mfma_f32_16x16x32_bf16 v[88:91], v[152:155], v[212:215], v[88:91]
	v_mfma_f32_16x16x32_bf16 v[124:127], v[156:159], v[168:171], v[124:127]
	v_mfma_f32_16x16x32_bf16 v[124:127], v[160:163], v[172:175], v[124:127]
	v_mfma_f32_16x16x32_bf16 v[112:115], v[156:159], v[176:179], v[112:115]
	v_mfma_f32_16x16x32_bf16 v[112:115], v[160:163], v[180:183], v[112:115]
	v_mfma_f32_16x16x32_bf16 v[96:99], v[156:159], v[184:187], v[96:99]
	v_mfma_f32_16x16x32_bf16 v[96:99], v[160:163], v[188:191], v[96:99]
	v_mfma_f32_16x16x32_bf16 v[80:83], v[156:159], v[192:195], v[80:83]
	v_mfma_f32_16x16x32_bf16 v[80:83], v[160:163], v[212:215], v[80:83]
	s_barrier
	s_setprio 0
	s_add_u32 s14, s12, 0xfff80080
	s_addc_u32 s15, s13, -1
	s_cmp_eq_u32 s39, 28
	s_cselect_b32 s17, s1, s15
	s_cselect_b32 s16, s11, s14
	s_cselect_b32 s15, s3, s38
	s_cselect_b32 s14, s36, s37
	s_add_i32 s42, 0, 0x14000
	v_add_u32_e32 v142, s42, v145
	s_add_i32 s40, s40, s19
	ds_read_b128 v[216:219], v142
	ds_read_b128 v[220:223], v142 offset:1024
	ds_read_b128 v[224:227], v142 offset:2048
	ds_read_b128 v[228:231], v142 offset:3072
	v_lshl_add_u64 v[142:143], s[14:15], 0, v[134:135]
	s_mov_b32 m0, s40
	v_lshl_add_u64 v[196:197], s[14:15], 0, v[0:1]
	global_load_lds_dwordx4 v[142:143], off
	s_add_i32 m0, s40, 0x2000
	s_nop 0
	global_load_lds_dwordx4 v[196:197], off
	s_setprio 1
	s_barrier
; #define PG8_WAIT_V(n) asm volatile("s_waitcnt vmcnt(" #n ")" ::: "memory")
; #define PG8_WAIT_L(n) asm volatile("s_waitcnt lgkmcnt(" #n ")" ::: "memory")
; #define PG8_BAR __builtin_amdgcn_s_barrier()
; #define PG8_SCHED __builtin_amdgcn_sched_barrier(0)
; template <class Epi, class AddrA, class AddrB>
; __device__ __forceinline__ void gemm_phase(const Sched S, const int lda, const int ldb, const int K, const AddrA addrA,
;                                            const AddrB addrB, const Epi E) {
;     ...
;       PG8_WAIT_L(8); PG8_BAR; PG8_WAIT_L(0); PG8_MMA(0, 0, At, B0); PG8_BAR; PG8_SCHED;
;       PG8_LDB(B1, 0, 1); PG8_STAGE(PG8_SB(0, 0), b2, voffB);
;       PG8_BAR; PG8_WAIT_L(0); PG8_MMA(0, 1, At, B1); PG8_BAR;
;       PG8_LDA(At, 0, 1); PG8_STAGE(PG8_SA(0, 0), a2, voffA);
;       PG8_BAR; PG8_WAIT_L(0); PG8_MMA(1, 0, At, B0); PG8_BAR; PG8_SCHED;
;       PG8_STAGE(PG8_SB(0, 1), b2 + hstepB, voffB);
;       PG8_WAIT_V(6); PG8_BAR; PG8_MMA(1, 1, At, B1); PG8_BAR;
;       PG8_LDB(B0, 1, 0); PG8_SCHED; PG8_LDA(At, 1, 0); PG8_STAGE(PG8_SA(0, 1), a2 + hstepA, voffA);
;       PG8_WAIT_L(8); PG8_BAR; PG8_WAIT_L(0); PG8_MMA(0, 0, At, B0); PG8_BAR; PG8_SCHED;
	s_waitcnt lgkmcnt(0)
	v_mfma_f32_16x16x32_bf16 v[116:119], v[216:219], v[168:171], v[116:119]
	v_mfma_f32_16x16x32_bf16 v[116:119], v[220:223], v[172:175], v[116:119]
	v_mfma_f32_16x16x32_bf16 v[100:103], v[216:219], v[176:179], v[100:103]
	v_mfma_f32_16x16x32_bf16 v[100:103], v[220:223], v[180:183], v[100:103]
	v_mfma_f32_16x16x32_bf16 v[84:87], v[216:219], v[184:187], v[84:87]
	v_mfma_f32_16x16x32_bf16 v[84:87], v[220:223], v[188:191], v[84:87]
	v_mfma_f32_16x16x32_bf16 v[72:75], v[216:219], v[192:195], v[72:75]
	v_mfma_f32_16x16x32_bf16 v[72:75], v[220:223], v[212:215], v[72:75]
	v_mfma_f32_16x16x32_bf16 v[108:111], v[224:227], v[168:171], v[108:111]
	v_mfma_f32_16x16x32_bf16 v[108:111], v[228:231], v[172:175], v[108:111]
	v_mfma_f32_16x16x32_bf16 v[92:95], v[224:227], v[176:179], v[92:95]
	v_mfma_f32_16x16x32_bf16 v[92:95], v[228:231], v[180:183], v[92:95]
	v_mfma_f32_16x16x32_bf16 v[76:79], v[224:227], v[184:187], v[76:79]
	v_mfma_f32_16x16x32_bf16 v[76:79], v[228:231], v[188:191], v[76:79]
	v_mfma_f32_16x16x32_bf16 v[68:71], v[224:227], v[192:195], v[68:71]
	v_mfma_f32_16x16x32_bf16 v[68:71], v[228:231], v[212:215], v[68:71]
	s_barrier
	s_setprio 0
	s_mov_b32 m0, s24
	v_lshl_add_u64 v[232:233], s[16:17], 0, v[136:137]
	ds_read_b128 v[168:171], v146 offset:16384
	ds_read_b128 v[172:175], v146 offset:17408
	ds_read_b128 v[176:179], v146 offset:18432
	ds_read_b128 v[180:183], v146 offset:19456
	ds_read_b128 v[184:187], v146 offset:20480
	ds_read_b128 v[188:191], v146 offset:21504
	ds_read_b128 v[192:195], v146 offset:22528
	ds_read_b128 v[212:215], v146 offset:23552
	global_load_lds_dwordx4 v[232:233], off
	v_lshl_add_u64 v[234:235], s[16:17], 0, v[132:133]
	s_mov_b32 m0, s25
	s_nop 0
	global_load_lds_dwordx4 v[234:235], off
	s_setprio 1
	s_barrier
	s_waitcnt lgkmcnt(0)
	v_mfma_f32_16x16x32_bf16 v[64:67], v[148:151], v[168:171], v[64:67]
	v_mfma_f32_16x16x32_bf16 v[64:67], v[152:155], v[172:175], v[64:67]
	v_mfma_f32_16x16x32_bf16 v[56:59], v[148:151], v[176:179], v[56:59]
	v_mfma_f32_16x16x32_bf16 v[56:59], v[152:155], v[180:183], v[56:59]
	v_mfma_f32_16x16x32_bf16 v[40:43], v[148:151], v[184:187], v[40:43]
	v_mfma_f32_16x16x32_bf16 v[40:43], v[152:155], v[188:191], v[40:43]
	v_mfma_f32_16x16x32_bf16 v[24:27], v[148:151], v[192:195], v[24:27]
	v_mfma_f32_16x16x32_bf16 v[24:27], v[152:155], v[212:215], v[24:27]
	v_mfma_f32_16x16x32_bf16 v[60:63], v[156:159], v[168:171], v[60:63]
	v_mfma_f32_16x16x32_bf16 v[60:63], v[160:163], v[172:175], v[60:63]
	v_mfma_f32_16x16x32_bf16 v[48:51], v[156:159], v[176:179], v[48:51]
	v_mfma_f32_16x16x32_bf16 v[48:51], v[160:163], v[180:183], v[48:51]
	v_mfma_f32_16x16x32_bf16 v[32:35], v[156:159], v[184:187], v[32:35]
	v_mfma_f32_16x16x32_bf16 v[32:35], v[160:163], v[188:191], v[32:35]
	v_mfma_f32_16x16x32_bf16 v[16:19], v[156:159], v[192:195], v[16:19]
	v_mfma_f32_16x16x32_bf16 v[16:19], v[160:163], v[212:215], v[16:19]
	s_barrier
	s_setprio 0
	s_add_u32 s40, s14, 0x80000
	s_addc_u32 s41, s15, 0
	s_add_i32 s42, s42, s19
	v_lshl_add_u64 v[148:149], s[40:41], 0, v[134:135]
	s_mov_b32 m0, s42
	s_nop 0
	global_load_lds_dwordx4 v[148:149], off
	v_lshl_add_u64 v[148:149], s[40:41], 0, v[0:1]
	s_add_i32 m0, s42, 0x2000
	s_nop 0
	global_load_lds_dwordx4 v[148:149], off
	s_waitcnt vmcnt(6)
	s_setprio 1
	s_barrier
	v_mfma_f32_16x16x32_bf16 v[52:55], v[216:219], v[168:171], v[52:55]
	v_mfma_f32_16x16x32_bf16 v[52:55], v[220:223], v[172:175], v[52:55]
	v_mfma_f32_16x16x32_bf16 v[36:39], v[216:219], v[176:179], v[36:39]
	v_mfma_f32_16x16x32_bf16 v[36:39], v[220:223], v[180:183], v[36:39]
	v_mfma_f32_16x16x32_bf16 v[20:23], v[216:219], v[184:187], v[20:23]
	v_mfma_f32_16x16x32_bf16 v[20:23], v[220:223], v[188:191], v[20:23]
	v_mfma_f32_16x16x32_bf16 v[8:11], v[216:219], v[192:195], v[8:11]
	v_mfma_f32_16x16x32_bf16 v[8:11], v[220:223], v[212:215], v[8:11]
	v_mfma_f32_16x16x32_bf16 v[44:47], v[224:227], v[168:171], v[44:47]
	v_mfma_f32_16x16x32_bf16 v[44:47], v[228:231], v[172:175], v[44:47]
	v_mfma_f32_16x16x32_bf16 v[28:31], v[224:227], v[176:179], v[28:31]
	v_mfma_f32_16x16x32_bf16 v[28:31], v[228:231], v[180:183], v[28:31]
	v_mfma_f32_16x16x32_bf16 v[12:15], v[224:227], v[184:187], v[12:15]
	v_mfma_f32_16x16x32_bf16 v[12:15], v[228:231], v[188:191], v[12:15]
	v_mfma_f32_16x16x32_bf16 v[4:7], v[224:227], v[192:195], v[4:7]
	v_mfma_f32_16x16x32_bf16 v[4:7], v[228:231], v[212:215], v[4:7]
	s_barrier
	s_setprio 0
	s_add_i32 s40, 0, 0x18000
	v_add_u32_e32 v147, s40, v145
	ds_read_b128 v[148:151], v147
	ds_read_b128 v[152:155], v147 offset:1024
	ds_read_b128 v[156:159], v147 offset:2048
	ds_read_b128 v[160:163], v147 offset:3072
	s_add_u32 s16, s16, 0x80000
	s_addc_u32 s17, s17, 0
	s_mov_b32 m0, s26
	v_lshl_add_u64 v[216:217], s[16:17], 0, v[136:137]
	ds_read_b128 v[168:171], v146 offset:32768
	ds_read_b128 v[172:175], v146 offset:33792
	ds_read_b128 v[176:179], v146 offset:34816
	ds_read_b128 v[180:183], v146 offset:35840
	ds_read_b128 v[184:187], v146 offset:36864
	ds_read_b128 v[188:191], v146 offset:37888
	ds_read_b128 v[192:195], v146 offset:38912
	ds_read_b128 v[212:215], v146 offset:39936
	global_load_lds_dwordx4 v[216:217], off
	v_lshl_add_u64 v[216:217], s[16:17], 0, v[132:133]
	s_mov_b32 m0, s27
	s_nop 0
	global_load_lds_dwordx4 v[216:217], off
	s_waitcnt lgkmcnt(8)
	s_setprio 1
	s_barrier
; #define PG8_WAIT_V(n) asm volatile("s_waitcnt vmcnt(" #n ")" ::: "memory")
; #define PG8_WAIT_L(n) asm volatile("s_waitcnt lgkmcnt(" #n ")" ::: "memory")
; #define PG8_BAR __builtin_amdgcn_s_barrier()
; #define PG8_SCHED __builtin_amdgcn_sched_barrier(0)
; template <class Epi, class AddrA, class AddrB>
; __device__ __forceinline__ void gemm_phase(const Sched S, const int lda, const int ldb, const int K, const AddrA addrA,
;                                            const AddrB addrB, const Epi E) {
;     ...
;       PG8_WAIT_V(6); PG8_BAR; PG8_MMA(1, 1, At, B1); PG8_BAR;
;       PG8_LDB(B0, 1, 0); PG8_SCHED; PG8_LDA(At, 1, 0); PG8_STAGE(PG8_SA(0, 1), a2 + hstepA, voffA);
;       PG8_WAIT_L(8); PG8_BAR; PG8_WAIT_L(0); PG8_MMA(0, 0, At, B0); PG8_BAR; PG8_SCHED;
;       PG8_LDB(B1, 1, 1); PG8_STAGE(PG8_SB(1, 0), b3, voffB);
;       PG8_BAR; PG8_WAIT_L(0); PG8_MMA(0, 1, At, B1); PG8_BAR;
;       PG8_LDA(At, 1, 1); PG8_STAGE(PG8_SA(1, 0), a3, voffA);
;       PG8_BAR; PG8_WAIT_L(0); PG8_MMA(1, 0, At, B0); PG8_BAR; PG8_SCHED;
;       PG8_STAGE(PG8_SB(1, 1), b3 + hstepB, voffB);
;       PG8_WAIT_V(6); PG8_BAR; PG8_MMA(1, 1, At, B1); PG8_BAR;
	s_waitcnt lgkmcnt(0)
	v_mfma_f32_16x16x32_bf16 v[128:131], v[148:151], v[168:171], v[128:131]
	v_mfma_f32_16x16x32_bf16 v[128:131], v[152:155], v[172:175], v[128:131]
	v_mfma_f32_16x16x32_bf16 v[120:123], v[148:151], v[176:179], v[120:123]
	v_mfma_f32_16x16x32_bf16 v[120:123], v[152:155], v[180:183], v[120:123]
	v_mfma_f32_16x16x32_bf16 v[104:107], v[148:151], v[184:187], v[104:107]
	v_mfma_f32_16x16x32_bf16 v[104:107], v[152:155], v[188:191], v[104:107]
	v_mfma_f32_16x16x32_bf16 v[88:91], v[148:151], v[192:195], v[88:91]
	v_mfma_f32_16x16x32_bf16 v[88:91], v[152:155], v[212:215], v[88:91]
	v_mfma_f32_16x16x32_bf16 v[124:127], v[156:159], v[168:171], v[124:127]
	v_mfma_f32_16x16x32_bf16 v[124:127], v[160:163], v[172:175], v[124:127]
	v_mfma_f32_16x16x32_bf16 v[112:115], v[156:159], v[176:179], v[112:115]
	v_mfma_f32_16x16x32_bf16 v[112:115], v[160:163], v[180:183], v[112:115]
	v_mfma_f32_16x16x32_bf16 v[96:99], v[156:159], v[184:187], v[96:99]
	v_mfma_f32_16x16x32_bf16 v[96:99], v[160:163], v[188:191], v[96:99]
	v_mfma_f32_16x16x32_bf16 v[80:83], v[156:159], v[192:195], v[80:83]
	v_mfma_f32_16x16x32_bf16 v[80:83], v[160:163], v[212:215], v[80:83]
	s_barrier
	s_setprio 0
	s_add_i32 s16, 0, 0x1c000
	s_add_i32 s17, s40, s19
	v_add_u32_e32 v147, s16, v145
	v_lshl_add_u64 v[142:143], v[142:143], 0, s[52:53]
	s_mov_b32 m0, s17
	ds_read_b128 v[216:219], v147
	ds_read_b128 v[220:223], v147 offset:1024
	ds_read_b128 v[224:227], v147 offset:2048
	ds_read_b128 v[228:231], v147 offset:3072
	global_load_lds_dwordx4 v[142:143], off
	v_lshl_add_u64 v[142:143], v[196:197], 0, s[52:53]
	s_add_i32 m0, s17, 0x2000
	s_nop 0
	global_load_lds_dwordx4 v[142:143], off
	s_setprio 1
	s_barrier
	s_waitcnt lgkmcnt(0)
	v_mfma_f32_16x16x32_bf16 v[116:119], v[216:219], v[168:171], v[116:119]
	v_mfma_f32_16x16x32_bf16 v[116:119], v[220:223], v[172:175], v[116:119]
	v_mfma_f32_16x16x32_bf16 v[100:103], v[216:219], v[176:179], v[100:103]
	v_mfma_f32_16x16x32_bf16 v[100:103], v[220:223], v[180:183], v[100:103]
	v_mfma_f32_16x16x32_bf16 v[84:87], v[216:219], v[184:187], v[84:87]
	v_mfma_f32_16x16x32_bf16 v[84:87], v[220:223], v[188:191], v[84:87]
	v_mfma_f32_16x16x32_bf16 v[72:75], v[216:219], v[192:195], v[72:75]
	v_mfma_f32_16x16x32_bf16 v[72:75], v[220:223], v[212:215], v[72:75]
	v_mfma_f32_16x16x32_bf16 v[108:111], v[224:227], v[168:171], v[108:111]
	v_mfma_f32_16x16x32_bf16 v[108:111], v[228:231], v[172:175], v[108:111]
	v_mfma_f32_16x16x32_bf16 v[92:95], v[224:227], v[176:179], v[92:95]
	v_mfma_f32_16x16x32_bf16 v[92:95], v[228:231], v[180:183], v[92:95]
	v_mfma_f32_16x16x32_bf16 v[76:79], v[224:227], v[184:187], v[76:79]
	v_mfma_f32_16x16x32_bf16 v[76:79], v[228:231], v[188:191], v[76:79]
	v_mfma_f32_16x16x32_bf16 v[68:71], v[224:227], v[192:195], v[68:71]
	v_mfma_f32_16x16x32_bf16 v[68:71], v[228:231], v[212:215], v[68:71]
	s_barrier
	s_setprio 0
	s_mov_b32 m0, s30
	v_lshl_add_u64 v[142:143], v[232:233], 0, s[52:53]
	ds_read_b128 v[168:171], v146 offset:49152
	ds_read_b128 v[172:175], v146 offset:50176
	ds_read_b128 v[176:179], v146 offset:51200
	ds_read_b128 v[180:183], v146 offset:52224
	ds_read_b128 v[184:187], v146 offset:53248
	ds_read_b128 v[188:191], v146 offset:54272
	ds_read_b128 v[192:195], v146 offset:55296
	ds_read_b128 v[212:215], v146 offset:56320
	global_load_lds_dwordx4 v[142:143], off
	v_lshl_add_u64 v[142:143], v[234:235], 0, s[52:53]
	s_mov_b32 m0, s31
	s_nop 0
	global_load_lds_dwordx4 v[142:143], off
	s_setprio 1
	s_barrier
	s_waitcnt lgkmcnt(0)
	v_mfma_f32_16x16x32_bf16 v[64:67], v[148:151], v[168:171], v[64:67]
	v_mfma_f32_16x16x32_bf16 v[64:67], v[152:155], v[172:175], v[64:67]
	v_mfma_f32_16x16x32_bf16 v[56:59], v[148:151], v[176:179], v[56:59]
	v_mfma_f32_16x16x32_bf16 v[56:59], v[152:155], v[180:183], v[56:59]
	v_mfma_f32_16x16x32_bf16 v[40:43], v[148:151], v[184:187], v[40:43]
	v_mfma_f32_16x16x32_bf16 v[40:43], v[152:155], v[188:191], v[40:43]
	v_mfma_f32_16x16x32_bf16 v[24:27], v[148:151], v[192:195], v[24:27]
	v_mfma_f32_16x16x32_bf16 v[24:27], v[152:155], v[212:215], v[24:27]
	v_mfma_f32_16x16x32_bf16 v[60:63], v[156:159], v[168:171], v[60:63]
	v_mfma_f32_16x16x32_bf16 v[60:63], v[160:163], v[172:175], v[60:63]
	v_mfma_f32_16x16x32_bf16 v[48:51], v[156:159], v[176:179], v[48:51]
	v_mfma_f32_16x16x32_bf16 v[48:51], v[160:163], v[180:183], v[48:51]
	v_mfma_f32_16x16x32_bf16 v[32:35], v[156:159], v[184:187], v[32:35]
	v_mfma_f32_16x16x32_bf16 v[32:35], v[160:163], v[188:191], v[32:35]
	v_mfma_f32_16x16x32_bf16 v[16:19], v[156:159], v[192:195], v[16:19]
	v_mfma_f32_16x16x32_bf16 v[16:19], v[160:163], v[212:215], v[16:19]
	s_barrier
	s_setprio 0
	s_add_u32 s14, s14, 0x80080
	s_addc_u32 s15, s15, 0
	s_add_i32 s16, s16, s19
	v_lshl_add_u64 v[142:143], s[14:15], 0, v[134:135]
	s_mov_b32 m0, s16
	s_nop 0
	global_load_lds_dwordx4 v[142:143], off
	v_lshl_add_u64 v[142:143], s[14:15], 0, v[0:1]
	s_add_i32 m0, s16, 0x2000
	s_nop 0
	global_load_lds_dwordx4 v[142:143], off
	s_add_i32 s39, s39, 2
	s_add_u32 s37, s37, 0x100
	s_addc_u32 s38, s38, 0
	s_add_u32 s12, s12, 0x100
	s_addc_u32 s13, s13, 0
	s_waitcnt vmcnt(6)
	s_setprio 1
	s_barrier
; #define PG8_WAIT_V(n) asm volatile("s_waitcnt vmcnt(" #n ")" ::: "memory")
; #define PG8_WAIT_L(n) asm volatile("s_waitcnt lgkmcnt(" #n ")" ::: "memory")
; #define PG8_BAR __builtin_amdgcn_s_barrier()
; #define PG8_SCHED __builtin_amdgcn_sched_barrier(0)
; template <class Epi, class AddrA, class AddrB>
; __device__ __forceinline__ void gemm_phase(const Sched S, const int lda, const int ldb, const int K, const AddrA addrA,
;                                            const AddrB addrB, const Epi E) {
;     ...
;       PG8_BAR; PG8_WAIT_L(0); PG8_MMA(1, 0, At, B0); PG8_BAR; PG8_SCHED;
;       PG8_STAGE(PG8_SB(1, 1), b3 + hstepB, voffB);
;       PG8_WAIT_V(6); PG8_BAR; PG8_MMA(1, 1, At, B1); PG8_BAR;
;     }
;     E(acc, cur, wr, wc, fr, fq);
;   __device__ __forceinline__ void operator()(EPI_ARGS) const {
;     bf16_t* base = proj + ((size_t)u.pn * MTOK + (size_t)(u.pm * 256 + wr * 64 + fr)) * PLD + wc * 32 + 8 * fq;
; #pragma unroll
;     for (int ai = 0; ai < 2; ++ai)
; #pragma unroll
;       for (int m = 0; m < 4; ++m) {
;         bf16_t* rowp = base + (size_t)(ai * HALF + m * 16) * PLD;
; #pragma unroll
;         for (int bj = 0; bj < 2; ++bj) {
;           const f32x4 v0 = acc[ai][bj][m][0], v1 = acc[ai][bj][m][1];
;           u32x4 o;
;           o.x = pack2(v0[0], v0[1]); o.y = pack2(v0[2], v0[3]); o.z = pack2(v1[0], v1[1]); o.w = pack2(v1[2], v1[3]);
;           *(u32x4*)(rowp + bj * HALF) = o;
;         }
;       }
	v_mfma_f32_16x16x32_bf16 v[52:55], v[216:219], v[168:171], v[52:55]
	v_mfma_f32_16x16x32_bf16 v[52:55], v[220:223], v[172:175], v[52:55]
	v_mfma_f32_16x16x32_bf16 v[36:39], v[216:219], v[176:179], v[36:39]
	v_mfma_f32_16x16x32_bf16 v[36:39], v[220:223], v[180:183], v[36:39]
	v_mfma_f32_16x16x32_bf16 v[20:23], v[216:219], v[184:187], v[20:23]
	v_mfma_f32_16x16x32_bf16 v[20:23], v[220:223], v[188:191], v[20:23]
	v_mfma_f32_16x16x32_bf16 v[8:11], v[216:219], v[192:195], v[8:11]
	v_mfma_f32_16x16x32_bf16 v[8:11], v[220:223], v[212:215], v[8:11]
	v_mfma_f32_16x16x32_bf16 v[44:47], v[224:227], v[168:171], v[44:47]
	v_mfma_f32_16x16x32_bf16 v[44:47], v[228:231], v[172:175], v[44:47]
	v_mfma_f32_16x16x32_bf16 v[28:31], v[224:227], v[176:179], v[28:31]
	v_mfma_f32_16x16x32_bf16 v[28:31], v[228:231], v[180:183], v[28:31]
	v_mfma_f32_16x16x32_bf16 v[12:15], v[224:227], v[184:187], v[12:15]
	v_mfma_f32_16x16x32_bf16 v[12:15], v[228:231], v[188:191], v[12:15]
	v_mfma_f32_16x16x32_bf16 v[4:7], v[224:227], v[192:195], v[4:7]
	v_mfma_f32_16x16x32_bf16 v[4:7], v[228:231], v[212:215], v[4:7]
	s_barrier
	s_setprio 0
	s_cmp_gt_u32 s39, 29
	s_cbranch_scc0 .LBB0_109
	s_ashr_i32 s11, s10, 31
	v_lshl_add_u32 v142, s35, 8, v144
	s_lshl_b64 s[10:11], s[10:11], 23
	v_ashrrev_i32_e32 v143, 31, v142
	s_add_u32 s10, s28, s10
	s_addc_u32 s11, s29, s11
	v_lshlrev_b64 v[142:143], 9, v[142:143]
	v_lshl_add_u64 v[142:143], s[10:11], 0, v[142:143]
	v_lshl_add_u64 v[142:143], v[142:143], 0, s[72:73]
	v_lshl_add_u64 v[142:143], v[142:143], 0, v[2:3]
	v_cvt_pk_bf16_f32 v116, v116, v117
	v_cvt_pk_bf16_f32 v117, v118, v119
	v_cvt_pk_bf16_f32 v119, v110, v111
	v_cvt_pk_bf16_f32 v110, v112, v113
	v_add_co_u32_e32 v112, vcc, s96, v142
	s_movk_i32 s1, 0x4000
	s_nop 0
	v_addc_co_u32_e32 v113, vcc, 0, v143, vcc
	v_cvt_pk_bf16_f32 v100, v100, v101
	v_cvt_pk_bf16_f32 v101, v102, v103
	v_cvt_pk_bf16_f32 v103, v94, v95
	v_cvt_pk_bf16_f32 v94, v96, v97
	v_add_co_u32_e32 v96, vcc, s1, v142
	s_movk_i32 s1, 0x6000
	s_nop 0
	v_addc_co_u32_e32 v97, vcc, 0, v143, vcc
	v_cvt_pk_bf16_f32 v84, v84, v85
	v_cvt_pk_bf16_f32 v85, v86, v87
	v_cvt_pk_bf16_f32 v87, v78, v79
	v_cvt_pk_bf16_f32 v78, v80, v81
	v_add_co_u32_e32 v80, vcc, s1, v142
	v_cvt_pk_bf16_f32 v64, v64, v65
	v_cvt_pk_bf16_f32 v65, v66, v67
	v_cvt_pk_bf16_f32 v66, v60, v61
	s_mov_b32 s1, 0x12000
	s_nop 0
	v_addc_co_u32_e32 v81, vcc, 0, v143, vcc
	v_add_co_u32_e32 v60, vcc, s67, v142
	v_cvt_pk_bf16_f32 v52, v52, v53
	v_cvt_pk_bf16_f32 v53, v54, v55
	v_cvt_pk_bf16_f32 v55, v46, v47
	v_cvt_pk_bf16_f32 v46, v48, v49
	s_nop 1
	v_addc_co_u32_e32 v61, vcc, 0, v143, vcc
	v_add_co_u32_e32 v48, vcc, s1, v142
	s_mov_b32 s1, 0x14000
	s_nop 0
	v_addc_co_u32_e32 v49, vcc, 0, v143, vcc
	v_cvt_pk_bf16_f32 v36, v36, v37
	v_cvt_pk_bf16_f32 v37, v38, v39
	v_cvt_pk_bf16_f32 v39, v30, v31
	v_cvt_pk_bf16_f32 v30, v32, v33
	v_add_co_u32_e32 v32, vcc, s1, v142
	s_mov_b32 s1, 0x16000
	s_nop 0
	v_addc_co_u32_e32 v33, vcc, 0, v143, vcc
	v_cvt_pk_bf16_f32 v20, v20, v21
	v_cvt_pk_bf16_f32 v21, v22, v23
	v_cvt_pk_bf16_f32 v23, v14, v15
	v_cvt_pk_bf16_f32 v14, v16, v17
	v_add_co_u32_e32 v16, vcc, s1, v142
	s_mov_b32 s10, s2
	s_nop 0
	v_addc_co_u32_e32 v17, vcc, 0, v143, vcc
	s_and_b64 vcc, exec, s[4:5]
	s_mov_b32 s35, s0
	s_mov_b64 s[12:13], s[8:9]
	s_mov_b64 s[14:15], s[6:7]
	v_cvt_pk_bf16_f32 v128, v128, v129
	v_cvt_pk_bf16_f32 v129, v130, v131
	v_cvt_pk_bf16_f32 v130, v124, v125
	v_cvt_pk_bf16_f32 v131, v126, v127
	flat_store_dwordx4 v[142:143], v[128:131]
	v_cvt_pk_bf16_f32 v118, v108, v109
	flat_store_dwordx4 v[142:143], v[116:119] offset:256
	v_cvt_pk_bf16_f32 v108, v120, v121
	v_cvt_pk_bf16_f32 v109, v122, v123
	v_cvt_pk_bf16_f32 v111, v114, v115
	flat_store_dwordx4 v[112:113], v[108:111]
	v_cvt_pk_bf16_f32 v102, v92, v93
	flat_store_dwordx4 v[112:113], v[100:103] offset:256
	v_cvt_pk_bf16_f32 v92, v104, v105
	v_cvt_pk_bf16_f32 v93, v106, v107
	v_cvt_pk_bf16_f32 v95, v98, v99
	flat_store_dwordx4 v[96:97], v[92:95]
	v_cvt_pk_bf16_f32 v86, v76, v77
	flat_store_dwordx4 v[96:97], v[84:87] offset:256
	v_cvt_pk_bf16_f32 v76, v88, v89
	v_cvt_pk_bf16_f32 v77, v90, v91
	v_cvt_pk_bf16_f32 v79, v82, v83
	flat_store_dwordx4 v[80:81], v[76:79]
	v_cvt_pk_bf16_f32 v72, v72, v73
	v_cvt_pk_bf16_f32 v73, v74, v75
	v_cvt_pk_bf16_f32 v74, v68, v69
	v_cvt_pk_bf16_f32 v75, v70, v71
	flat_store_dwordx4 v[80:81], v[72:75] offset:256
	v_cvt_pk_bf16_f32 v67, v62, v63
	flat_store_dwordx4 v[60:61], v[64:67]
	v_cvt_pk_bf16_f32 v54, v44, v45
	flat_store_dwordx4 v[60:61], v[52:55] offset:256
	v_cvt_pk_bf16_f32 v44, v56, v57
	v_cvt_pk_bf16_f32 v45, v58, v59
	v_cvt_pk_bf16_f32 v47, v50, v51
	flat_store_dwordx4 v[48:49], v[44:47]
	v_cvt_pk_bf16_f32 v38, v28, v29
	flat_store_dwordx4 v[48:49], v[36:39] offset:256
	v_cvt_pk_bf16_f32 v28, v40, v41
	v_cvt_pk_bf16_f32 v29, v42, v43
	v_cvt_pk_bf16_f32 v31, v34, v35
	flat_store_dwordx4 v[32:33], v[28:31]
	v_cvt_pk_bf16_f32 v22, v12, v13
	flat_store_dwordx4 v[32:33], v[20:23] offset:256
	v_cvt_pk_bf16_f32 v12, v24, v25
	v_cvt_pk_bf16_f32 v13, v26, v27
	v_cvt_pk_bf16_f32 v15, v18, v19
	flat_store_dwordx4 v[16:17], v[12:15]
	v_cvt_pk_bf16_f32 v8, v8, v9
	v_cvt_pk_bf16_f32 v9, v10, v11
	v_cvt_pk_bf16_f32 v10, v4, v5
	v_cvt_pk_bf16_f32 v11, v6, v7
	flat_store_dwordx4 v[16:17], v[8:11] offset:256
	s_cbranch_vccz .LBB0_106
	s_waitcnt vmcnt(0)
	s_cmpk_gt_u32 s18, 0xff
	s_cbranch_scc1 .LBB0_113
	s_barrier

; #define PG8_WAIT_L(n) asm volatile("s_waitcnt lgkmcnt(" #n ")" ::: "memory")
; #define PG8_BAR __builtin_amdgcn_s_barrier()
; #define PG8_SCHED __builtin_amdgcn_sched_barrier(0)
; template <class Epi, class AddrA, class AddrB>
; __device__ __forceinline__ void gemm_phase(const Sched S, const int lda, const int ldb, const int K, const AddrA addrA,
;                                            const AddrB addrB, const Epi E) {
;     ...
;   for (;;) {
;     const bool has_next = S.next(ui + 1, nxt);
;     const char* nA = has_next ? addrA(nxt) : cA;
;     const char* nB = has_next ? addrB(nxt) : cB;
;     for (int t = 0; t < nt; t += 2) {
;       const bool last = (t == nt - 2);
;       const char* a1 = cA + (size_t)(t + 1) * kstep;
;       const char* a2 = last ? nA : cA + (size_t)(t + 2) * kstep;
;       const char* b2 = last ? nB : cB + (size_t)(t + 2) * kstep;
;       const char* a3 = a2 + kstep;
;       const char* b3 = b2 + kstep;
;       PG8_LDB(B0, 0, 0); PG8_SCHED; PG8_LDA(At, 0, 0); PG8_STAGE(PG8_SA(1, 1), a1 + hstepA, voffA);
;       PG8_WAIT_L(8); PG8_BAR; PG8_WAIT_L(0); PG8_MMA(0, 0, At, B0); PG8_BAR; PG8_SCHED;
;       PG8_LDB(B1, 0, 1); PG8_STAGE(PG8_SB(0, 0), b2, voffB);
;       PG8_BAR; PG8_WAIT_L(0); PG8_MMA(0, 1, At, B1); PG8_BAR;
;       PG8_LDA(At, 0, 1); PG8_STAGE(PG8_SA(0, 0), a2, voffA);
;       PG8_BAR; PG8_WAIT_L(0); PG8_MMA(1, 0, At, B0); PG8_BAR; PG8_SCHED;
.LBB0_484:
	s_ashr_i32 s15, s14, 31
	s_lshl_b64 s[20:21], s[14:15], 20
	s_add_u32 s3, s25, s20
	s_addc_u32 s15, s26, s21
	s_lshl_b32 s17, s16, 8
	s_and_b32 s20, s17, 0xfffffe00
	s_ashr_i32 s21, s20, 31
	s_lshl_b64 s[20:21], s[20:21], 1
	s_add_u32 s20, s3, s20
	s_addc_u32 s21, s15, s21
	s_and_b64 s[22:23], s[10:11], exec
	s_cselect_b32 s3, s21, s7
	s_cselect_b32 s15, s20, s6
	s_ashr_i32 s17, s16, 31
	s_lshl_b64 s[22:23], s[16:17], 18
	s_add_u32 s22, s27, s22
	s_addc_u32 s23, s28, s23
	s_and_b64 s[10:11], s[10:11], exec
	s_cselect_b32 s17, s23, s5
	s_cselect_b32 s40, s22, s4
	s_add_u32 s41, s4, 0x100
	s_addc_u32 s42, s5, 0
	s_add_u32 s4, s6, 0x80080
	s_addc_u32 s5, s7, 0
	s_mov_b32 s43, -2
	s_add_i32 s44, 0, 0x10000
	v_add_u32_e32 v2, s44, v167
	ds_read_b128 v[92:95], v2
	ds_read_b128 v[100:103], v2 offset:1024
	ds_read_b128 v[132:135], v2 offset:2048
	ds_read_b128 v[144:147], v2 offset:3072
	v_lshl_add_u64 v[196:197], s[4:5], 0, v[172:173]
	s_add_i32 m0, s30, 0xc000
	ds_read_b128 v[148:151], v169
	ds_read_b128 v[152:155], v169 offset:1024
	ds_read_b128 v[176:179], v169 offset:2048
	ds_read_b128 v[180:183], v169 offset:3072
	ds_read_b128 v[184:187], v169 offset:4096
	ds_read_b128 v[188:191], v169 offset:5120
	ds_read_b128 v[192:195], v169 offset:6144
	ds_read_b128 v[212:215], v169 offset:7168
	global_load_lds_dwordx4 v[196:197], off
	v_lshl_add_u64 v[196:197], s[4:5], 0, v[170:171]
	s_add_i32 m0, s30, 0xe000
	s_nop 0
	global_load_lds_dwordx4 v[196:197], off
	s_waitcnt lgkmcnt(8)
	s_setprio 1
	s_barrier
	s_waitcnt lgkmcnt(0)
	v_mfma_f32_16x16x32_bf16 v[140:143], v[92:95], v[148:151], 0
	v_mfma_f32_16x16x32_bf16 v[140:143], v[100:103], v[152:155], v[140:143]
	v_mfma_f32_16x16x32_bf16 v[128:131], v[92:95], v[176:179], 0
	v_mfma_f32_16x16x32_bf16 v[128:131], v[100:103], v[180:183], v[128:131]
	v_mfma_f32_16x16x32_bf16 v[120:123], v[92:95], v[184:187], 0
	v_mfma_f32_16x16x32_bf16 v[120:123], v[100:103], v[188:191], v[120:123]
	v_mfma_f32_16x16x32_bf16 v[112:115], v[92:95], v[192:195], 0
	v_mfma_f32_16x16x32_bf16 v[112:115], v[100:103], v[212:215], v[112:115]
	v_mfma_f32_16x16x32_bf16 v[136:139], v[132:135], v[148:151], 0
	v_mfma_f32_16x16x32_bf16 v[136:139], v[144:147], v[152:155], v[136:139]
	v_mfma_f32_16x16x32_bf16 v[124:127], v[132:135], v[176:179], 0
	v_mfma_f32_16x16x32_bf16 v[124:127], v[144:147], v[180:183], v[124:127]
	v_mfma_f32_16x16x32_bf16 v[116:119], v[132:135], v[184:187], 0
	v_mfma_f32_16x16x32_bf16 v[116:119], v[144:147], v[188:191], v[116:119]
	v_mfma_f32_16x16x32_bf16 v[108:111], v[132:135], v[192:195], 0
	v_mfma_f32_16x16x32_bf16 v[108:111], v[144:147], v[212:215], v[108:111]
	s_barrier
	s_setprio 0
	s_add_u32 s6, s4, 0xfff80080
	s_addc_u32 s7, s5, -1
	s_cmp_eq_u32 s43, 4
	s_cselect_b32 s11, s3, s7
	s_cselect_b32 s10, s15, s6
	s_cselect_b32 s7, s17, s42
	s_cselect_b32 s6, s40, s41
	s_add_i32 s46, 0, 0x14000
	s_add_i32 s44, s44, s29
	v_add_u32_e32 v2, s46, v167
	v_lshl_add_u64 v[196:197], s[6:7], 0, v[158:159]
	s_mov_b32 m0, s44
	ds_read_b128 v[216:219], v2
	ds_read_b128 v[220:223], v2 offset:1024
	ds_read_b128 v[224:227], v2 offset:2048
	ds_read_b128 v[228:231], v2 offset:3072
	global_load_lds_dwordx4 v[196:197], off
	v_lshl_add_u64 v[232:233], s[6:7], 0, v[0:1]
	s_add_i32 m0, s44, 0x2000
	s_nop 0
	global_load_lds_dwordx4 v[232:233], off
	s_setprio 1
	s_barrier
	s_waitcnt lgkmcnt(0)
	v_mfma_f32_16x16x32_bf16 v[64:67], v[216:219], v[148:151], 0
	v_mfma_f32_16x16x32_bf16 v[64:67], v[220:223], v[152:155], v[64:67]
	v_mfma_f32_16x16x32_bf16 v[56:59], v[216:219], v[176:179], 0
	v_mfma_f32_16x16x32_bf16 v[56:59], v[220:223], v[180:183], v[56:59]
	v_mfma_f32_16x16x32_bf16 v[48:51], v[216:219], v[184:187], 0
	v_mfma_f32_16x16x32_bf16 v[48:51], v[220:223], v[188:191], v[48:51]
	v_mfma_f32_16x16x32_bf16 v[40:43], v[216:219], v[192:195], 0
	v_mfma_f32_16x16x32_bf16 v[40:43], v[220:223], v[212:215], v[40:43]
	v_mfma_f32_16x16x32_bf16 v[60:63], v[224:227], v[148:151], 0
	v_mfma_f32_16x16x32_bf16 v[60:63], v[228:231], v[152:155], v[60:63]
	v_mfma_f32_16x16x32_bf16 v[52:55], v[224:227], v[176:179], 0
	v_mfma_f32_16x16x32_bf16 v[52:55], v[228:231], v[180:183], v[52:55]
	v_mfma_f32_16x16x32_bf16 v[44:47], v[224:227], v[184:187], 0
	v_mfma_f32_16x16x32_bf16 v[44:47], v[228:231], v[188:191], v[44:47]
	v_mfma_f32_16x16x32_bf16 v[36:39], v[224:227], v[192:195], 0
	v_mfma_f32_16x16x32_bf16 v[36:39], v[228:231], v[212:215], v[36:39]
	s_barrier
	s_setprio 0
	s_mov_b32 m0, s30
	v_lshl_add_u64 v[234:235], s[10:11], 0, v[160:161]
	ds_read_b128 v[148:151], v169 offset:16384
	ds_read_b128 v[152:155], v169 offset:17408
	ds_read_b128 v[176:179], v169 offset:18432
	ds_read_b128 v[180:183], v169 offset:19456
	ds_read_b128 v[184:187], v169 offset:20480
	ds_read_b128 v[188:191], v169 offset:21504
	ds_read_b128 v[192:195], v169 offset:22528
	ds_read_b128 v[212:215], v169 offset:23552
	global_load_lds_dwordx4 v[234:235], off
	v_lshl_add_u64 v[236:237], s[10:11], 0, v[156:157]
	s_mov_b32 m0, s31
	s_nop 0
	global_load_lds_dwordx4 v[236:237], off
	s_setprio 1
	s_barrier
	s_waitcnt lgkmcnt(0)
	v_mfma_f32_16x16x32_bf16 v[104:107], v[92:95], v[148:151], 0
	v_mfma_f32_16x16x32_bf16 v[104:107], v[100:103], v[152:155], v[104:107]
	v_mfma_f32_16x16x32_bf16 v[88:91], v[92:95], v[176:179], 0
	v_mfma_f32_16x16x32_bf16 v[88:91], v[100:103], v[180:183], v[88:91]
	v_mfma_f32_16x16x32_bf16 v[80:83], v[92:95], v[184:187], 0
	v_mfma_f32_16x16x32_bf16 v[80:83], v[100:103], v[188:191], v[80:83]
	v_mfma_f32_16x16x32_bf16 v[72:75], v[92:95], v[192:195], 0
	v_mfma_f32_16x16x32_bf16 v[72:75], v[100:103], v[212:215], v[72:75]
	v_mfma_f32_16x16x32_bf16 v[96:99], v[132:135], v[148:151], 0
	v_mfma_f32_16x16x32_bf16 v[96:99], v[144:147], v[152:155], v[96:99]
	v_mfma_f32_16x16x32_bf16 v[84:87], v[132:135], v[176:179], 0
	v_mfma_f32_16x16x32_bf16 v[84:87], v[144:147], v[180:183], v[84:87]
	v_mfma_f32_16x16x32_bf16 v[76:79], v[132:135], v[184:187], 0
	v_mfma_f32_16x16x32_bf16 v[76:79], v[144:147], v[188:191], v[76:79]
	v_mfma_f32_16x16x32_bf16 v[68:71], v[132:135], v[192:195], 0
	v_mfma_f32_16x16x32_bf16 v[68:71], v[144:147], v[212:215], v[68:71]
	s_barrier
; #define PG8_WAIT_V(n) asm volatile("s_waitcnt vmcnt(" #n ")" ::: "memory")
; #define PG8_WAIT_L(n) asm volatile("s_waitcnt lgkmcnt(" #n ")" ::: "memory")
; #define PG8_BAR __builtin_amdgcn_s_barrier()
; #define PG8_SCHED __builtin_amdgcn_sched_barrier(0)
; template <class Epi, class AddrA, class AddrB>
; __device__ __forceinline__ void gemm_phase(const Sched S, const int lda, const int ldb, const int K, const AddrA addrA,
;                                            const AddrB addrB, const Epi E) {
;     ...
;       PG8_BAR; PG8_WAIT_L(0); PG8_MMA(1, 0, At, B0); PG8_BAR; PG8_SCHED;
;       PG8_STAGE(PG8_SB(0, 1), b2 + hstepB, voffB);
;       PG8_WAIT_V(6); PG8_BAR; PG8_MMA(1, 1, At, B1); PG8_BAR;
;       PG8_LDB(B0, 1, 0); PG8_SCHED; PG8_LDA(At, 1, 0); PG8_STAGE(PG8_SA(0, 1), a2 + hstepA, voffA);
;       PG8_WAIT_L(8); PG8_BAR; PG8_WAIT_L(0); PG8_MMA(0, 0, At, B0); PG8_BAR; PG8_SCHED;
;       PG8_LDB(B1, 1, 1); PG8_STAGE(PG8_SB(1, 0), b3, voffB);
;       PG8_BAR; PG8_WAIT_L(0); PG8_MMA(0, 1, At, B1); PG8_BAR;
;       PG8_LDA(At, 1, 1); PG8_STAGE(PG8_SA(1, 0), a3, voffA);
;       PG8_BAR; PG8_WAIT_L(0); PG8_MMA(1, 0, At, B0); PG8_BAR; PG8_SCHED;
	s_setprio 0
	s_add_u32 s44, s6, 0x20000
	s_addc_u32 s45, s7, 0
	s_add_i32 s46, s46, s29
	v_lshl_add_u64 v[92:93], s[44:45], 0, v[158:159]
	s_mov_b32 m0, s46
	s_nop 0
	global_load_lds_dwordx4 v[92:93], off
	v_lshl_add_u64 v[92:93], s[44:45], 0, v[0:1]
	s_add_i32 m0, s46, 0x2000
	s_nop 0
	global_load_lds_dwordx4 v[92:93], off
	s_waitcnt vmcnt(6)
	s_setprio 1
	s_barrier
	v_mfma_f32_16x16x32_bf16 v[32:35], v[216:219], v[148:151], 0
	v_mfma_f32_16x16x32_bf16 v[32:35], v[220:223], v[152:155], v[32:35]
	v_mfma_f32_16x16x32_bf16 v[24:27], v[216:219], v[176:179], 0
	v_mfma_f32_16x16x32_bf16 v[24:27], v[220:223], v[180:183], v[24:27]
	v_mfma_f32_16x16x32_bf16 v[16:19], v[216:219], v[184:187], 0
	v_mfma_f32_16x16x32_bf16 v[16:19], v[220:223], v[188:191], v[16:19]
	v_mfma_f32_16x16x32_bf16 v[8:11], v[216:219], v[192:195], 0
	v_mfma_f32_16x16x32_bf16 v[8:11], v[220:223], v[212:215], v[8:11]
	v_mfma_f32_16x16x32_bf16 v[28:31], v[224:227], v[148:151], 0
	v_mfma_f32_16x16x32_bf16 v[28:31], v[228:231], v[152:155], v[28:31]
	v_mfma_f32_16x16x32_bf16 v[20:23], v[224:227], v[176:179], 0
	v_mfma_f32_16x16x32_bf16 v[20:23], v[228:231], v[180:183], v[20:23]
	v_mfma_f32_16x16x32_bf16 v[12:15], v[224:227], v[184:187], 0
	v_mfma_f32_16x16x32_bf16 v[12:15], v[228:231], v[188:191], v[12:15]
	v_mfma_f32_16x16x32_bf16 v[4:7], v[224:227], v[192:195], 0
	v_mfma_f32_16x16x32_bf16 v[4:7], v[228:231], v[212:215], v[4:7]
	s_barrier
	s_setprio 0
	s_add_i32 s44, 0, 0x18000
	v_add_u32_e32 v2, s44, v167
	ds_read_b128 v[92:95], v2
	ds_read_b128 v[100:103], v2 offset:1024
	ds_read_b128 v[132:135], v2 offset:2048
	ds_read_b128 v[144:147], v2 offset:3072
	s_add_u32 s10, s10, 0x80000
	s_addc_u32 s11, s11, 0
	s_mov_b32 m0, s34
	v_lshl_add_u64 v[216:217], s[10:11], 0, v[160:161]
	ds_read_b128 v[148:151], v169 offset:32768
	ds_read_b128 v[152:155], v169 offset:33792
	ds_read_b128 v[176:179], v169 offset:34816
	ds_read_b128 v[180:183], v169 offset:35840
	ds_read_b128 v[184:187], v169 offset:36864
	ds_read_b128 v[188:191], v169 offset:37888
	ds_read_b128 v[192:195], v169 offset:38912
	ds_read_b128 v[212:215], v169 offset:39936
	global_load_lds_dwordx4 v[216:217], off
	v_lshl_add_u64 v[216:217], s[10:11], 0, v[156:157]
	s_mov_b32 m0, s35
	s_nop 0
	global_load_lds_dwordx4 v[216:217], off
	s_waitcnt lgkmcnt(8)
	s_setprio 1
	s_barrier
	s_waitcnt lgkmcnt(0)
	v_mfma_f32_16x16x32_bf16 v[140:143], v[92:95], v[148:151], v[140:143]
	v_mfma_f32_16x16x32_bf16 v[140:143], v[100:103], v[152:155], v[140:143]
	v_mfma_f32_16x16x32_bf16 v[128:131], v[92:95], v[176:179], v[128:131]
	v_mfma_f32_16x16x32_bf16 v[128:131], v[100:103], v[180:183], v[128:131]
	v_mfma_f32_16x16x32_bf16 v[120:123], v[92:95], v[184:187], v[120:123]
	v_mfma_f32_16x16x32_bf16 v[120:123], v[100:103], v[188:191], v[120:123]
	v_mfma_f32_16x16x32_bf16 v[112:115], v[92:95], v[192:195], v[112:115]
	v_mfma_f32_16x16x32_bf16 v[112:115], v[100:103], v[212:215], v[112:115]
	v_mfma_f32_16x16x32_bf16 v[136:139], v[132:135], v[148:151], v[136:139]
	v_mfma_f32_16x16x32_bf16 v[136:139], v[144:147], v[152:155], v[136:139]
	v_mfma_f32_16x16x32_bf16 v[124:127], v[132:135], v[176:179], v[124:127]
	v_mfma_f32_16x16x32_bf16 v[124:127], v[144:147], v[180:183], v[124:127]
	v_mfma_f32_16x16x32_bf16 v[116:119], v[132:135], v[184:187], v[116:119]
	v_mfma_f32_16x16x32_bf16 v[116:119], v[144:147], v[188:191], v[116:119]
	v_mfma_f32_16x16x32_bf16 v[108:111], v[132:135], v[192:195], v[108:111]
	v_mfma_f32_16x16x32_bf16 v[108:111], v[144:147], v[212:215], v[108:111]
	s_barrier
	s_setprio 0
	s_add_i32 s10, 0, 0x1c000
	s_add_i32 s11, s44, s29
	v_add_u32_e32 v2, s10, v167
	v_lshl_add_u64 v[196:197], v[196:197], 0, s[52:53]
	s_mov_b32 m0, s11
	ds_read_b128 v[216:219], v2
	ds_read_b128 v[220:223], v2 offset:1024
	ds_read_b128 v[224:227], v2 offset:2048
	ds_read_b128 v[228:231], v2 offset:3072
	global_load_lds_dwordx4 v[196:197], off
	v_lshl_add_u64 v[196:197], v[232:233], 0, s[52:53]
	s_add_i32 m0, s11, 0x2000
	s_nop 0
	global_load_lds_dwordx4 v[196:197], off
	s_setprio 1
	s_barrier
	s_waitcnt lgkmcnt(0)
	v_mfma_f32_16x16x32_bf16 v[64:67], v[216:219], v[148:151], v[64:67]
	v_mfma_f32_16x16x32_bf16 v[64:67], v[220:223], v[152:155], v[64:67]
	v_mfma_f32_16x16x32_bf16 v[56:59], v[216:219], v[176:179], v[56:59]
	v_mfma_f32_16x16x32_bf16 v[56:59], v[220:223], v[180:183], v[56:59]
	v_mfma_f32_16x16x32_bf16 v[48:51], v[216:219], v[184:187], v[48:51]
	v_mfma_f32_16x16x32_bf16 v[48:51], v[220:223], v[188:191], v[48:51]
	v_mfma_f32_16x16x32_bf16 v[40:43], v[216:219], v[192:195], v[40:43]
	v_mfma_f32_16x16x32_bf16 v[40:43], v[220:223], v[212:215], v[40:43]
	v_mfma_f32_16x16x32_bf16 v[60:63], v[224:227], v[148:151], v[60:63]
	v_mfma_f32_16x16x32_bf16 v[60:63], v[228:231], v[152:155], v[60:63]
	v_mfma_f32_16x16x32_bf16 v[52:55], v[224:227], v[176:179], v[52:55]
	v_mfma_f32_16x16x32_bf16 v[52:55], v[228:231], v[180:183], v[52:55]
	v_mfma_f32_16x16x32_bf16 v[44:47], v[224:227], v[184:187], v[44:47]
	v_mfma_f32_16x16x32_bf16 v[44:47], v[228:231], v[188:191], v[44:47]
	v_mfma_f32_16x16x32_bf16 v[36:39], v[224:227], v[192:195], v[36:39]
	v_mfma_f32_16x16x32_bf16 v[36:39], v[228:231], v[212:215], v[36:39]
	s_barrier
	s_setprio 0
	s_mov_b32 m0, s37
	v_lshl_add_u64 v[196:197], v[234:235], 0, s[52:53]
	ds_read_b128 v[148:151], v169 offset:49152
	ds_read_b128 v[152:155], v169 offset:50176
	ds_read_b128 v[176:179], v169 offset:51200
	ds_read_b128 v[180:183], v169 offset:52224
	ds_read_b128 v[184:187], v169 offset:53248
	ds_read_b128 v[188:191], v169 offset:54272
	ds_read_b128 v[192:195], v169 offset:55296
	ds_read_b128 v[212:215], v169 offset:56320
	global_load_lds_dwordx4 v[196:197], off
	v_lshl_add_u64 v[196:197], v[236:237], 0, s[52:53]
	s_mov_b32 m0, s38
	s_nop 0
	global_load_lds_dwordx4 v[196:197], off
	s_setprio 1
	s_barrier
; #define PG8_WAIT_V(n) asm volatile("s_waitcnt vmcnt(" #n ")" ::: "memory")
; #define PG8_WAIT_L(n) asm volatile("s_waitcnt lgkmcnt(" #n ")" ::: "memory")
; #define PG8_BAR __builtin_amdgcn_s_barrier()
; #define PG8_SCHED __builtin_amdgcn_sched_barrier(0)
; template <class Epi, class AddrA, class AddrB>
; __device__ __forceinline__ void gemm_phase(const Sched S, const int lda, const int ldb, const int K, const AddrA addrA,
;                                            const AddrB addrB, const Epi E) {
;     ...
;     for (int t = 0; t < nt; t += 2) {
;       const bool last = (t == nt - 2);
;       const char* a1 = cA + (size_t)(t + 1) * kstep;
;       const char* a2 = last ? nA : cA + (size_t)(t + 2) * kstep;
;       const char* b2 = last ? nB : cB + (size_t)(t + 2) * kstep;
;       const char* a3 = a2 + kstep;
;       const char* b3 = b2 + kstep;
;       PG8_LDB(B0, 0, 0); PG8_SCHED; PG8_LDA(At, 0, 0); PG8_STAGE(PG8_SA(1, 1), a1 + hstepA, voffA);
;       PG8_WAIT_L(8); PG8_BAR; PG8_WAIT_L(0); PG8_MMA(0, 0, At, B0); PG8_BAR; PG8_SCHED;
;     ...
;       PG8_WAIT_V(6); PG8_BAR; PG8_MMA(1, 1, At, B1); PG8_BAR;
;       PG8_LDB(B0, 1, 0); PG8_SCHED; PG8_LDA(At, 1, 0); PG8_STAGE(PG8_SA(0, 1), a2 + hstepA, voffA);
;       PG8_WAIT_L(8); PG8_BAR; PG8_WAIT_L(0); PG8_MMA(0, 0, At, B0); PG8_BAR; PG8_SCHED;
;       PG8_LDB(B1, 1, 1); PG8_STAGE(PG8_SB(1, 0), b3, voffB);
;       PG8_BAR; PG8_WAIT_L(0); PG8_MMA(0, 1, At, B1); PG8_BAR;
;       PG8_LDA(At, 1, 1); PG8_STAGE(PG8_SA(1, 0), a3, voffA);
;       PG8_BAR; PG8_WAIT_L(0); PG8_MMA(1, 0, At, B0); PG8_BAR; PG8_SCHED;
;       PG8_STAGE(PG8_SB(1, 1), b3 + hstepB, voffB);
;       PG8_WAIT_V(6); PG8_BAR; PG8_MMA(1, 1, At, B1); PG8_BAR;
;     }
	s_waitcnt lgkmcnt(0)
	v_mfma_f32_16x16x32_bf16 v[104:107], v[92:95], v[148:151], v[104:107]
	v_mfma_f32_16x16x32_bf16 v[104:107], v[100:103], v[152:155], v[104:107]
	v_mfma_f32_16x16x32_bf16 v[88:91], v[92:95], v[176:179], v[88:91]
	v_mfma_f32_16x16x32_bf16 v[88:91], v[100:103], v[180:183], v[88:91]
	v_mfma_f32_16x16x32_bf16 v[80:83], v[92:95], v[184:187], v[80:83]
	v_mfma_f32_16x16x32_bf16 v[80:83], v[100:103], v[188:191], v[80:83]
	v_mfma_f32_16x16x32_bf16 v[72:75], v[92:95], v[192:195], v[72:75]
	v_mfma_f32_16x16x32_bf16 v[72:75], v[100:103], v[212:215], v[72:75]
	v_mfma_f32_16x16x32_bf16 v[96:99], v[132:135], v[148:151], v[96:99]
	v_mfma_f32_16x16x32_bf16 v[96:99], v[144:147], v[152:155], v[96:99]
	v_mfma_f32_16x16x32_bf16 v[84:87], v[132:135], v[176:179], v[84:87]
	v_mfma_f32_16x16x32_bf16 v[84:87], v[144:147], v[180:183], v[84:87]
	v_mfma_f32_16x16x32_bf16 v[76:79], v[132:135], v[184:187], v[76:79]
	v_mfma_f32_16x16x32_bf16 v[76:79], v[144:147], v[188:191], v[76:79]
	v_mfma_f32_16x16x32_bf16 v[68:71], v[132:135], v[192:195], v[68:71]
	v_mfma_f32_16x16x32_bf16 v[68:71], v[144:147], v[212:215], v[68:71]
	s_barrier
	s_setprio 0
	s_add_u32 s6, s6, 0x20080
	s_addc_u32 s7, s7, 0
	s_add_i32 s10, s10, s29
	v_lshl_add_u64 v[92:93], s[6:7], 0, v[158:159]
	s_mov_b32 m0, s10
	s_nop 0
	global_load_lds_dwordx4 v[92:93], off
	v_lshl_add_u64 v[92:93], s[6:7], 0, v[0:1]
	s_add_i32 m0, s10, 0x2000
	s_nop 0
	global_load_lds_dwordx4 v[92:93], off
	s_add_i32 s43, s43, 2
	s_add_u32 s41, s41, 0x100
	s_addc_u32 s42, s42, 0
	s_add_u32 s4, s4, 0x100
	s_addc_u32 s5, s5, 0
	s_waitcnt vmcnt(6)
	s_setprio 1
	s_barrier
	v_mfma_f32_16x16x32_bf16 v[32:35], v[216:219], v[148:151], v[32:35]
	v_mfma_f32_16x16x32_bf16 v[32:35], v[220:223], v[152:155], v[32:35]
	v_mfma_f32_16x16x32_bf16 v[24:27], v[216:219], v[176:179], v[24:27]
	v_mfma_f32_16x16x32_bf16 v[24:27], v[220:223], v[180:183], v[24:27]
	v_mfma_f32_16x16x32_bf16 v[16:19], v[216:219], v[184:187], v[16:19]
	v_mfma_f32_16x16x32_bf16 v[16:19], v[220:223], v[188:191], v[16:19]
	v_mfma_f32_16x16x32_bf16 v[8:11], v[216:219], v[192:195], v[8:11]
	v_mfma_f32_16x16x32_bf16 v[8:11], v[220:223], v[212:215], v[8:11]
	v_mfma_f32_16x16x32_bf16 v[28:31], v[224:227], v[148:151], v[28:31]
	v_mfma_f32_16x16x32_bf16 v[28:31], v[228:231], v[152:155], v[28:31]
	v_mfma_f32_16x16x32_bf16 v[20:23], v[224:227], v[176:179], v[20:23]
	v_mfma_f32_16x16x32_bf16 v[20:23], v[228:231], v[180:183], v[20:23]
	v_mfma_f32_16x16x32_bf16 v[12:15], v[224:227], v[184:187], v[12:15]
	v_mfma_f32_16x16x32_bf16 v[12:15], v[228:231], v[188:191], v[12:15]
	v_mfma_f32_16x16x32_bf16 v[4:7], v[224:227], v[192:195], v[4:7]
	v_mfma_f32_16x16x32_bf16 v[4:7], v[228:231], v[212:215], v[4:7]
	s_barrier
	s_setprio 0
	s_cmp_gt_u32 s43, 5
.LBB0_485:
	s_add_i32 s44, 0, 0x10000
	v_add_u32_e32 v2, s44, v167
	ds_read_b128 v[92:95], v2
	ds_read_b128 v[100:103], v2 offset:1024
	ds_read_b128 v[132:135], v2 offset:2048
	ds_read_b128 v[144:147], v2 offset:3072
	v_lshl_add_u64 v[196:197], s[4:5], 0, v[172:173]
	s_add_i32 m0, s30, 0xc000
	ds_read_b128 v[148:151], v169
	ds_read_b128 v[152:155], v169 offset:1024
	ds_read_b128 v[176:179], v169 offset:2048
	ds_read_b128 v[180:183], v169 offset:3072
	ds_read_b128 v[184:187], v169 offset:4096
	ds_read_b128 v[188:191], v169 offset:5120
	ds_read_b128 v[192:195], v169 offset:6144
	ds_read_b128 v[212:215], v169 offset:7168
	global_load_lds_dwordx4 v[196:197], off
	v_lshl_add_u64 v[196:197], s[4:5], 0, v[170:171]
	s_add_i32 m0, s30, 0xe000
	s_nop 0
	global_load_lds_dwordx4 v[196:197], off
	s_waitcnt lgkmcnt(8)
	s_setprio 1
	s_barrier
	s_waitcnt lgkmcnt(0)
	v_mfma_f32_16x16x32_bf16 v[140:143], v[92:95], v[148:151], v[140:143]
	v_mfma_f32_16x16x32_bf16 v[140:143], v[100:103], v[152:155], v[140:143]
	v_mfma_f32_16x16x32_bf16 v[128:131], v[92:95], v[176:179], v[128:131]
	v_mfma_f32_16x16x32_bf16 v[128:131], v[100:103], v[180:183], v[128:131]
	v_mfma_f32_16x16x32_bf16 v[120:123], v[92:95], v[184:187], v[120:123]
	v_mfma_f32_16x16x32_bf16 v[120:123], v[100:103], v[188:191], v[120:123]
	v_mfma_f32_16x16x32_bf16 v[112:115], v[92:95], v[192:195], v[112:115]
	v_mfma_f32_16x16x32_bf16 v[112:115], v[100:103], v[212:215], v[112:115]
	v_mfma_f32_16x16x32_bf16 v[136:139], v[132:135], v[148:151], v[136:139]
	v_mfma_f32_16x16x32_bf16 v[136:139], v[144:147], v[152:155], v[136:139]
	v_mfma_f32_16x16x32_bf16 v[124:127], v[132:135], v[176:179], v[124:127]
	v_mfma_f32_16x16x32_bf16 v[124:127], v[144:147], v[180:183], v[124:127]
	v_mfma_f32_16x16x32_bf16 v[116:119], v[132:135], v[184:187], v[116:119]
	v_mfma_f32_16x16x32_bf16 v[116:119], v[144:147], v[188:191], v[116:119]
	v_mfma_f32_16x16x32_bf16 v[108:111], v[132:135], v[192:195], v[108:111]
	v_mfma_f32_16x16x32_bf16 v[108:111], v[144:147], v[212:215], v[108:111]
	s_barrier
	s_setprio 0
	s_add_u32 s6, s4, 0xfff80080
	s_addc_u32 s7, s5, -1
	s_cmp_eq_u32 s43, 4
	s_cselect_b32 s11, s3, s7
	s_cselect_b32 s10, s15, s6
	s_cselect_b32 s7, s17, s42
	s_cselect_b32 s6, s40, s41
	s_add_i32 s46, 0, 0x14000
	s_add_i32 s44, s44, s29
	v_add_u32_e32 v2, s46, v167
	v_lshl_add_u64 v[196:197], s[6:7], 0, v[158:159]
	s_mov_b32 m0, s44
	ds_read_b128 v[216:219], v2
	ds_read_b128 v[220:223], v2 offset:1024
	ds_read_b128 v[224:227], v2 offset:2048
	ds_read_b128 v[228:231], v2 offset:3072
	global_load_lds_dwordx4 v[196:197], off
	v_lshl_add_u64 v[232:233], s[6:7], 0, v[0:1]
	s_add_i32 m0, s44, 0x2000
	s_nop 0
	global_load_lds_dwordx4 v[232:233], off
	s_setprio 1
	s_barrier
; #define PG8_WAIT_V(n) asm volatile("s_waitcnt vmcnt(" #n ")" ::: "memory")
; #define PG8_WAIT_L(n) asm volatile("s_waitcnt lgkmcnt(" #n ")" ::: "memory")
; #define PG8_BAR __builtin_amdgcn_s_barrier()
; #define PG8_SCHED __builtin_amdgcn_sched_barrier(0)
; template <class Epi, class AddrA, class AddrB>
; __device__ __forceinline__ void gemm_phase(const Sched S, const int lda, const int ldb, const int K, const AddrA addrA,
;                                            const AddrB addrB, const Epi E) {
;     ...
;       PG8_WAIT_L(8); PG8_BAR; PG8_WAIT_L(0); PG8_MMA(0, 0, At, B0); PG8_BAR; PG8_SCHED;
;       PG8_LDB(B1, 0, 1); PG8_STAGE(PG8_SB(0, 0), b2, voffB);
;       PG8_BAR; PG8_WAIT_L(0); PG8_MMA(0, 1, At, B1); PG8_BAR;
;       PG8_LDA(At, 0, 1); PG8_STAGE(PG8_SA(0, 0), a2, voffA);
;       PG8_BAR; PG8_WAIT_L(0); PG8_MMA(1, 0, At, B0); PG8_BAR; PG8_SCHED;
;       PG8_STAGE(PG8_SB(0, 1), b2 + hstepB, voffB);
;       PG8_WAIT_V(6); PG8_BAR; PG8_MMA(1, 1, At, B1); PG8_BAR;
;       PG8_LDB(B0, 1, 0); PG8_SCHED; PG8_LDA(At, 1, 0); PG8_STAGE(PG8_SA(0, 1), a2 + hstepA, voffA);
;       PG8_WAIT_L(8); PG8_BAR; PG8_WAIT_L(0); PG8_MMA(0, 0, At, B0); PG8_BAR; PG8_SCHED;
	s_waitcnt lgkmcnt(0)
	v_mfma_f32_16x16x32_bf16 v[64:67], v[216:219], v[148:151], v[64:67]
	v_mfma_f32_16x16x32_bf16 v[64:67], v[220:223], v[152:155], v[64:67]
	v_mfma_f32_16x16x32_bf16 v[56:59], v[216:219], v[176:179], v[56:59]
	v_mfma_f32_16x16x32_bf16 v[56:59], v[220:223], v[180:183], v[56:59]
	v_mfma_f32_16x16x32_bf16 v[48:51], v[216:219], v[184:187], v[48:51]
	v_mfma_f32_16x16x32_bf16 v[48:51], v[220:223], v[188:191], v[48:51]
	v_mfma_f32_16x16x32_bf16 v[40:43], v[216:219], v[192:195], v[40:43]
	v_mfma_f32_16x16x32_bf16 v[40:43], v[220:223], v[212:215], v[40:43]
	v_mfma_f32_16x16x32_bf16 v[60:63], v[224:227], v[148:151], v[60:63]
	v_mfma_f32_16x16x32_bf16 v[60:63], v[228:231], v[152:155], v[60:63]
	v_mfma_f32_16x16x32_bf16 v[52:55], v[224:227], v[176:179], v[52:55]
	v_mfma_f32_16x16x32_bf16 v[52:55], v[228:231], v[180:183], v[52:55]
	v_mfma_f32_16x16x32_bf16 v[44:47], v[224:227], v[184:187], v[44:47]
	v_mfma_f32_16x16x32_bf16 v[44:47], v[228:231], v[188:191], v[44:47]
	v_mfma_f32_16x16x32_bf16 v[36:39], v[224:227], v[192:195], v[36:39]
	v_mfma_f32_16x16x32_bf16 v[36:39], v[228:231], v[212:215], v[36:39]
	s_barrier
	s_setprio 0
	s_mov_b32 m0, s30
	v_lshl_add_u64 v[234:235], s[10:11], 0, v[160:161]
	ds_read_b128 v[148:151], v169 offset:16384
	ds_read_b128 v[152:155], v169 offset:17408
	ds_read_b128 v[176:179], v169 offset:18432
	ds_read_b128 v[180:183], v169 offset:19456
	ds_read_b128 v[184:187], v169 offset:20480
	ds_read_b128 v[188:191], v169 offset:21504
	ds_read_b128 v[192:195], v169 offset:22528
	ds_read_b128 v[212:215], v169 offset:23552
	global_load_lds_dwordx4 v[234:235], off
	v_lshl_add_u64 v[236:237], s[10:11], 0, v[156:157]
	s_mov_b32 m0, s31
	s_nop 0
	global_load_lds_dwordx4 v[236:237], off
	s_setprio 1
	s_barrier
	s_waitcnt lgkmcnt(0)
	v_mfma_f32_16x16x32_bf16 v[104:107], v[92:95], v[148:151], v[104:107]
	v_mfma_f32_16x16x32_bf16 v[104:107], v[100:103], v[152:155], v[104:107]
	v_mfma_f32_16x16x32_bf16 v[88:91], v[92:95], v[176:179], v[88:91]
	v_mfma_f32_16x16x32_bf16 v[88:91], v[100:103], v[180:183], v[88:91]
	v_mfma_f32_16x16x32_bf16 v[80:83], v[92:95], v[184:187], v[80:83]
	v_mfma_f32_16x16x32_bf16 v[80:83], v[100:103], v[188:191], v[80:83]
	v_mfma_f32_16x16x32_bf16 v[72:75], v[92:95], v[192:195], v[72:75]
	v_mfma_f32_16x16x32_bf16 v[72:75], v[100:103], v[212:215], v[72:75]
	v_mfma_f32_16x16x32_bf16 v[96:99], v[132:135], v[148:151], v[96:99]
	v_mfma_f32_16x16x32_bf16 v[96:99], v[144:147], v[152:155], v[96:99]
	v_mfma_f32_16x16x32_bf16 v[84:87], v[132:135], v[176:179], v[84:87]
	v_mfma_f32_16x16x32_bf16 v[84:87], v[144:147], v[180:183], v[84:87]
	v_mfma_f32_16x16x32_bf16 v[76:79], v[132:135], v[184:187], v[76:79]
	v_mfma_f32_16x16x32_bf16 v[76:79], v[144:147], v[188:191], v[76:79]
	v_mfma_f32_16x16x32_bf16 v[68:71], v[132:135], v[192:195], v[68:71]
	v_mfma_f32_16x16x32_bf16 v[68:71], v[144:147], v[212:215], v[68:71]
	s_barrier
	s_setprio 0
	s_add_u32 s44, s6, 0x20000
	s_addc_u32 s45, s7, 0
	s_add_i32 s46, s46, s29
	v_lshl_add_u64 v[92:93], s[44:45], 0, v[158:159]
	s_mov_b32 m0, s46
	s_nop 0
	global_load_lds_dwordx4 v[92:93], off
	v_lshl_add_u64 v[92:93], s[44:45], 0, v[0:1]
	s_add_i32 m0, s46, 0x2000
	s_nop 0
	global_load_lds_dwordx4 v[92:93], off
	s_waitcnt vmcnt(6)
	s_setprio 1
	s_barrier
	v_mfma_f32_16x16x32_bf16 v[32:35], v[216:219], v[148:151], v[32:35]
	v_mfma_f32_16x16x32_bf16 v[32:35], v[220:223], v[152:155], v[32:35]
	v_mfma_f32_16x16x32_bf16 v[24:27], v[216:219], v[176:179], v[24:27]
	v_mfma_f32_16x16x32_bf16 v[24:27], v[220:223], v[180:183], v[24:27]
	v_mfma_f32_16x16x32_bf16 v[16:19], v[216:219], v[184:187], v[16:19]
	v_mfma_f32_16x16x32_bf16 v[16:19], v[220:223], v[188:191], v[16:19]
	v_mfma_f32_16x16x32_bf16 v[8:11], v[216:219], v[192:195], v[8:11]
	v_mfma_f32_16x16x32_bf16 v[8:11], v[220:223], v[212:215], v[8:11]
	v_mfma_f32_16x16x32_bf16 v[28:31], v[224:227], v[148:151], v[28:31]
	v_mfma_f32_16x16x32_bf16 v[28:31], v[228:231], v[152:155], v[28:31]
	v_mfma_f32_16x16x32_bf16 v[20:23], v[224:227], v[176:179], v[20:23]
	v_mfma_f32_16x16x32_bf16 v[20:23], v[228:231], v[180:183], v[20:23]
	v_mfma_f32_16x16x32_bf16 v[12:15], v[224:227], v[184:187], v[12:15]
	v_mfma_f32_16x16x32_bf16 v[12:15], v[228:231], v[188:191], v[12:15]
	v_mfma_f32_16x16x32_bf16 v[4:7], v[224:227], v[192:195], v[4:7]
	v_mfma_f32_16x16x32_bf16 v[4:7], v[228:231], v[212:215], v[4:7]
	s_barrier
	s_setprio 0
	s_add_i32 s44, 0, 0x18000
	v_add_u32_e32 v2, s44, v167
	ds_read_b128 v[92:95], v2
	ds_read_b128 v[100:103], v2 offset:1024
	ds_read_b128 v[132:135], v2 offset:2048
	ds_read_b128 v[144:147], v2 offset:3072
	s_add_u32 s10, s10, 0x80000
	s_addc_u32 s11, s11, 0
	s_mov_b32 m0, s34
	v_lshl_add_u64 v[216:217], s[10:11], 0, v[160:161]
	ds_read_b128 v[148:151], v169 offset:32768
	ds_read_b128 v[152:155], v169 offset:33792
	ds_read_b128 v[176:179], v169 offset:34816
	ds_read_b128 v[180:183], v169 offset:35840
	ds_read_b128 v[184:187], v169 offset:36864
	ds_read_b128 v[188:191], v169 offset:37888
	ds_read_b128 v[192:195], v169 offset:38912
	ds_read_b128 v[212:215], v169 offset:39936
	global_load_lds_dwordx4 v[216:217], off
	v_lshl_add_u64 v[216:217], s[10:11], 0, v[156:157]
	s_mov_b32 m0, s35
	s_nop 0
	global_load_lds_dwordx4 v[216:217], off
	s_waitcnt lgkmcnt(8)
	s_setprio 1
	s_barrier
; #define PG8_WAIT_V(n) asm volatile("s_waitcnt vmcnt(" #n ")" ::: "memory")
; #define PG8_WAIT_L(n) asm volatile("s_waitcnt lgkmcnt(" #n ")" ::: "memory")
; #define PG8_BAR __builtin_amdgcn_s_barrier()
; #define PG8_SCHED __builtin_amdgcn_sched_barrier(0)
; template <class Epi, class AddrA, class AddrB>
; __device__ __forceinline__ void gemm_phase(const Sched S, const int lda, const int ldb, const int K, const AddrA addrA,
;                                            const AddrB addrB, const Epi E) {
;     ...
;       PG8_WAIT_V(6); PG8_BAR; PG8_MMA(1, 1, At, B1); PG8_BAR;
;       PG8_LDB(B0, 1, 0); PG8_SCHED; PG8_LDA(At, 1, 0); PG8_STAGE(PG8_SA(0, 1), a2 + hstepA, voffA);
;       PG8_WAIT_L(8); PG8_BAR; PG8_WAIT_L(0); PG8_MMA(0, 0, At, B0); PG8_BAR; PG8_SCHED;
;       PG8_LDB(B1, 1, 1); PG8_STAGE(PG8_SB(1, 0), b3, voffB);
;       PG8_BAR; PG8_WAIT_L(0); PG8_MMA(0, 1, At, B1); PG8_BAR;
;       PG8_LDA(At, 1, 1); PG8_STAGE(PG8_SA(1, 0), a3, voffA);
;       PG8_BAR; PG8_WAIT_L(0); PG8_MMA(1, 0, At, B0); PG8_BAR; PG8_SCHED;
;       PG8_STAGE(PG8_SB(1, 1), b3 + hstepB, voffB);
;       PG8_WAIT_V(6); PG8_BAR; PG8_MMA(1, 1, At, B1); PG8_BAR;
	s_waitcnt lgkmcnt(0)
	v_mfma_f32_16x16x32_bf16 v[140:143], v[92:95], v[148:151], v[140:143]
	v_mfma_f32_16x16x32_bf16 v[140:143], v[100:103], v[152:155], v[140:143]
	v_mfma_f32_16x16x32_bf16 v[128:131], v[92:95], v[176:179], v[128:131]
	v_mfma_f32_16x16x32_bf16 v[128:131], v[100:103], v[180:183], v[128:131]
	v_mfma_f32_16x16x32_bf16 v[120:123], v[92:95], v[184:187], v[120:123]
	v_mfma_f32_16x16x32_bf16 v[120:123], v[100:103], v[188:191], v[120:123]
	v_mfma_f32_16x16x32_bf16 v[112:115], v[92:95], v[192:195], v[112:115]
	v_mfma_f32_16x16x32_bf16 v[112:115], v[100:103], v[212:215], v[112:115]
	v_mfma_f32_16x16x32_bf16 v[136:139], v[132:135], v[148:151], v[136:139]
	v_mfma_f32_16x16x32_bf16 v[136:139], v[144:147], v[152:155], v[136:139]
	v_mfma_f32_16x16x32_bf16 v[124:127], v[132:135], v[176:179], v[124:127]
	v_mfma_f32_16x16x32_bf16 v[124:127], v[144:147], v[180:183], v[124:127]
	v_mfma_f32_16x16x32_bf16 v[116:119], v[132:135], v[184:187], v[116:119]
	v_mfma_f32_16x16x32_bf16 v[116:119], v[144:147], v[188:191], v[116:119]
	v_mfma_f32_16x16x32_bf16 v[108:111], v[132:135], v[192:195], v[108:111]
	v_mfma_f32_16x16x32_bf16 v[108:111], v[144:147], v[212:215], v[108:111]
	s_barrier
	s_setprio 0
	s_add_i32 s10, 0, 0x1c000
	s_add_i32 s11, s44, s29
	v_add_u32_e32 v2, s10, v167
	v_lshl_add_u64 v[196:197], v[196:197], 0, s[52:53]
	s_mov_b32 m0, s11
	ds_read_b128 v[216:219], v2
	ds_read_b128 v[220:223], v2 offset:1024
	ds_read_b128 v[224:227], v2 offset:2048
	ds_read_b128 v[228:231], v2 offset:3072
	global_load_lds_dwordx4 v[196:197], off
	v_lshl_add_u64 v[196:197], v[232:233], 0, s[52:53]
	s_add_i32 m0, s11, 0x2000
	s_nop 0
	global_load_lds_dwordx4 v[196:197], off
	s_setprio 1
	s_barrier
	s_waitcnt lgkmcnt(0)
	v_mfma_f32_16x16x32_bf16 v[64:67], v[216:219], v[148:151], v[64:67]
	v_mfma_f32_16x16x32_bf16 v[64:67], v[220:223], v[152:155], v[64:67]
	v_mfma_f32_16x16x32_bf16 v[56:59], v[216:219], v[176:179], v[56:59]
	v_mfma_f32_16x16x32_bf16 v[56:59], v[220:223], v[180:183], v[56:59]
	v_mfma_f32_16x16x32_bf16 v[48:51], v[216:219], v[184:187], v[48:51]
	v_mfma_f32_16x16x32_bf16 v[48:51], v[220:223], v[188:191], v[48:51]
	v_mfma_f32_16x16x32_bf16 v[40:43], v[216:219], v[192:195], v[40:43]
	v_mfma_f32_16x16x32_bf16 v[40:43], v[220:223], v[212:215], v[40:43]
	v_mfma_f32_16x16x32_bf16 v[60:63], v[224:227], v[148:151], v[60:63]
	v_mfma_f32_16x16x32_bf16 v[60:63], v[228:231], v[152:155], v[60:63]
	v_mfma_f32_16x16x32_bf16 v[52:55], v[224:227], v[176:179], v[52:55]
	v_mfma_f32_16x16x32_bf16 v[52:55], v[228:231], v[180:183], v[52:55]
	v_mfma_f32_16x16x32_bf16 v[44:47], v[224:227], v[184:187], v[44:47]
	v_mfma_f32_16x16x32_bf16 v[44:47], v[228:231], v[188:191], v[44:47]
	v_mfma_f32_16x16x32_bf16 v[36:39], v[224:227], v[192:195], v[36:39]
	v_mfma_f32_16x16x32_bf16 v[36:39], v[228:231], v[212:215], v[36:39]
	s_barrier
	s_setprio 0
	s_mov_b32 m0, s37
	v_lshl_add_u64 v[196:197], v[234:235], 0, s[52:53]
	ds_read_b128 v[148:151], v169 offset:49152
	ds_read_b128 v[152:155], v169 offset:50176
	ds_read_b128 v[176:179], v169 offset:51200
	ds_read_b128 v[180:183], v169 offset:52224
	ds_read_b128 v[184:187], v169 offset:53248
	ds_read_b128 v[188:191], v169 offset:54272
	ds_read_b128 v[192:195], v169 offset:55296
	ds_read_b128 v[212:215], v169 offset:56320
	global_load_lds_dwordx4 v[196:197], off
	v_lshl_add_u64 v[196:197], v[236:237], 0, s[52:53]
	s_mov_b32 m0, s38
	s_nop 0
	global_load_lds_dwordx4 v[196:197], off
	s_setprio 1
	s_barrier
	s_waitcnt lgkmcnt(0)
	v_mfma_f32_16x16x32_bf16 v[104:107], v[92:95], v[148:151], v[104:107]
	v_mfma_f32_16x16x32_bf16 v[104:107], v[100:103], v[152:155], v[104:107]
	v_mfma_f32_16x16x32_bf16 v[88:91], v[92:95], v[176:179], v[88:91]
	v_mfma_f32_16x16x32_bf16 v[88:91], v[100:103], v[180:183], v[88:91]
	v_mfma_f32_16x16x32_bf16 v[80:83], v[92:95], v[184:187], v[80:83]
	v_mfma_f32_16x16x32_bf16 v[80:83], v[100:103], v[188:191], v[80:83]
	v_mfma_f32_16x16x32_bf16 v[72:75], v[92:95], v[192:195], v[72:75]
	v_mfma_f32_16x16x32_bf16 v[72:75], v[100:103], v[212:215], v[72:75]
	v_mfma_f32_16x16x32_bf16 v[96:99], v[132:135], v[148:151], v[96:99]
	v_mfma_f32_16x16x32_bf16 v[96:99], v[144:147], v[152:155], v[96:99]
	v_mfma_f32_16x16x32_bf16 v[84:87], v[132:135], v[176:179], v[84:87]
	v_mfma_f32_16x16x32_bf16 v[84:87], v[144:147], v[180:183], v[84:87]
	v_mfma_f32_16x16x32_bf16 v[76:79], v[132:135], v[184:187], v[76:79]
	v_mfma_f32_16x16x32_bf16 v[76:79], v[144:147], v[188:191], v[76:79]
	v_mfma_f32_16x16x32_bf16 v[68:71], v[132:135], v[192:195], v[68:71]
	v_mfma_f32_16x16x32_bf16 v[68:71], v[144:147], v[212:215], v[68:71]
	s_barrier
	s_setprio 0
	s_add_u32 s6, s6, 0x20080
	s_addc_u32 s7, s7, 0
	s_add_i32 s10, s10, s29
	v_lshl_add_u64 v[92:93], s[6:7], 0, v[158:159]
	s_mov_b32 m0, s10
	s_nop 0
	global_load_lds_dwordx4 v[92:93], off
	v_lshl_add_u64 v[92:93], s[6:7], 0, v[0:1]
	s_add_i32 m0, s10, 0x2000
	s_nop 0
	global_load_lds_dwordx4 v[92:93], off
	s_add_i32 s43, s43, 2
	s_add_u32 s41, s41, 0x100
	s_addc_u32 s42, s42, 0
	s_add_u32 s4, s4, 0x100
	s_addc_u32 s5, s5, 0
	s_waitcnt vmcnt(6)
	s_setprio 1
	s_barrier
	v_mfma_f32_16x16x32_bf16 v[32:35], v[216:219], v[148:151], v[32:35]
	v_mfma_f32_16x16x32_bf16 v[32:35], v[220:223], v[152:155], v[32:35]
	v_mfma_f32_16x16x32_bf16 v[24:27], v[216:219], v[176:179], v[24:27]
	v_mfma_f32_16x16x32_bf16 v[24:27], v[220:223], v[180:183], v[24:27]
	v_mfma_f32_16x16x32_bf16 v[16:19], v[216:219], v[184:187], v[16:19]
	v_mfma_f32_16x16x32_bf16 v[16:19], v[220:223], v[188:191], v[16:19]
	v_mfma_f32_16x16x32_bf16 v[8:11], v[216:219], v[192:195], v[8:11]
	v_mfma_f32_16x16x32_bf16 v[8:11], v[220:223], v[212:215], v[8:11]
	v_mfma_f32_16x16x32_bf16 v[28:31], v[224:227], v[148:151], v[28:31]
	v_mfma_f32_16x16x32_bf16 v[28:31], v[228:231], v[152:155], v[28:31]
	v_mfma_f32_16x16x32_bf16 v[20:23], v[224:227], v[176:179], v[20:23]
	v_mfma_f32_16x16x32_bf16 v[20:23], v[228:231], v[180:183], v[20:23]
	v_mfma_f32_16x16x32_bf16 v[12:15], v[224:227], v[184:187], v[12:15]
	v_mfma_f32_16x16x32_bf16 v[12:15], v[228:231], v[188:191], v[12:15]
	v_mfma_f32_16x16x32_bf16 v[4:7], v[224:227], v[192:195], v[4:7]
	v_mfma_f32_16x16x32_bf16 v[4:7], v[228:231], v[212:215], v[4:7]
	s_barrier
; __device__ __forceinline__ size_t pidx(size_t row, int col) { return ((size_t)(col >> 8) * MTOK + row) * PLD + (col & 255); }
; __device__ __forceinline__ float bflo(unsigned v) { return __uint_as_float(v << 16); }
; __device__ __forceinline__ float bfhi(unsigned v) { return __uint_as_float(v & 0xffff0000u); }
; __device__ __forceinline__ float siluf_(float x) { return x * __builtin_amdgcn_rcpf(1.0f + __expf(-x)); }
; #define PG8_WAIT_V(n) asm volatile("s_waitcnt vmcnt(" #n ")" ::: "memory")
; #define PG8_BAR __builtin_amdgcn_s_barrier()
; template <class Epi, class AddrA, class AddrB>
; __device__ __forceinline__ void gemm_phase(const Sched S, const int lda, const int ldb, const int K, const AddrA addrA,
;                                            const AddrB addrB, const Epi E) {
;     ...
;       PG8_WAIT_V(6); PG8_BAR; PG8_MMA(1, 1, At, B1); PG8_BAR;
;     }
;     E(acc, cur, wr, wc, fr, fq);
;   __device__ __forceinline__ void operator()(EPI_ARGS) const {
;     const size_t row0 = (size_t)u.pm * 256 + wr * 64 + fr;
;     const int col0 = u.pn * 256 + wc * 32 + 8 * fq;
; #pragma unroll
;     for (int bj = 0; bj < 2; ++bj) {
;       const int c = col0 + bj * HALF;
;       const f32x4 s0 = *(const f32x4*)(psc + c), s1 = *(const f32x4*)(psc + c + 4);
; #pragma unroll
;       for (int ai = 0; ai < 2; ++ai) {
;         u32x4 z[4];
; #pragma unroll
;         for (int m = 0; m < 4; ++m) z[m] = *(const u32x4*)(proj + pidx(row0 + ai * HALF + m * 16, PZ + c));
;         __builtin_amdgcn_sched_barrier(0);
; #pragma unroll
;         for (int m = 0; m < 4; ++m) {
;           const size_t row = row0 + ai * HALF + m * 16;
;           const f32x4 v0 = acc[ai][bj][m][0], v1 = acc[ai][bj][m][1];
;           u32x4 o;
;           o.x = pack2(v0[0] * s0[0] * siluf_(bflo(z[m].x)), v0[1] * s0[1] * siluf_(bfhi(z[m].x)));
;           o.y = pack2(v0[2] * s0[2] * siluf_(bflo(z[m].y)), v0[3] * s0[3] * siluf_(bfhi(z[m].y)));
;           o.z = pack2(v1[0] * s1[0] * siluf_(bflo(z[m].z)), v1[1] * s1[1] * siluf_(bfhi(z[m].z)));
;           o.w = pack2(v1[2] * s1[2] * siluf_(bflo(z[m].w)), v1[3] * s1[3] * siluf_(bfhi(z[m].w)));
;           *(u32x4*)(y0 + row * DM + c) = o;
	s_setprio 0
	s_cmp_gt_u32 s43, 5
	s_cbranch_scc0 .LBB0_485
	s_ashr_i32 s3, s2, 31
	s_lshl_b64 s[2:3], s[2:3], 8
	v_lshl_add_u64 v[186:187], s[2:3], 0, v[162:163]
	s_lshl_b32 s2, s33, 8
	v_or_b32_e32 v196, s2, v168
	s_addk_i32 s2, 0x800
	s_ashr_i32 s2, s2, 8
	s_ashr_i32 s3, s2, 31
	s_lshl_b64 s[2:3], s[2:3], 23
	s_add_u32 s2, s0, s2
	s_addc_u32 s3, s1, s3
	v_lshlrev_b32_e32 v2, 1, v168
	v_or_b32_e32 v194, 16, v186
	v_mov_b32_e32 v195, v187
	v_ashrrev_i32_e32 v197, 31, v196
	v_lshl_add_u64 v[188:189], s[2:3], 0, v[2:3]
	v_lshlrev_b64 v[178:179], 9, v[186:187]
	v_lshlrev_b64 v[180:181], 9, v[194:195]
	v_or_b32_e32 v192, 32, v186
	v_mov_b32_e32 v193, v187
	v_or_b32_e32 v190, 48, v186
	v_mov_b32_e32 v191, v187
	v_lshl_add_u64 v[176:177], v[196:197], 2, s[12:13]
	v_lshl_add_u64 v[132:133], v[188:189], 0, v[178:179]
	v_lshl_add_u64 v[134:135], v[188:189], 0, v[180:181]
	v_lshlrev_b64 v[182:183], 9, v[192:193]
	v_lshlrev_b64 v[184:185], 9, v[190:191]
	global_load_dwordx4 v[92:95], v[176:177], off offset:16
	global_load_dwordx4 v[100:103], v[176:177], off
	flat_load_dwordx4 v[152:155], v[132:133]
	flat_load_dwordx4 v[148:151], v[134:135]
	v_lshl_add_u64 v[132:133], v[188:189], 0, v[182:183]
	v_lshl_add_u64 v[134:135], v[188:189], 0, v[184:185]
	flat_load_dwordx4 v[144:147], v[132:133]
	s_nop 0
	flat_load_dwordx4 v[132:135], v[134:135]
	s_waitcnt vmcnt(0) lgkmcnt(0)
	v_lshlrev_b32_e32 v213, 16, v152
	v_mul_f32_e32 v2, 0xbfb8aa3b, v213
	v_exp_f32_e32 v2, v2
	v_mov_b32_e32 v214, v140
	v_mov_b32_e32 v212, v100
	s_mov_b64 s[4:5], 0x90
	v_add_f32_e32 v2, 1.0, v2
	v_rcp_f32_e32 v215, v2
	s_nop 0
	v_pk_mul_f32 v[212:213], v[214:215], v[212:213]
	s_nop 0
	v_mul_f32_e32 v2, v212, v213
	v_and_b32_e32 v213, 0xffff0000, v152
	v_mul_f32_e32 v140, 0xbfb8aa3b, v213
	v_exp_f32_e32 v140, v140
	v_mov_b32_e32 v214, v141
	v_mov_b32_e32 v212, v101
	v_add_f32_e32 v140, 1.0, v140
	v_rcp_f32_e32 v215, v140
	s_nop 0
	v_pk_mul_f32 v[140:141], v[214:215], v[212:213]
	s_nop 0
	v_mul_f32_e32 v140, v140, v141
	v_lshlrev_b32_e32 v141, 16, v153
	v_cvt_pk_bf16_f32 v152, v2, v140
	v_mul_f32_e32 v2, 0xbfb8aa3b, v141
	v_exp_f32_e32 v2, v2
	v_mov_b32_e32 v212, v142
	v_mov_b32_e32 v140, v102
	v_mov_b32_e32 v142, v136
	v_add_f32_e32 v2, 1.0, v2
	v_rcp_f32_e32 v213, v2
	s_nop 0
	v_pk_mul_f32 v[140:141], v[212:213], v[140:141]
	s_nop 0
	v_mul_f32_e32 v2, v140, v141
	v_and_b32_e32 v141, 0xffff0000, v153
	v_mul_f32_e32 v140, 0xbfb8aa3b, v141
	v_exp_f32_e32 v140, v140
	v_mov_b32_e32 v212, v143
	v_add_f32_e32 v140, 1.0, v140
	v_rcp_f32_e32 v213, v140
	v_mov_b32_e32 v140, v103
	v_pk_mul_f32 v[140:141], v[212:213], v[140:141]
	s_nop 0
	v_mul_f32_e32 v140, v140, v141
	v_lshlrev_b32_e32 v141, 16, v154
	v_cvt_pk_bf16_f32 v153, v2, v140
	v_mul_f32_e32 v2, 0xbfb8aa3b, v141
	v_exp_f32_e32 v2, v2
	v_mov_b32_e32 v140, v92
	v_add_f32_e32 v2, 1.0, v2
	v_rcp_f32_e32 v143, v2
	s_nop 0
	v_pk_mul_f32 v[140:141], v[142:143], v[140:141]
	s_nop 0
	v_mul_f32_e32 v2, v140, v141
	v_and_b32_e32 v141, 0xffff0000, v154
	v_mul_f32_e32 v136, 0xbfb8aa3b, v141
	v_exp_f32_e32 v136, v136
	v_mov_b32_e32 v142, v137
	v_mov_b32_e32 v140, v93
	v_add_f32_e32 v136, 1.0, v136
	v_rcp_f32_e32 v143, v136
	s_nop 0
	v_pk_mul_f32 v[136:137], v[142:143], v[140:141]
	s_nop 0
	v_mul_f32_e32 v136, v136, v137
	v_lshlrev_b32_e32 v137, 16, v155
	v_cvt_pk_bf16_f32 v154, v2, v136
	v_mul_f32_e32 v2, 0xbfb8aa3b, v137
	v_exp_f32_e32 v2, v2
	v_mov_b32_e32 v140, v138
	v_mov_b32_e32 v136, v94
	v_mov_b32_e32 v142, v128
	v_add_f32_e32 v2, 1.0, v2
	v_rcp_f32_e32 v141, v2
	v_mov_b32_e32 v138, v100
	v_pk_mul_f32 v[136:137], v[140:141], v[136:137]
	s_nop 0
	v_mul_f32_e32 v2, v136, v137
	v_and_b32_e32 v137, 0xffff0000, v155
	v_mul_f32_e32 v136, 0xbfb8aa3b, v137
	v_exp_f32_e32 v136, v136
	v_mov_b32_e32 v140, v139
	v_lshlrev_b32_e32 v139, 16, v148
	v_add_f32_e32 v136, 1.0, v136
	v_rcp_f32_e32 v141, v136
	v_mov_b32_e32 v136, v95
	v_pk_mul_f32 v[136:137], v[140:141], v[136:137]
	s_nop 0
	v_mul_f32_e32 v136, v136, v137
	v_cvt_pk_bf16_f32 v155, v2, v136
	v_mul_f32_e32 v2, 0xbfb8aa3b, v139
	v_exp_f32_e32 v2, v2
	v_lshlrev_b64 v[140:141], 1, v[196:197]
	v_lshlrev_b64 v[136:137], 12, v[186:187]
	v_lshl_add_u64 v[136:137], s[8:9], 0, v[136:137]
	v_add_f32_e32 v2, 1.0, v2
	v_rcp_f32_e32 v143, v2
	v_lshl_add_u64 v[136:137], v[136:137], 0, v[140:141]
	flat_store_dwordx4 v[136:137], v[152:155]
	v_pk_mul_f32 v[138:139], v[142:143], v[138:139]
	s_nop 0
	v_mul_f32_e32 v2, v138, v139
	v_and_b32_e32 v139, 0xffff0000, v148
	v_mul_f32_e32 v128, 0xbfb8aa3b, v139
	v_exp_f32_e32 v128, v128
	v_mov_b32_e32 v142, v129
	v_mov_b32_e32 v138, v101
	v_add_f32_e32 v128, 1.0, v128
	v_rcp_f32_e32 v143, v128
	s_nop 0
	v_pk_mul_f32 v[128:129], v[142:143], v[138:139]
	s_nop 0
	v_mul_f32_e32 v128, v128, v129
	v_lshlrev_b32_e32 v139, 16, v149
	v_cvt_pk_bf16_f32 v128, v2, v128
	v_mul_f32_e32 v2, 0xbfb8aa3b, v139
	v_exp_f32_e32 v2, v2
	v_mov_b32_e32 v142, v130
	v_mov_b32_e32 v138, v102
	v_add_f32_e32 v2, 1.0, v2
	v_rcp_f32_e32 v143, v2
	s_nop 0
	v_pk_mul_f32 v[138:139], v[142:143], v[138:139]
	s_nop 0
	v_mul_f32_e32 v2, v138, v139
	v_and_b32_e32 v139, 0xffff0000, v149
	v_mul_f32_e32 v129, 0xbfb8aa3b, v139
	v_exp_f32_e32 v129, v129
	v_mov_b32_e32 v142, v131
	v_mov_b32_e32 v138, v103
	v_lshl_add_u64 v[148:149], v[186:187], 0, s[52:53]
	v_add_f32_e32 v129, 1.0, v129
	v_rcp_f32_e32 v143, v129
	s_nop 0
	v_pk_mul_f32 v[130:131], v[142:143], v[138:139]
	s_nop 0
	v_mul_f32_e32 v129, v130, v131
	v_lshlrev_b32_e32 v131, 16, v150
	v_cvt_pk_bf16_f32 v129, v2, v129
	v_mul_f32_e32 v2, 0xbfb8aa3b, v131
	v_exp_f32_e32 v2, v2
	v_mov_b32_e32 v138, v124
	v_mov_b32_e32 v130, v92
	v_add_f32_e32 v2, 1.0, v2
; __device__ __forceinline__ size_t pidx(size_t row, int col) { return ((size_t)(col >> 8) * MTOK + row) * PLD + (col & 255); }
; __device__ __forceinline__ float bflo(unsigned v) { return __uint_as_float(v << 16); }
; __device__ __forceinline__ float bfhi(unsigned v) { return __uint_as_float(v & 0xffff0000u); }
; __device__ __forceinline__ float siluf_(float x) { return x * __builtin_amdgcn_rcpf(1.0f + __expf(-x)); }
;   __device__ __forceinline__ void operator()(EPI_ARGS) const {
;     ...
;         for (int m = 0; m < 4; ++m) z[m] = *(const u32x4*)(proj + pidx(row0 + ai * HALF + m * 16, PZ + c));
;         __builtin_amdgcn_sched_barrier(0);
; #pragma unroll
;         for (int m = 0; m < 4; ++m) {
;           const size_t row = row0 + ai * HALF + m * 16;
;           const f32x4 v0 = acc[ai][bj][m][0], v1 = acc[ai][bj][m][1];
;           u32x4 o;
;           o.x = pack2(v0[0] * s0[0] * siluf_(bflo(z[m].x)), v0[1] * s0[1] * siluf_(bfhi(z[m].x)));
;           o.y = pack2(v0[2] * s0[2] * siluf_(bflo(z[m].y)), v0[3] * s0[3] * siluf_(bfhi(z[m].y)));
;           o.z = pack2(v1[0] * s1[0] * siluf_(bflo(z[m].z)), v1[1] * s1[1] * siluf_(bfhi(z[m].z)));
;           o.w = pack2(v1[2] * s1[2] * siluf_(bflo(z[m].w)), v1[3] * s1[3] * siluf_(bfhi(z[m].w)));
;           *(u32x4*)(y0 + row * DM + c) = o;
	v_rcp_f32_e32 v139, v2
	s_nop 0
	v_pk_mul_f32 v[130:131], v[138:139], v[130:131]
	s_nop 0
	v_mul_f32_e32 v2, v130, v131
	v_and_b32_e32 v131, 0xffff0000, v150
	v_mul_f32_e32 v124, 0xbfb8aa3b, v131
	v_exp_f32_e32 v124, v124
	v_mov_b32_e32 v138, v125
	v_mov_b32_e32 v130, v93
	v_add_f32_e32 v124, 1.0, v124
	v_rcp_f32_e32 v139, v124
	s_nop 0
	v_pk_mul_f32 v[124:125], v[138:139], v[130:131]
	s_nop 0
	v_mul_f32_e32 v124, v124, v125
	v_lshlrev_b32_e32 v125, 16, v151
	v_cvt_pk_bf16_f32 v130, v2, v124
	v_mul_f32_e32 v2, 0xbfb8aa3b, v125
	v_exp_f32_e32 v2, v2
	v_mov_b32_e32 v138, v126
	v_mov_b32_e32 v124, v94
	v_mov_b32_e32 v126, v100
	v_add_f32_e32 v2, 1.0, v2
	v_rcp_f32_e32 v139, v2
	s_nop 0
	v_pk_mul_f32 v[124:125], v[138:139], v[124:125]
	s_nop 0
	v_mul_f32_e32 v2, v124, v125
	v_and_b32_e32 v125, 0xffff0000, v151
	v_mul_f32_e32 v124, 0xbfb8aa3b, v125
	v_exp_f32_e32 v124, v124
	v_mov_b32_e32 v138, v127
	v_lshlrev_b32_e32 v127, 16, v144
	v_add_f32_e32 v124, 1.0, v124
	v_rcp_f32_e32 v139, v124
	v_mov_b32_e32 v124, v95
	v_pk_mul_f32 v[124:125], v[138:139], v[124:125]
	s_nop 0
	v_mul_f32_e32 v124, v124, v125
	v_cvt_pk_bf16_f32 v131, v2, v124
	v_mul_f32_e32 v2, 0xbfb8aa3b, v127
	v_exp_f32_e32 v2, v2
	v_lshlrev_b64 v[124:125], 12, v[194:195]
	v_lshl_add_u64 v[124:125], s[8:9], 0, v[124:125]
	v_lshl_add_u64 v[124:125], v[124:125], 0, v[140:141]
	v_add_f32_e32 v2, 1.0, v2
	flat_store_dwordx4 v[124:125], v[128:131]
	s_nop 1
	v_rcp_f32_e32 v129, v2
	v_mov_b32_e32 v128, v120
	v_lshlrev_b64 v[130:131], 9, v[148:149]
	v_pk_mul_f32 v[126:127], v[128:129], v[126:127]
	s_nop 0
	v_mul_f32_e32 v2, v126, v127
	v_and_b32_e32 v127, 0xffff0000, v144
	v_mul_f32_e32 v120, 0xbfb8aa3b, v127
	v_exp_f32_e32 v120, v120
	v_mov_b32_e32 v128, v121
	v_mov_b32_e32 v126, v101
	v_add_f32_e32 v120, 1.0, v120
	v_rcp_f32_e32 v129, v120
	s_nop 0
	v_pk_mul_f32 v[120:121], v[128:129], v[126:127]
	s_nop 0
	v_mul_f32_e32 v120, v120, v121
	v_lshlrev_b32_e32 v127, 16, v145
	v_cvt_pk_bf16_f32 v120, v2, v120
	v_mul_f32_e32 v2, 0xbfb8aa3b, v127
	v_exp_f32_e32 v2, v2
	v_mov_b32_e32 v128, v122
	v_mov_b32_e32 v126, v102
	v_add_f32_e32 v2, 1.0, v2
	v_rcp_f32_e32 v129, v2
	s_nop 0
	v_pk_mul_f32 v[126:127], v[128:129], v[126:127]
	s_nop 0
	v_mul_f32_e32 v2, v126, v127
	v_and_b32_e32 v127, 0xffff0000, v145
	v_mul_f32_e32 v121, 0xbfb8aa3b, v127
	v_exp_f32_e32 v121, v121
	v_mov_b32_e32 v128, v123
	v_mov_b32_e32 v126, v103
	v_add_f32_e32 v121, 1.0, v121
	v_rcp_f32_e32 v129, v121
	s_nop 0
	v_pk_mul_f32 v[122:123], v[128:129], v[126:127]
	s_nop 0
	v_mul_f32_e32 v121, v122, v123
	v_lshlrev_b32_e32 v123, 16, v146
	v_cvt_pk_bf16_f32 v121, v2, v121
	v_mul_f32_e32 v2, 0xbfb8aa3b, v123
	v_exp_f32_e32 v2, v2
	v_mov_b32_e32 v126, v116
	v_mov_b32_e32 v122, v92
	v_add_f32_e32 v2, 1.0, v2
	v_rcp_f32_e32 v127, v2
	s_nop 0
	v_pk_mul_f32 v[122:123], v[126:127], v[122:123]
	s_nop 0
	v_mul_f32_e32 v2, v122, v123
	v_and_b32_e32 v123, 0xffff0000, v146
	v_mul_f32_e32 v116, 0xbfb8aa3b, v123
	v_exp_f32_e32 v116, v116
	v_mov_b32_e32 v126, v117
	v_mov_b32_e32 v122, v93
	v_add_f32_e32 v116, 1.0, v116
	v_rcp_f32_e32 v127, v116
	s_nop 0
	v_pk_mul_f32 v[116:117], v[126:127], v[122:123]
	s_nop 0
	v_mul_f32_e32 v116, v116, v117
	v_lshlrev_b32_e32 v117, 16, v147
	v_cvt_pk_bf16_f32 v122, v2, v116
	v_mul_f32_e32 v2, 0xbfb8aa3b, v117
	v_exp_f32_e32 v2, v2
	v_mov_b32_e32 v126, v118
	v_mov_b32_e32 v116, v94
	v_mov_b32_e32 v118, v112
	v_add_f32_e32 v2, 1.0, v2
	v_rcp_f32_e32 v127, v2
	s_nop 0
	v_pk_mul_f32 v[116:117], v[126:127], v[116:117]
	s_nop 0
	v_mul_f32_e32 v2, v116, v117
	v_and_b32_e32 v117, 0xffff0000, v147
	v_mul_f32_e32 v116, 0xbfb8aa3b, v117
	v_exp_f32_e32 v116, v116
	v_mov_b32_e32 v126, v119
	v_lshl_add_u64 v[146:147], v[186:187], 0, s[4:5]
	s_mov_b64 s[4:5], 0xa0
	v_add_f32_e32 v116, 1.0, v116
	v_rcp_f32_e32 v127, v116
	v_mov_b32_e32 v116, v95
	v_lshl_add_u64 v[144:145], v[186:187], 0, s[4:5]
	s_mov_b64 s[4:5], 0xb0
	v_pk_mul_f32 v[116:117], v[126:127], v[116:117]
	v_lshl_add_u64 v[142:143], v[186:187], 0, s[4:5]
	v_mul_f32_e32 v116, v116, v117
	v_cvt_pk_bf16_f32 v123, v2, v116
	v_lshlrev_b64 v[116:117], 12, v[192:193]
	v_lshl_add_u64 v[116:117], s[8:9], 0, v[116:117]
	v_lshl_add_u64 v[128:129], v[116:117], 0, v[140:141]
	v_lshlrev_b32_e32 v117, 16, v132
	v_mul_f32_e32 v2, 0xbfb8aa3b, v117
	v_exp_f32_e32 v2, v2
	v_mov_b32_e32 v116, v100
	flat_store_dwordx4 v[128:129], v[120:123]
	v_lshlrev_b64 v[138:139], 9, v[142:143]
	v_add_f32_e32 v2, 1.0, v2
	v_rcp_f32_e32 v119, v2
	s_nop 0
	v_pk_mul_f32 v[116:117], v[118:119], v[116:117]
	s_nop 0
	v_mul_f32_e32 v2, v116, v117
	v_and_b32_e32 v117, 0xffff0000, v132
	v_mul_f32_e32 v112, 0xbfb8aa3b, v117
	v_exp_f32_e32 v112, v112
	v_mov_b32_e32 v118, v113
	v_mov_b32_e32 v116, v101
	v_add_f32_e32 v112, 1.0, v112
	v_rcp_f32_e32 v119, v112
	s_nop 0
	v_pk_mul_f32 v[112:113], v[118:119], v[116:117]
	s_nop 0
	v_mul_f32_e32 v112, v112, v113
	v_lshlrev_b32_e32 v117, 16, v133
	v_cvt_pk_bf16_f32 v112, v2, v112
	v_mul_f32_e32 v2, 0xbfb8aa3b, v117
	v_exp_f32_e32 v2, v2
	v_mov_b32_e32 v118, v114
	v_mov_b32_e32 v116, v102
	v_add_f32_e32 v2, 1.0, v2
	v_rcp_f32_e32 v119, v2
	s_nop 0
	v_pk_mul_f32 v[116:117], v[118:119], v[116:117]
	s_nop 0
	v_mul_f32_e32 v2, v116, v117
	v_and_b32_e32 v117, 0xffff0000, v133
	v_mul_f32_e32 v113, 0xbfb8aa3b, v117
	v_exp_f32_e32 v113, v113
	v_mov_b32_e32 v118, v115
	v_mov_b32_e32 v116, v103
	v_lshlrev_b64 v[132:133], 9, v[146:147]
	v_add_f32_e32 v113, 1.0, v113
	v_rcp_f32_e32 v119, v113
	s_nop 0
	v_pk_mul_f32 v[114:115], v[118:119], v[116:117]
	s_nop 0
	v_mul_f32_e32 v113, v114, v115
	v_lshlrev_b32_e32 v115, 16, v134
	v_cvt_pk_bf16_f32 v113, v2, v113
	v_mul_f32_e32 v2, 0xbfb8aa3b, v115
; __device__ __forceinline__ size_t pidx(size_t row, int col) { return ((size_t)(col >> 8) * MTOK + row) * PLD + (col & 255); }
; __device__ __forceinline__ float bflo(unsigned v) { return __uint_as_float(v << 16); }
; __device__ __forceinline__ float bfhi(unsigned v) { return __uint_as_float(v & 0xffff0000u); }
; __device__ __forceinline__ float siluf_(float x) { return x * __builtin_amdgcn_rcpf(1.0f + __expf(-x)); }
;   __device__ __forceinline__ void operator()(EPI_ARGS) const {
;     ...
;         for (int m = 0; m < 4; ++m) z[m] = *(const u32x4*)(proj + pidx(row0 + ai * HALF + m * 16, PZ + c));
;         __builtin_amdgcn_sched_barrier(0);
; #pragma unroll
;         for (int m = 0; m < 4; ++m) {
;           const size_t row = row0 + ai * HALF + m * 16;
;           const f32x4 v0 = acc[ai][bj][m][0], v1 = acc[ai][bj][m][1];
;           u32x4 o;
;           o.x = pack2(v0[0] * s0[0] * siluf_(bflo(z[m].x)), v0[1] * s0[1] * siluf_(bfhi(z[m].x)));
;           o.y = pack2(v0[2] * s0[2] * siluf_(bflo(z[m].y)), v0[3] * s0[3] * siluf_(bfhi(z[m].y)));
;           o.z = pack2(v1[0] * s1[0] * siluf_(bflo(z[m].z)), v1[1] * s1[1] * siluf_(bfhi(z[m].z)));
;           o.w = pack2(v1[2] * s1[2] * siluf_(bflo(z[m].w)), v1[3] * s1[3] * siluf_(bfhi(z[m].w)));
;           *(u32x4*)(y0 + row * DM + c) = o;
	v_exp_f32_e32 v2, v2
	v_mov_b32_e32 v116, v108
	v_mov_b32_e32 v114, v92
	v_add_f32_e32 v2, 1.0, v2
	v_rcp_f32_e32 v117, v2
	s_nop 0
	v_pk_mul_f32 v[114:115], v[116:117], v[114:115]
	s_nop 0
	v_mul_f32_e32 v2, v114, v115
	v_and_b32_e32 v115, 0xffff0000, v134
	v_mul_f32_e32 v108, 0xbfb8aa3b, v115
	v_exp_f32_e32 v108, v108
	v_mov_b32_e32 v116, v109
	v_mov_b32_e32 v114, v93
	v_add_f32_e32 v108, 1.0, v108
	v_rcp_f32_e32 v117, v108
	s_nop 0
	v_pk_mul_f32 v[108:109], v[116:117], v[114:115]
	s_nop 0
	v_mul_f32_e32 v108, v108, v109
	v_lshlrev_b32_e32 v109, 16, v135
	v_cvt_pk_bf16_f32 v114, v2, v108
	v_mul_f32_e32 v2, 0xbfb8aa3b, v109
	v_exp_f32_e32 v2, v2
	v_mov_b32_e32 v116, v110
	v_mov_b32_e32 v108, v94
	v_add_f32_e32 v2, 1.0, v2
	v_rcp_f32_e32 v117, v2
	s_nop 0
	v_pk_mul_f32 v[108:109], v[116:117], v[108:109]
	s_nop 0
	v_mul_f32_e32 v2, v108, v109
	v_and_b32_e32 v109, 0xffff0000, v135
	v_mul_f32_e32 v108, 0xbfb8aa3b, v109
	v_exp_f32_e32 v108, v108
	v_mov_b32_e32 v116, v111
	v_lshlrev_b64 v[134:135], 9, v[144:145]
	v_add_f32_e32 v108, 1.0, v108
	v_rcp_f32_e32 v117, v108
	v_mov_b32_e32 v108, v95
	v_pk_mul_f32 v[108:109], v[116:117], v[108:109]
	s_nop 0
	v_mul_f32_e32 v108, v108, v109
	v_cvt_pk_bf16_f32 v115, v2, v108
	v_lshlrev_b64 v[108:109], 12, v[190:191]
	v_lshl_add_u64 v[108:109], s[8:9], 0, v[108:109]
	v_lshl_add_u64 v[126:127], v[108:109], 0, v[140:141]
	flat_store_dwordx4 v[126:127], v[112:115]
	v_lshl_add_u64 v[108:109], v[188:189], 0, v[130:131]
	flat_load_dwordx4 v[120:123], v[108:109]
	v_lshl_add_u64 v[108:109], v[188:189], 0, v[132:133]
	flat_load_dwordx4 v[116:119], v[108:109]
	v_lshl_add_u64 v[108:109], v[188:189], 0, v[134:135]
	flat_load_dwordx4 v[112:115], v[108:109]
	v_lshl_add_u64 v[108:109], v[188:189], 0, v[138:139]
	flat_load_dwordx4 v[108:111], v[108:109]
	s_waitcnt vmcnt(0) lgkmcnt(0)
	v_lshlrev_b32_e32 v151, 16, v120
	v_mul_f32_e32 v2, 0xbfb8aa3b, v151
	v_exp_f32_e32 v2, v2
	v_mov_b32_e32 v152, v104
	v_mov_b32_e32 v150, v100
	v_mov_b32_e32 v175, v3
	v_add_f32_e32 v2, 1.0, v2
	v_rcp_f32_e32 v153, v2
	s_nop 0
	v_pk_mul_f32 v[150:151], v[152:153], v[150:151]
	s_nop 0
	v_mul_f32_e32 v2, v150, v151
	v_and_b32_e32 v151, 0xffff0000, v120
	v_mul_f32_e32 v104, 0xbfb8aa3b, v151
	v_exp_f32_e32 v104, v104
	v_mov_b32_e32 v152, v105
	v_mov_b32_e32 v150, v101
	v_mov_b32_e32 v120, v103
	v_add_f32_e32 v104, 1.0, v104
	v_rcp_f32_e32 v153, v104
	s_nop 0
	v_pk_mul_f32 v[104:105], v[152:153], v[150:151]
	s_nop 0
	v_mul_f32_e32 v104, v104, v105
	v_lshlrev_b32_e32 v151, 16, v121
	v_cvt_pk_bf16_f32 v104, v2, v104
	v_mul_f32_e32 v2, 0xbfb8aa3b, v151
	v_exp_f32_e32 v2, v2
	v_and_b32_e32 v121, 0xffff0000, v121
	v_mul_f32_e32 v105, 0xbfb8aa3b, v121
	v_exp_f32_e32 v105, v105
	v_add_f32_e32 v2, 1.0, v2
	v_rcp_f32_e32 v153, v2
	v_mov_b32_e32 v152, v106
	v_mov_b32_e32 v150, v102
	v_add_f32_e32 v105, 1.0, v105
	v_pk_mul_f32 v[150:151], v[152:153], v[150:151]
	s_nop 0
	v_mul_f32_e32 v2, v150, v151
	v_rcp_f32_e32 v151, v105
	v_mov_b32_e32 v150, v107
	v_pk_mul_f32 v[106:107], v[150:151], v[120:121]
	s_nop 0
	v_mul_f32_e32 v105, v106, v107
	v_lshlrev_b32_e32 v107, 16, v122
	v_cvt_pk_bf16_f32 v105, v2, v105
	v_mul_f32_e32 v2, 0xbfb8aa3b, v107
	v_exp_f32_e32 v2, v2
	v_mov_b32_e32 v120, v96
	v_mov_b32_e32 v106, v92
	v_add_f32_e32 v2, 1.0, v2
	v_rcp_f32_e32 v121, v2
	s_nop 0
	v_pk_mul_f32 v[106:107], v[120:121], v[106:107]
	s_nop 0
	v_mul_f32_e32 v2, v106, v107
	v_and_b32_e32 v107, 0xffff0000, v122
	v_mul_f32_e32 v96, 0xbfb8aa3b, v107
	v_exp_f32_e32 v96, v96
	v_mov_b32_e32 v120, v97
	v_mov_b32_e32 v106, v93
	v_add_f32_e32 v96, 1.0, v96
	v_rcp_f32_e32 v121, v96
	s_nop 0
	v_pk_mul_f32 v[96:97], v[120:121], v[106:107]
	s_nop 0
	v_mul_f32_e32 v96, v96, v97
	v_lshlrev_b32_e32 v97, 16, v123
	v_cvt_pk_bf16_f32 v106, v2, v96
	v_mul_f32_e32 v2, 0xbfb8aa3b, v97
	v_exp_f32_e32 v2, v2
	v_mov_b32_e32 v120, v98
	v_mov_b32_e32 v96, v94
	v_mov_b32_e32 v98, v100
	v_add_f32_e32 v2, 1.0, v2
	v_rcp_f32_e32 v121, v2
	s_nop 0
	v_pk_mul_f32 v[96:97], v[120:121], v[96:97]
	s_nop 0
	v_mul_f32_e32 v2, v96, v97
	v_and_b32_e32 v97, 0xffff0000, v123
	v_mul_f32_e32 v96, 0xbfb8aa3b, v97
	v_exp_f32_e32 v96, v96
	v_mov_b32_e32 v120, v99
	v_lshlrev_b32_e32 v99, 16, v116
	v_add_f32_e32 v96, 1.0, v96
	v_rcp_f32_e32 v121, v96
	v_mov_b32_e32 v96, v95
	v_pk_mul_f32 v[96:97], v[120:121], v[96:97]
	s_nop 0
	v_mul_f32_e32 v96, v96, v97
	v_cvt_pk_bf16_f32 v107, v2, v96
	v_mul_f32_e32 v2, 0xbfb8aa3b, v99
	v_exp_f32_e32 v2, v2
	v_lshlrev_b64 v[96:97], 12, v[148:149]
	v_lshl_add_u64 v[96:97], s[8:9], 0, v[96:97]
	v_lshl_add_u64 v[96:97], v[96:97], 0, v[140:141]
	v_add_f32_e32 v2, 1.0, v2
	flat_store_dwordx4 v[96:97], v[104:107]
	s_nop 1
	v_rcp_f32_e32 v105, v2
	v_mov_b32_e32 v104, v88
	v_pk_mul_f32 v[98:99], v[104:105], v[98:99]
	s_nop 0
	v_mul_f32_e32 v2, v98, v99
	v_and_b32_e32 v99, 0xffff0000, v116
	v_mul_f32_e32 v88, 0xbfb8aa3b, v99
	v_exp_f32_e32 v88, v88
	v_mov_b32_e32 v104, v89
	v_mov_b32_e32 v98, v101
	v_add_f32_e32 v88, 1.0, v88
	v_rcp_f32_e32 v105, v88
	s_nop 0
	v_pk_mul_f32 v[88:89], v[104:105], v[98:99]
	s_nop 0
	v_mul_f32_e32 v88, v88, v89
	v_lshlrev_b32_e32 v99, 16, v117
	v_cvt_pk_bf16_f32 v88, v2, v88
	v_mul_f32_e32 v2, 0xbfb8aa3b, v99
	v_exp_f32_e32 v2, v2
	v_mov_b32_e32 v104, v90
	v_mov_b32_e32 v98, v102
	v_add_f32_e32 v2, 1.0, v2
	v_rcp_f32_e32 v105, v2
	s_nop 0
	v_pk_mul_f32 v[98:99], v[104:105], v[98:99]
	s_nop 0
	v_mul_f32_e32 v2, v98, v99
	v_and_b32_e32 v99, 0xffff0000, v117
	v_mul_f32_e32 v89, 0xbfb8aa3b, v99
	v_exp_f32_e32 v89, v89
	v_mov_b32_e32 v104, v91
	v_mov_b32_e32 v98, v103
	v_add_f32_e32 v89, 1.0, v89
	v_rcp_f32_e32 v105, v89
	s_nop 0
	v_pk_mul_f32 v[90:91], v[104:105], v[98:99]
; __device__ __forceinline__ size_t pidx(size_t row, int col) { return ((size_t)(col >> 8) * MTOK + row) * PLD + (col & 255); }
; __device__ __forceinline__ float bflo(unsigned v) { return __uint_as_float(v << 16); }
; __device__ __forceinline__ float bfhi(unsigned v) { return __uint_as_float(v & 0xffff0000u); }
; __device__ __forceinline__ float siluf_(float x) { return x * __builtin_amdgcn_rcpf(1.0f + __expf(-x)); }
;   __device__ __forceinline__ void operator()(EPI_ARGS) const {
;     ...
;         for (int m = 0; m < 4; ++m) z[m] = *(const u32x4*)(proj + pidx(row0 + ai * HALF + m * 16, PZ + c));
;         __builtin_amdgcn_sched_barrier(0);
; #pragma unroll
;         for (int m = 0; m < 4; ++m) {
;           const size_t row = row0 + ai * HALF + m * 16;
;           const f32x4 v0 = acc[ai][bj][m][0], v1 = acc[ai][bj][m][1];
;           u32x4 o;
;           o.x = pack2(v0[0] * s0[0] * siluf_(bflo(z[m].x)), v0[1] * s0[1] * siluf_(bfhi(z[m].x)));
;           o.y = pack2(v0[2] * s0[2] * siluf_(bflo(z[m].y)), v0[3] * s0[3] * siluf_(bfhi(z[m].y)));
;           o.z = pack2(v1[0] * s1[0] * siluf_(bflo(z[m].z)), v1[1] * s1[1] * siluf_(bfhi(z[m].z)));
;           o.w = pack2(v1[2] * s1[2] * siluf_(bflo(z[m].w)), v1[3] * s1[3] * siluf_(bfhi(z[m].w)));
;           *(u32x4*)(y0 + row * DM + c) = o;
	s_nop 0
	v_mul_f32_e32 v89, v90, v91
	v_lshlrev_b32_e32 v91, 16, v118
	v_cvt_pk_bf16_f32 v89, v2, v89
	v_mul_f32_e32 v2, 0xbfb8aa3b, v91
	v_exp_f32_e32 v2, v2
	v_mov_b32_e32 v98, v84
	v_mov_b32_e32 v90, v92
	v_add_f32_e32 v2, 1.0, v2
	v_rcp_f32_e32 v99, v2
	s_nop 0
	v_pk_mul_f32 v[90:91], v[98:99], v[90:91]
	s_nop 0
	v_mul_f32_e32 v2, v90, v91
	v_and_b32_e32 v91, 0xffff0000, v118
	v_mul_f32_e32 v84, 0xbfb8aa3b, v91
	v_exp_f32_e32 v84, v84
	v_mov_b32_e32 v98, v85
	v_mov_b32_e32 v90, v93
	v_add_f32_e32 v84, 1.0, v84
	v_rcp_f32_e32 v99, v84
	s_nop 0
	v_pk_mul_f32 v[84:85], v[98:99], v[90:91]
	s_nop 0
	v_mul_f32_e32 v84, v84, v85
	v_lshlrev_b32_e32 v85, 16, v119
	v_cvt_pk_bf16_f32 v90, v2, v84
	v_mul_f32_e32 v2, 0xbfb8aa3b, v85
	v_exp_f32_e32 v2, v2
	v_mov_b32_e32 v98, v86
	v_mov_b32_e32 v84, v94
	v_mov_b32_e32 v86, v80
	v_add_f32_e32 v2, 1.0, v2
	v_rcp_f32_e32 v99, v2
	s_nop 0
	v_pk_mul_f32 v[84:85], v[98:99], v[84:85]
	s_nop 0
	v_mul_f32_e32 v2, v84, v85
	v_and_b32_e32 v85, 0xffff0000, v119
	v_mul_f32_e32 v84, 0xbfb8aa3b, v85
	v_exp_f32_e32 v84, v84
	v_mov_b32_e32 v98, v87
	v_add_f32_e32 v84, 1.0, v84
	v_rcp_f32_e32 v99, v84
	v_mov_b32_e32 v84, v95
	v_pk_mul_f32 v[84:85], v[98:99], v[84:85]
	s_nop 0
	v_mul_f32_e32 v84, v84, v85
	v_cvt_pk_bf16_f32 v91, v2, v84
	v_lshlrev_b64 v[84:85], 12, v[146:147]
	v_lshl_add_u64 v[84:85], s[8:9], 0, v[84:85]
	v_lshl_add_u64 v[98:99], v[84:85], 0, v[140:141]
	v_lshlrev_b32_e32 v85, 16, v112
	v_mul_f32_e32 v2, 0xbfb8aa3b, v85
	v_exp_f32_e32 v2, v2
	v_mov_b32_e32 v84, v100
	flat_store_dwordx4 v[98:99], v[88:91]
	v_add_f32_e32 v2, 1.0, v2
	v_rcp_f32_e32 v87, v2
	s_nop 0
	v_pk_mul_f32 v[84:85], v[86:87], v[84:85]
	s_nop 0
	v_mul_f32_e32 v2, v84, v85
	v_and_b32_e32 v85, 0xffff0000, v112
	v_mul_f32_e32 v80, 0xbfb8aa3b, v85
	v_exp_f32_e32 v80, v80
	v_mov_b32_e32 v86, v81
	v_mov_b32_e32 v84, v101
	v_add_f32_e32 v80, 1.0, v80
	v_rcp_f32_e32 v87, v80
	s_nop 0
	v_pk_mul_f32 v[80:81], v[86:87], v[84:85]
	s_nop 0
	v_mul_f32_e32 v80, v80, v81
	v_lshlrev_b32_e32 v85, 16, v113
	v_cvt_pk_bf16_f32 v80, v2, v80
	v_mul_f32_e32 v2, 0xbfb8aa3b, v85
	v_exp_f32_e32 v2, v2
	v_mov_b32_e32 v86, v82
	v_mov_b32_e32 v84, v102
	v_add_f32_e32 v2, 1.0, v2
	v_rcp_f32_e32 v87, v2
	s_nop 0
	v_pk_mul_f32 v[84:85], v[86:87], v[84:85]
	s_nop 0
	v_mul_f32_e32 v2, v84, v85
	v_and_b32_e32 v85, 0xffff0000, v113
	v_mul_f32_e32 v81, 0xbfb8aa3b, v85
	v_exp_f32_e32 v81, v81
	v_mov_b32_e32 v86, v83
	v_mov_b32_e32 v84, v103
	v_add_f32_e32 v81, 1.0, v81
	v_rcp_f32_e32 v87, v81
	s_nop 0
	v_pk_mul_f32 v[82:83], v[86:87], v[84:85]
	s_nop 0
	v_mul_f32_e32 v81, v82, v83
	v_lshlrev_b32_e32 v83, 16, v114
	v_cvt_pk_bf16_f32 v81, v2, v81
	v_mul_f32_e32 v2, 0xbfb8aa3b, v83
	v_exp_f32_e32 v2, v2
	v_mov_b32_e32 v84, v76
	v_mov_b32_e32 v82, v92
	v_add_f32_e32 v2, 1.0, v2
	v_rcp_f32_e32 v85, v2
	s_nop 0
	v_pk_mul_f32 v[82:83], v[84:85], v[82:83]
	s_nop 0
	v_mul_f32_e32 v2, v82, v83
	v_and_b32_e32 v83, 0xffff0000, v114
	v_mul_f32_e32 v76, 0xbfb8aa3b, v83
	v_exp_f32_e32 v76, v76
	v_mov_b32_e32 v84, v77
	v_mov_b32_e32 v82, v93
	v_add_f32_e32 v76, 1.0, v76
	v_rcp_f32_e32 v85, v76
	s_nop 0
	v_pk_mul_f32 v[76:77], v[84:85], v[82:83]
	s_nop 0
	v_mul_f32_e32 v76, v76, v77
	v_lshlrev_b32_e32 v77, 16, v115
	v_cvt_pk_bf16_f32 v82, v2, v76
	v_mul_f32_e32 v2, 0xbfb8aa3b, v77
	v_exp_f32_e32 v2, v2
	v_mov_b32_e32 v84, v78
	v_mov_b32_e32 v76, v94
	v_mov_b32_e32 v78, v72
	v_add_f32_e32 v2, 1.0, v2
	v_rcp_f32_e32 v85, v2
	s_nop 0
	v_pk_mul_f32 v[76:77], v[84:85], v[76:77]
	s_nop 0
	v_mul_f32_e32 v2, v76, v77
	v_and_b32_e32 v77, 0xffff0000, v115
	v_mul_f32_e32 v76, 0xbfb8aa3b, v77
	v_exp_f32_e32 v76, v76
	v_mov_b32_e32 v84, v79
	v_add_f32_e32 v76, 1.0, v76
	v_rcp_f32_e32 v85, v76
	v_mov_b32_e32 v76, v95
	v_pk_mul_f32 v[76:77], v[84:85], v[76:77]
	s_nop 0
	v_mul_f32_e32 v76, v76, v77
	v_cvt_pk_bf16_f32 v83, v2, v76
	v_lshlrev_b64 v[76:77], 12, v[144:145]
	v_lshl_add_u64 v[76:77], s[8:9], 0, v[76:77]
	v_lshl_add_u64 v[104:105], v[76:77], 0, v[140:141]
	v_lshlrev_b32_e32 v77, 16, v108
	v_mul_f32_e32 v2, 0xbfb8aa3b, v77
	v_exp_f32_e32 v2, v2
	v_mov_b32_e32 v76, v100
	flat_store_dwordx4 v[104:105], v[80:83]
	v_add_f32_e32 v2, 1.0, v2
	v_rcp_f32_e32 v79, v2
	s_nop 0
	v_pk_mul_f32 v[76:77], v[78:79], v[76:77]
	s_nop 0
	v_mul_f32_e32 v2, v76, v77
	v_and_b32_e32 v77, 0xffff0000, v108
	v_mul_f32_e32 v72, 0xbfb8aa3b, v77
	v_exp_f32_e32 v72, v72
	v_mov_b32_e32 v78, v73
	v_mov_b32_e32 v76, v101
	v_add_f32_e32 v72, 1.0, v72
	v_rcp_f32_e32 v79, v72
	s_nop 0
	v_pk_mul_f32 v[72:73], v[78:79], v[76:77]
	s_nop 0
	v_mul_f32_e32 v72, v72, v73
	v_lshlrev_b32_e32 v77, 16, v109
	v_cvt_pk_bf16_f32 v72, v2, v72
	v_mul_f32_e32 v2, 0xbfb8aa3b, v77
	v_exp_f32_e32 v2, v2
	v_mov_b32_e32 v78, v74
	v_mov_b32_e32 v76, v102
	v_add_f32_e32 v2, 1.0, v2
	v_rcp_f32_e32 v79, v2
	s_nop 0
	v_pk_mul_f32 v[76:77], v[78:79], v[76:77]
	s_nop 0
	v_mul_f32_e32 v2, v76, v77
	v_and_b32_e32 v77, 0xffff0000, v109
	v_mul_f32_e32 v73, 0xbfb8aa3b, v77
	v_exp_f32_e32 v73, v73
	v_mov_b32_e32 v78, v75
	v_mov_b32_e32 v76, v103
	v_add_f32_e32 v73, 1.0, v73
	v_rcp_f32_e32 v79, v73
	s_nop 0
	v_pk_mul_f32 v[74:75], v[78:79], v[76:77]
	s_nop 0
	v_mul_f32_e32 v73, v74, v75
	v_lshlrev_b32_e32 v75, 16, v110
	v_cvt_pk_bf16_f32 v73, v2, v73
	v_mul_f32_e32 v2, 0xbfb8aa3b, v75
	v_exp_f32_e32 v2, v2
	v_mov_b32_e32 v76, v68
	v_mov_b32_e32 v74, v92
	v_add_f32_e32 v2, 1.0, v2
	v_rcp_f32_e32 v77, v2
	s_nop 0
	v_pk_mul_f32 v[74:75], v[76:77], v[74:75]
	s_nop 0
	v_mul_f32_e32 v2, v74, v75
	v_and_b32_e32 v75, 0xffff0000, v110
	v_mul_f32_e32 v68, 0xbfb8aa3b, v75
	v_exp_f32_e32 v68, v68
	v_mov_b32_e32 v76, v69
	v_mov_b32_e32 v74, v93
	v_add_f32_e32 v68, 1.0, v68
; __device__ __forceinline__ size_t pidx(size_t row, int col) { return ((size_t)(col >> 8) * MTOK + row) * PLD + (col & 255); }
; __device__ __forceinline__ float bflo(unsigned v) { return __uint_as_float(v << 16); }
; __device__ __forceinline__ float bfhi(unsigned v) { return __uint_as_float(v & 0xffff0000u); }
; __device__ __forceinline__ float siluf_(float x) { return x * __builtin_amdgcn_rcpf(1.0f + __expf(-x)); }
;   __device__ __forceinline__ void operator()(EPI_ARGS) const {
;     ...
;       const f32x4 s0 = *(const f32x4*)(psc + c), s1 = *(const f32x4*)(psc + c + 4);
; #pragma unroll
;       for (int ai = 0; ai < 2; ++ai) {
;         u32x4 z[4];
; #pragma unroll
;         for (int m = 0; m < 4; ++m) z[m] = *(const u32x4*)(proj + pidx(row0 + ai * HALF + m * 16, PZ + c));
;         __builtin_amdgcn_sched_barrier(0);
; #pragma unroll
;         for (int m = 0; m < 4; ++m) {
;           const size_t row = row0 + ai * HALF + m * 16;
;           const f32x4 v0 = acc[ai][bj][m][0], v1 = acc[ai][bj][m][1];
;           u32x4 o;
;           o.x = pack2(v0[0] * s0[0] * siluf_(bflo(z[m].x)), v0[1] * s0[1] * siluf_(bfhi(z[m].x)));
;           o.y = pack2(v0[2] * s0[2] * siluf_(bflo(z[m].y)), v0[3] * s0[3] * siluf_(bfhi(z[m].y)));
;           o.z = pack2(v1[0] * s1[0] * siluf_(bflo(z[m].z)), v1[1] * s1[1] * siluf_(bfhi(z[m].z)));
;           o.w = pack2(v1[2] * s1[2] * siluf_(bflo(z[m].w)), v1[3] * s1[3] * siluf_(bfhi(z[m].w)));
;           *(u32x4*)(y0 + row * DM + c) = o;
	v_rcp_f32_e32 v77, v68
	s_nop 0
	v_pk_mul_f32 v[68:69], v[76:77], v[74:75]
	s_nop 0
	v_mul_f32_e32 v68, v68, v69
	v_lshlrev_b32_e32 v69, 16, v111
	v_cvt_pk_bf16_f32 v74, v2, v68
	v_mul_f32_e32 v2, 0xbfb8aa3b, v69
	v_exp_f32_e32 v2, v2
	v_mov_b32_e32 v76, v70
	v_mov_b32_e32 v68, v94
	v_add_f32_e32 v2, 1.0, v2
	v_rcp_f32_e32 v77, v2
	s_nop 0
	v_pk_mul_f32 v[68:69], v[76:77], v[68:69]
	s_nop 0
	v_mul_f32_e32 v2, v68, v69
	v_and_b32_e32 v69, 0xffff0000, v111
	v_mul_f32_e32 v68, 0xbfb8aa3b, v69
	v_exp_f32_e32 v68, v68
	v_mov_b32_e32 v76, v71
	v_add_f32_e32 v68, 1.0, v68
	v_rcp_f32_e32 v77, v68
	v_mov_b32_e32 v68, v95
	v_lshl_add_u64 v[94:95], s[2:3], 0, v[174:175]
	v_pk_mul_f32 v[68:69], v[76:77], v[68:69]
	s_nop 0
	v_mul_f32_e32 v68, v68, v69
	v_cvt_pk_bf16_f32 v75, v2, v68
	v_lshlrev_b64 v[68:69], 12, v[142:143]
	v_lshl_add_u64 v[68:69], s[8:9], 0, v[68:69]
	v_lshl_add_u64 v[92:93], v[68:69], 0, v[140:141]
	flat_store_dwordx4 v[92:93], v[72:75]
	v_lshl_add_u64 v[76:77], v[94:95], 0, v[178:179]
	global_load_dwordx4 v[68:71], v[176:177], off offset:528
	global_load_dwordx4 v[72:75], v[176:177], off offset:512
	flat_load_dwordx4 v[88:91], v[76:77]
	v_lshl_add_u64 v[76:77], v[94:95], 0, v[180:181]
	flat_load_dwordx4 v[84:87], v[76:77]
	v_lshl_add_u64 v[76:77], v[94:95], 0, v[182:183]
	flat_load_dwordx4 v[80:83], v[76:77]
	v_lshl_add_u64 v[76:77], v[94:95], 0, v[184:185]
	flat_load_dwordx4 v[76:79], v[76:77]
	s_waitcnt vmcnt(0) lgkmcnt(0)
	v_lshlrev_b32_e32 v101, 16, v88
	v_mul_f32_e32 v2, 0xbfb8aa3b, v101
	v_exp_f32_e32 v2, v2
	v_mov_b32_e32 v102, v64
	v_mov_b32_e32 v100, v72
	v_add_f32_e32 v2, 1.0, v2
	v_rcp_f32_e32 v103, v2
	s_nop 0
	v_pk_mul_f32 v[100:101], v[102:103], v[100:101]
	s_nop 0
	v_mul_f32_e32 v2, v100, v101
	v_and_b32_e32 v101, 0xffff0000, v88
	v_mul_f32_e32 v64, 0xbfb8aa3b, v101
	v_exp_f32_e32 v64, v64
	v_mov_b32_e32 v102, v65
	v_mov_b32_e32 v100, v73
	v_mov_b32_e32 v88, v75
	v_add_f32_e32 v64, 1.0, v64
	v_rcp_f32_e32 v103, v64
	s_nop 0
	v_pk_mul_f32 v[64:65], v[102:103], v[100:101]
	s_nop 0
	v_mul_f32_e32 v64, v64, v65
	v_lshlrev_b32_e32 v101, 16, v89
	v_cvt_pk_bf16_f32 v64, v2, v64
	v_mul_f32_e32 v2, 0xbfb8aa3b, v101
	v_exp_f32_e32 v2, v2
	v_and_b32_e32 v89, 0xffff0000, v89
	v_mul_f32_e32 v65, 0xbfb8aa3b, v89
	v_exp_f32_e32 v65, v65
	v_add_f32_e32 v2, 1.0, v2
	v_rcp_f32_e32 v103, v2
	v_mov_b32_e32 v102, v66
	v_mov_b32_e32 v100, v74
	v_add_f32_e32 v65, 1.0, v65
	v_pk_mul_f32 v[100:101], v[102:103], v[100:101]
	s_nop 0
	v_mul_f32_e32 v2, v100, v101
	v_rcp_f32_e32 v101, v65
	v_mov_b32_e32 v100, v67
	v_pk_mul_f32 v[66:67], v[100:101], v[88:89]
	s_nop 0
	v_mul_f32_e32 v65, v66, v67
	v_lshlrev_b32_e32 v67, 16, v90
	v_cvt_pk_bf16_f32 v65, v2, v65
	v_mul_f32_e32 v2, 0xbfb8aa3b, v67
	v_exp_f32_e32 v2, v2
	v_mov_b32_e32 v88, v60
	v_mov_b32_e32 v66, v68
	v_add_f32_e32 v2, 1.0, v2
	v_rcp_f32_e32 v89, v2
	s_nop 0
	v_pk_mul_f32 v[66:67], v[88:89], v[66:67]
	s_nop 0
	v_mul_f32_e32 v2, v66, v67
	v_and_b32_e32 v67, 0xffff0000, v90
	v_mul_f32_e32 v60, 0xbfb8aa3b, v67
	v_exp_f32_e32 v60, v60
	v_mov_b32_e32 v88, v61
	v_mov_b32_e32 v66, v69
	v_add_f32_e32 v60, 1.0, v60
	v_rcp_f32_e32 v89, v60
	s_nop 0
	v_pk_mul_f32 v[60:61], v[88:89], v[66:67]
	s_nop 0
	v_mul_f32_e32 v60, v60, v61
	v_lshlrev_b32_e32 v61, 16, v91
	v_cvt_pk_bf16_f32 v66, v2, v60
	v_mul_f32_e32 v2, 0xbfb8aa3b, v61
	v_exp_f32_e32 v2, v2
	v_mov_b32_e32 v88, v62
	v_mov_b32_e32 v60, v70
	v_mov_b32_e32 v62, v56
	v_add_f32_e32 v2, 1.0, v2
	v_rcp_f32_e32 v89, v2
	s_nop 0
	v_pk_mul_f32 v[60:61], v[88:89], v[60:61]
	s_nop 0
	v_mul_f32_e32 v2, v60, v61
	v_and_b32_e32 v61, 0xffff0000, v91
	v_mul_f32_e32 v60, 0xbfb8aa3b, v61
	v_exp_f32_e32 v60, v60
	v_mov_b32_e32 v88, v63
	v_add_f32_e32 v60, 1.0, v60
	v_rcp_f32_e32 v89, v60
	v_mov_b32_e32 v60, v71
	v_pk_mul_f32 v[60:61], v[88:89], v[60:61]
	s_nop 0
	v_mul_f32_e32 v60, v60, v61
	v_lshlrev_b32_e32 v61, 16, v84
	v_cvt_pk_bf16_f32 v67, v2, v60
	v_mul_f32_e32 v2, 0xbfb8aa3b, v61
	v_exp_f32_e32 v2, v2
	v_mov_b32_e32 v60, v72
	flat_store_dwordx4 v[136:137], v[64:67] offset:256
	v_add_f32_e32 v2, 1.0, v2
	v_rcp_f32_e32 v63, v2
	s_nop 0
	v_pk_mul_f32 v[60:61], v[62:63], v[60:61]
	s_nop 0
	v_mul_f32_e32 v2, v60, v61
	v_and_b32_e32 v61, 0xffff0000, v84
	v_mul_f32_e32 v56, 0xbfb8aa3b, v61
	v_exp_f32_e32 v56, v56
	v_mov_b32_e32 v62, v57
	v_mov_b32_e32 v60, v73
	v_add_f32_e32 v56, 1.0, v56
	v_rcp_f32_e32 v63, v56
	s_nop 0
	v_pk_mul_f32 v[56:57], v[62:63], v[60:61]
	s_nop 0
	v_mul_f32_e32 v56, v56, v57
	v_lshlrev_b32_e32 v61, 16, v85
	v_cvt_pk_bf16_f32 v56, v2, v56
	v_mul_f32_e32 v2, 0xbfb8aa3b, v61
	v_exp_f32_e32 v2, v2
	v_mov_b32_e32 v62, v58
	v_mov_b32_e32 v60, v74
	v_add_f32_e32 v2, 1.0, v2
	v_rcp_f32_e32 v63, v2
	s_nop 0
	v_pk_mul_f32 v[60:61], v[62:63], v[60:61]
	s_nop 0
	v_mul_f32_e32 v2, v60, v61
	v_and_b32_e32 v61, 0xffff0000, v85
	v_mul_f32_e32 v57, 0xbfb8aa3b, v61
	v_exp_f32_e32 v57, v57
	v_mov_b32_e32 v62, v59
	v_mov_b32_e32 v60, v75
	v_add_f32_e32 v57, 1.0, v57
	v_rcp_f32_e32 v63, v57
	s_nop 0
	v_pk_mul_f32 v[58:59], v[62:63], v[60:61]
	s_nop 0
	v_mul_f32_e32 v57, v58, v59
	v_lshlrev_b32_e32 v59, 16, v86
	v_cvt_pk_bf16_f32 v57, v2, v57
	v_mul_f32_e32 v2, 0xbfb8aa3b, v59
	v_exp_f32_e32 v2, v2
	v_mov_b32_e32 v60, v52
	v_mov_b32_e32 v58, v68
	v_add_f32_e32 v2, 1.0, v2
	v_rcp_f32_e32 v61, v2
	s_nop 0
	v_pk_mul_f32 v[58:59], v[60:61], v[58:59]
	s_nop 0
	v_mul_f32_e32 v2, v58, v59
	v_and_b32_e32 v59, 0xffff0000, v86
	v_mul_f32_e32 v52, 0xbfb8aa3b, v59
	v_exp_f32_e32 v52, v52
	v_mov_b32_e32 v60, v53
	v_mov_b32_e32 v58, v69
	v_add_f32_e32 v52, 1.0, v52
	v_rcp_f32_e32 v61, v52
	s_nop 0
	v_pk_mul_f32 v[52:53], v[60:61], v[58:59]
	s_nop 0
	v_mul_f32_e32 v52, v52, v53
; __device__ __forceinline__ size_t pidx(size_t row, int col) { return ((size_t)(col >> 8) * MTOK + row) * PLD + (col & 255); }
; __device__ __forceinline__ float bflo(unsigned v) { return __uint_as_float(v << 16); }
; __device__ __forceinline__ float bfhi(unsigned v) { return __uint_as_float(v & 0xffff0000u); }
; __device__ __forceinline__ float siluf_(float x) { return x * __builtin_amdgcn_rcpf(1.0f + __expf(-x)); }
;   __device__ __forceinline__ void operator()(EPI_ARGS) const {
;     ...
;         for (int m = 0; m < 4; ++m) z[m] = *(const u32x4*)(proj + pidx(row0 + ai * HALF + m * 16, PZ + c));
;         __builtin_amdgcn_sched_barrier(0);
; #pragma unroll
;         for (int m = 0; m < 4; ++m) {
;           const size_t row = row0 + ai * HALF + m * 16;
;           const f32x4 v0 = acc[ai][bj][m][0], v1 = acc[ai][bj][m][1];
;           u32x4 o;
;           o.x = pack2(v0[0] * s0[0] * siluf_(bflo(z[m].x)), v0[1] * s0[1] * siluf_(bfhi(z[m].x)));
;           o.y = pack2(v0[2] * s0[2] * siluf_(bflo(z[m].y)), v0[3] * s0[3] * siluf_(bfhi(z[m].y)));
;           o.z = pack2(v1[0] * s1[0] * siluf_(bflo(z[m].z)), v1[1] * s1[1] * siluf_(bfhi(z[m].z)));
;           o.w = pack2(v1[2] * s1[2] * siluf_(bflo(z[m].w)), v1[3] * s1[3] * siluf_(bfhi(z[m].w)));
;           *(u32x4*)(y0 + row * DM + c) = o;
	v_lshlrev_b32_e32 v53, 16, v87
	v_cvt_pk_bf16_f32 v58, v2, v52
	v_mul_f32_e32 v2, 0xbfb8aa3b, v53
	v_exp_f32_e32 v2, v2
	v_mov_b32_e32 v60, v54
	v_mov_b32_e32 v52, v70
	v_mov_b32_e32 v54, v48
	v_add_f32_e32 v2, 1.0, v2
	v_rcp_f32_e32 v61, v2
	s_nop 0
	v_pk_mul_f32 v[52:53], v[60:61], v[52:53]
	s_nop 0
	v_mul_f32_e32 v2, v52, v53
	v_and_b32_e32 v53, 0xffff0000, v87
	v_mul_f32_e32 v52, 0xbfb8aa3b, v53
	v_exp_f32_e32 v52, v52
	v_mov_b32_e32 v60, v55
	v_add_f32_e32 v52, 1.0, v52
	v_rcp_f32_e32 v61, v52
	v_mov_b32_e32 v52, v71
	v_pk_mul_f32 v[52:53], v[60:61], v[52:53]
	s_nop 0
	v_mul_f32_e32 v52, v52, v53
	v_lshlrev_b32_e32 v53, 16, v80
	v_cvt_pk_bf16_f32 v59, v2, v52
	v_mul_f32_e32 v2, 0xbfb8aa3b, v53
	v_exp_f32_e32 v2, v2
	v_mov_b32_e32 v52, v72
	flat_store_dwordx4 v[124:125], v[56:59] offset:256
	v_add_f32_e32 v2, 1.0, v2
	v_rcp_f32_e32 v55, v2
	s_nop 0
	v_pk_mul_f32 v[52:53], v[54:55], v[52:53]
	s_nop 0
	v_mul_f32_e32 v2, v52, v53
	v_and_b32_e32 v53, 0xffff0000, v80
	v_mul_f32_e32 v48, 0xbfb8aa3b, v53
	v_exp_f32_e32 v48, v48
	v_mov_b32_e32 v54, v49
	v_mov_b32_e32 v52, v73
	v_add_f32_e32 v48, 1.0, v48
	v_rcp_f32_e32 v55, v48
	s_nop 0
	v_pk_mul_f32 v[48:49], v[54:55], v[52:53]
	s_nop 0
	v_mul_f32_e32 v48, v48, v49
	v_lshlrev_b32_e32 v53, 16, v81
	v_cvt_pk_bf16_f32 v48, v2, v48
	v_mul_f32_e32 v2, 0xbfb8aa3b, v53
	v_exp_f32_e32 v2, v2
	v_mov_b32_e32 v54, v50
	v_mov_b32_e32 v52, v74
	v_add_f32_e32 v2, 1.0, v2
	v_rcp_f32_e32 v55, v2
	s_nop 0
	v_pk_mul_f32 v[52:53], v[54:55], v[52:53]
	s_nop 0
	v_mul_f32_e32 v2, v52, v53
	v_and_b32_e32 v53, 0xffff0000, v81
	v_mul_f32_e32 v49, 0xbfb8aa3b, v53
	v_exp_f32_e32 v49, v49
	v_mov_b32_e32 v54, v51
	v_mov_b32_e32 v52, v75
	v_add_f32_e32 v49, 1.0, v49
	v_rcp_f32_e32 v55, v49
	s_nop 0
	v_pk_mul_f32 v[50:51], v[54:55], v[52:53]
	s_nop 0
	v_mul_f32_e32 v49, v50, v51
	v_lshlrev_b32_e32 v51, 16, v82
	v_cvt_pk_bf16_f32 v49, v2, v49
	v_mul_f32_e32 v2, 0xbfb8aa3b, v51
	v_exp_f32_e32 v2, v2
	v_mov_b32_e32 v52, v44
	v_mov_b32_e32 v50, v68
	v_add_f32_e32 v2, 1.0, v2
	v_rcp_f32_e32 v53, v2
	s_nop 0
	v_pk_mul_f32 v[50:51], v[52:53], v[50:51]
	s_nop 0
	v_mul_f32_e32 v2, v50, v51
	v_and_b32_e32 v51, 0xffff0000, v82
	v_mul_f32_e32 v44, 0xbfb8aa3b, v51
	v_exp_f32_e32 v44, v44
	v_mov_b32_e32 v52, v45
	v_mov_b32_e32 v50, v69
	v_add_f32_e32 v44, 1.0, v44
	v_rcp_f32_e32 v53, v44
	s_nop 0
	v_pk_mul_f32 v[44:45], v[52:53], v[50:51]
	s_nop 0
	v_mul_f32_e32 v44, v44, v45
	v_lshlrev_b32_e32 v45, 16, v83
	v_cvt_pk_bf16_f32 v50, v2, v44
	v_mul_f32_e32 v2, 0xbfb8aa3b, v45
	v_exp_f32_e32 v2, v2
	v_mov_b32_e32 v52, v46
	v_mov_b32_e32 v44, v70
	v_mov_b32_e32 v46, v40
	v_add_f32_e32 v2, 1.0, v2
	v_rcp_f32_e32 v53, v2
	s_nop 0
	v_pk_mul_f32 v[44:45], v[52:53], v[44:45]
	s_nop 0
	v_mul_f32_e32 v2, v44, v45
	v_and_b32_e32 v45, 0xffff0000, v83
	v_mul_f32_e32 v44, 0xbfb8aa3b, v45
	v_exp_f32_e32 v44, v44
	v_mov_b32_e32 v52, v47
	v_add_f32_e32 v44, 1.0, v44
	v_rcp_f32_e32 v53, v44
	v_mov_b32_e32 v44, v71
	v_pk_mul_f32 v[44:45], v[52:53], v[44:45]
	s_nop 0
	v_mul_f32_e32 v44, v44, v45
	v_lshlrev_b32_e32 v45, 16, v76
	v_cvt_pk_bf16_f32 v51, v2, v44
	v_mul_f32_e32 v2, 0xbfb8aa3b, v45
	v_exp_f32_e32 v2, v2
	v_mov_b32_e32 v44, v72
	flat_store_dwordx4 v[128:129], v[48:51] offset:256
	v_add_f32_e32 v2, 1.0, v2
	v_rcp_f32_e32 v47, v2
	s_nop 0
	v_pk_mul_f32 v[44:45], v[46:47], v[44:45]
	s_nop 0
	v_mul_f32_e32 v2, v44, v45
	v_and_b32_e32 v45, 0xffff0000, v76
	v_mul_f32_e32 v40, 0xbfb8aa3b, v45
	v_exp_f32_e32 v40, v40
	v_mov_b32_e32 v46, v41
	v_mov_b32_e32 v44, v73
	v_add_f32_e32 v40, 1.0, v40
	v_rcp_f32_e32 v47, v40
	s_nop 0
	v_pk_mul_f32 v[40:41], v[46:47], v[44:45]
	s_nop 0
	v_mul_f32_e32 v40, v40, v41
	v_lshlrev_b32_e32 v45, 16, v77
	v_cvt_pk_bf16_f32 v40, v2, v40
	v_mul_f32_e32 v2, 0xbfb8aa3b, v45
	v_exp_f32_e32 v2, v2
	v_mov_b32_e32 v46, v42
	v_mov_b32_e32 v44, v74
	v_add_f32_e32 v2, 1.0, v2
	v_rcp_f32_e32 v47, v2
	s_nop 0
	v_pk_mul_f32 v[44:45], v[46:47], v[44:45]
	s_nop 0
	v_mul_f32_e32 v2, v44, v45
	v_and_b32_e32 v45, 0xffff0000, v77
	v_mul_f32_e32 v41, 0xbfb8aa3b, v45
	v_exp_f32_e32 v41, v41
	v_mov_b32_e32 v46, v43
	v_mov_b32_e32 v44, v75
	v_add_f32_e32 v41, 1.0, v41
	v_rcp_f32_e32 v47, v41
	s_nop 0
	v_pk_mul_f32 v[42:43], v[46:47], v[44:45]
	s_nop 0
	v_mul_f32_e32 v41, v42, v43
	v_lshlrev_b32_e32 v43, 16, v78
	v_cvt_pk_bf16_f32 v41, v2, v41
	v_mul_f32_e32 v2, 0xbfb8aa3b, v43
	v_exp_f32_e32 v2, v2
	v_mov_b32_e32 v44, v36
	v_mov_b32_e32 v42, v68
	v_add_f32_e32 v2, 1.0, v2
	v_rcp_f32_e32 v45, v2
	s_nop 0
	v_pk_mul_f32 v[42:43], v[44:45], v[42:43]
	s_nop 0
	v_mul_f32_e32 v2, v42, v43
	v_and_b32_e32 v43, 0xffff0000, v78
	v_mul_f32_e32 v36, 0xbfb8aa3b, v43
	v_exp_f32_e32 v36, v36
	v_mov_b32_e32 v44, v37
	v_mov_b32_e32 v42, v69
	v_add_f32_e32 v36, 1.0, v36
	v_rcp_f32_e32 v45, v36
	s_nop 0
	v_pk_mul_f32 v[36:37], v[44:45], v[42:43]
	s_nop 0
	v_mul_f32_e32 v36, v36, v37
	v_lshlrev_b32_e32 v37, 16, v79
	v_cvt_pk_bf16_f32 v42, v2, v36
	v_mul_f32_e32 v2, 0xbfb8aa3b, v37
	v_exp_f32_e32 v2, v2
	v_mov_b32_e32 v44, v38
	v_mov_b32_e32 v36, v70
	v_add_f32_e32 v2, 1.0, v2
	v_rcp_f32_e32 v45, v2
	s_nop 0
	v_pk_mul_f32 v[36:37], v[44:45], v[36:37]
	s_nop 0
	v_mul_f32_e32 v2, v36, v37
	v_and_b32_e32 v37, 0xffff0000, v79
	v_mul_f32_e32 v36, 0xbfb8aa3b, v37
	v_exp_f32_e32 v36, v36
	v_mov_b32_e32 v44, v39
	v_add_f32_e32 v36, 1.0, v36
	v_rcp_f32_e32 v45, v36
	v_mov_b32_e32 v36, v71
	v_pk_mul_f32 v[36:37], v[44:45], v[36:37]
	s_nop 0
	v_mul_f32_e32 v36, v36, v37
	v_cvt_pk_bf16_f32 v43, v2, v36
	flat_store_dwordx4 v[126:127], v[40:43] offset:256
	v_lshl_add_u64 v[36:37], v[94:95], 0, v[130:131]
	flat_load_dwordx4 v[48:51], v[36:37]
	v_lshl_add_u64 v[36:37], v[94:95], 0, v[132:133]
	flat_load_dwordx4 v[44:47], v[36:37]
	v_lshl_add_u64 v[36:37], v[94:95], 0, v[134:135]
	flat_load_dwordx4 v[40:43], v[36:37]
	v_lshl_add_u64 v[36:37], v[94:95], 0, v[138:139]
	flat_load_dwordx4 v[36:39], v[36:37]
	s_waitcnt vmcnt(0) lgkmcnt(0)
; __device__ __forceinline__ size_t pidx(size_t row, int col) { return ((size_t)(col >> 8) * MTOK + row) * PLD + (col & 255); }
; __device__ __forceinline__ float bflo(unsigned v) { return __uint_as_float(v << 16); }
; __device__ __forceinline__ float bfhi(unsigned v) { return __uint_as_float(v & 0xffff0000u); }
; __device__ __forceinline__ float siluf_(float x) { return x * __builtin_amdgcn_rcpf(1.0f + __expf(-x)); }
; template <class Epi, class AddrA, class AddrB>
; __device__ __forceinline__ void gemm_phase(const Sched S, const int lda, const int ldb, const int K, const AddrA addrA,
;                                            const AddrB addrB, const Epi E) {
;     ...
;     if (!has_next) break;
;     if (!(Epi::KEEP && cur.br + 1 < S.nbr)) {
; #pragma unroll
;       for (int a = 0; a < 2; ++a)
; #pragma unroll
;         for (int b = 0; b < 2; ++b)
; #pragma unroll
;           for (int m = 0; m < 4; ++m)
; #pragma unroll
;             for (int n = 0; n < 2; ++n) acc[a][b][m][n] = (f32x4){0.f, 0.f, 0.f, 0.f};
;     }
;     cur = nxt; cA = nA; cB = nB; ++ui;
;   __device__ __forceinline__ void operator()(EPI_ARGS) const {
;     ...
;         for (int m = 0; m < 4; ++m) z[m] = *(const u32x4*)(proj + pidx(row0 + ai * HALF + m * 16, PZ + c));
;         __builtin_amdgcn_sched_barrier(0);
; #pragma unroll
;         for (int m = 0; m < 4; ++m) {
;           const size_t row = row0 + ai * HALF + m * 16;
;           const f32x4 v0 = acc[ai][bj][m][0], v1 = acc[ai][bj][m][1];
;           u32x4 o;
;           o.x = pack2(v0[0] * s0[0] * siluf_(bflo(z[m].x)), v0[1] * s0[1] * siluf_(bfhi(z[m].x)));
;           o.y = pack2(v0[2] * s0[2] * siluf_(bflo(z[m].y)), v0[3] * s0[3] * siluf_(bfhi(z[m].y)));
;           o.z = pack2(v1[0] * s1[0] * siluf_(bflo(z[m].z)), v1[1] * s1[1] * siluf_(bfhi(z[m].z)));
;           o.w = pack2(v1[2] * s1[2] * siluf_(bflo(z[m].w)), v1[3] * s1[3] * siluf_(bfhi(z[m].w)));
;           *(u32x4*)(y0 + row * DM + c) = o;
	v_lshlrev_b32_e32 v53, 16, v48
	v_mul_f32_e32 v2, 0xbfb8aa3b, v53
	v_exp_f32_e32 v2, v2
	v_mov_b32_e32 v54, v32
	v_mov_b32_e32 v52, v72
	s_and_b64 vcc, exec, s[18:19]
	v_add_f32_e32 v2, 1.0, v2
	v_rcp_f32_e32 v55, v2
	s_mov_b32 s33, s16
	s_mov_b32 s2, s14
	s_mov_b64 s[4:5], s[22:23]
	v_pk_mul_f32 v[52:53], v[54:55], v[52:53]
	v_mov_b32_e32 v54, v33
	v_mul_f32_e32 v2, v52, v53
	v_and_b32_e32 v53, 0xffff0000, v48
	v_mul_f32_e32 v32, 0xbfb8aa3b, v53
	v_exp_f32_e32 v32, v32
	v_mov_b32_e32 v52, v73
	v_mov_b32_e32 v48, v75
	s_mov_b64 s[6:7], s[20:21]
	v_add_f32_e32 v32, 1.0, v32
	v_rcp_f32_e32 v55, v32
	s_nop 0
	v_pk_mul_f32 v[32:33], v[54:55], v[52:53]
	s_nop 0
	v_mul_f32_e32 v32, v32, v33
	v_lshlrev_b32_e32 v53, 16, v49
	v_cvt_pk_bf16_f32 v32, v2, v32
	v_mul_f32_e32 v2, 0xbfb8aa3b, v53
	v_exp_f32_e32 v2, v2
	v_and_b32_e32 v49, 0xffff0000, v49
	v_mul_f32_e32 v33, 0xbfb8aa3b, v49
	v_exp_f32_e32 v33, v33
	v_add_f32_e32 v2, 1.0, v2
	v_rcp_f32_e32 v55, v2
	v_mov_b32_e32 v54, v34
	v_mov_b32_e32 v52, v74
	v_add_f32_e32 v33, 1.0, v33
	v_pk_mul_f32 v[52:53], v[54:55], v[52:53]
	s_nop 0
	v_mul_f32_e32 v2, v52, v53
	v_rcp_f32_e32 v53, v33
	v_mov_b32_e32 v52, v35
	v_pk_mul_f32 v[34:35], v[52:53], v[48:49]
	s_nop 0
	v_mul_f32_e32 v33, v34, v35
	v_lshlrev_b32_e32 v35, 16, v50
	v_cvt_pk_bf16_f32 v33, v2, v33
	v_mul_f32_e32 v2, 0xbfb8aa3b, v35
	v_exp_f32_e32 v2, v2
	v_mov_b32_e32 v48, v28
	v_mov_b32_e32 v34, v68
	v_add_f32_e32 v2, 1.0, v2
	v_rcp_f32_e32 v49, v2
	s_nop 0
	v_pk_mul_f32 v[34:35], v[48:49], v[34:35]
	s_nop 0
	v_mul_f32_e32 v2, v34, v35
	v_and_b32_e32 v35, 0xffff0000, v50
	v_mul_f32_e32 v28, 0xbfb8aa3b, v35
	v_exp_f32_e32 v28, v28
	v_mov_b32_e32 v48, v29
	v_mov_b32_e32 v34, v69
	v_add_f32_e32 v28, 1.0, v28
	v_rcp_f32_e32 v49, v28
	s_nop 0
	v_pk_mul_f32 v[28:29], v[48:49], v[34:35]
	s_nop 0
	v_mul_f32_e32 v28, v28, v29
	v_lshlrev_b32_e32 v29, 16, v51
	v_cvt_pk_bf16_f32 v34, v2, v28
	v_mul_f32_e32 v2, 0xbfb8aa3b, v29
	v_exp_f32_e32 v2, v2
	v_mov_b32_e32 v48, v30
	v_mov_b32_e32 v28, v70
	v_mov_b32_e32 v30, v24
	v_add_f32_e32 v2, 1.0, v2
	v_rcp_f32_e32 v49, v2
	s_nop 0
	v_pk_mul_f32 v[28:29], v[48:49], v[28:29]
	s_nop 0
	v_mul_f32_e32 v2, v28, v29
	v_and_b32_e32 v29, 0xffff0000, v51
	v_mul_f32_e32 v28, 0xbfb8aa3b, v29
	v_exp_f32_e32 v28, v28
	v_mov_b32_e32 v48, v31
	v_add_f32_e32 v28, 1.0, v28
	v_rcp_f32_e32 v49, v28
	v_mov_b32_e32 v28, v71
	v_pk_mul_f32 v[28:29], v[48:49], v[28:29]
	s_nop 0
	v_mul_f32_e32 v28, v28, v29
	v_lshlrev_b32_e32 v29, 16, v44
	v_cvt_pk_bf16_f32 v35, v2, v28
	v_mul_f32_e32 v2, 0xbfb8aa3b, v29
	v_exp_f32_e32 v2, v2
	v_mov_b32_e32 v28, v72
	flat_store_dwordx4 v[96:97], v[32:35] offset:256
	v_add_f32_e32 v2, 1.0, v2
	v_rcp_f32_e32 v31, v2
	s_nop 0
	v_pk_mul_f32 v[28:29], v[30:31], v[28:29]
	s_nop 0
	v_mul_f32_e32 v2, v28, v29
	v_and_b32_e32 v29, 0xffff0000, v44
	v_mul_f32_e32 v24, 0xbfb8aa3b, v29
	v_exp_f32_e32 v24, v24
	v_mov_b32_e32 v30, v25
	v_mov_b32_e32 v28, v73
	v_add_f32_e32 v24, 1.0, v24
	v_rcp_f32_e32 v31, v24
	s_nop 0
	v_pk_mul_f32 v[24:25], v[30:31], v[28:29]
	s_nop 0
	v_mul_f32_e32 v24, v24, v25
	v_lshlrev_b32_e32 v29, 16, v45
	v_cvt_pk_bf16_f32 v24, v2, v24
	v_mul_f32_e32 v2, 0xbfb8aa3b, v29
	v_exp_f32_e32 v2, v2
	v_mov_b32_e32 v30, v26
	v_mov_b32_e32 v28, v74
	v_add_f32_e32 v2, 1.0, v2
	v_rcp_f32_e32 v31, v2
	s_nop 0
	v_pk_mul_f32 v[28:29], v[30:31], v[28:29]
	s_nop 0
	v_mul_f32_e32 v2, v28, v29
	v_and_b32_e32 v29, 0xffff0000, v45
	v_mul_f32_e32 v25, 0xbfb8aa3b, v29
	v_exp_f32_e32 v25, v25
	v_mov_b32_e32 v30, v27
	v_mov_b32_e32 v28, v75
	v_add_f32_e32 v25, 1.0, v25
	v_rcp_f32_e32 v31, v25
	s_nop 0
	v_pk_mul_f32 v[26:27], v[30:31], v[28:29]
	s_nop 0
	v_mul_f32_e32 v25, v26, v27
	v_lshlrev_b32_e32 v27, 16, v46
	v_cvt_pk_bf16_f32 v25, v2, v25
	v_mul_f32_e32 v2, 0xbfb8aa3b, v27
	v_exp_f32_e32 v2, v2
	v_mov_b32_e32 v28, v20
	v_mov_b32_e32 v26, v68
	v_add_f32_e32 v2, 1.0, v2
	v_rcp_f32_e32 v29, v2
	s_nop 0
	v_pk_mul_f32 v[26:27], v[28:29], v[26:27]
	s_nop 0
	v_mul_f32_e32 v2, v26, v27
	v_and_b32_e32 v27, 0xffff0000, v46
	v_mul_f32_e32 v20, 0xbfb8aa3b, v27
	v_exp_f32_e32 v20, v20
	v_mov_b32_e32 v28, v21
	v_mov_b32_e32 v26, v69
	v_add_f32_e32 v20, 1.0, v20
	v_rcp_f32_e32 v29, v20
	s_nop 0
	v_pk_mul_f32 v[20:21], v[28:29], v[26:27]
	s_nop 0
	v_mul_f32_e32 v20, v20, v21
	v_lshlrev_b32_e32 v21, 16, v47
	v_cvt_pk_bf16_f32 v26, v2, v20
	v_mul_f32_e32 v2, 0xbfb8aa3b, v21
	v_exp_f32_e32 v2, v2
	v_mov_b32_e32 v28, v22
	v_mov_b32_e32 v20, v70
	v_mov_b32_e32 v22, v16
	v_add_f32_e32 v2, 1.0, v2
	v_rcp_f32_e32 v29, v2
	s_nop 0
	v_pk_mul_f32 v[20:21], v[28:29], v[20:21]
	s_nop 0
	v_mul_f32_e32 v2, v20, v21
	v_and_b32_e32 v21, 0xffff0000, v47
	v_mul_f32_e32 v20, 0xbfb8aa3b, v21
	v_exp_f32_e32 v20, v20
	v_mov_b32_e32 v28, v23
	v_add_f32_e32 v20, 1.0, v20
	v_rcp_f32_e32 v29, v20
	v_mov_b32_e32 v20, v71
	v_pk_mul_f32 v[20:21], v[28:29], v[20:21]
	s_nop 0
	v_mul_f32_e32 v20, v20, v21
	v_lshlrev_b32_e32 v21, 16, v40
	v_cvt_pk_bf16_f32 v27, v2, v20
	v_mul_f32_e32 v2, 0xbfb8aa3b, v21
	v_exp_f32_e32 v2, v2
	v_mov_b32_e32 v20, v72
	flat_store_dwordx4 v[98:99], v[24:27] offset:256
; __device__ __forceinline__ float bflo(unsigned v) { return __uint_as_float(v << 16); }
; __device__ __forceinline__ float bfhi(unsigned v) { return __uint_as_float(v & 0xffff0000u); }
; __device__ __forceinline__ float siluf_(float x) { return x * __builtin_amdgcn_rcpf(1.0f + __expf(-x)); }
; #define PG8_WAIT_V(n) asm volatile("s_waitcnt vmcnt(" #n ")" ::: "memory")
; #define PG8_BAR __builtin_amdgcn_s_barrier()
; template <class Epi, class AddrA, class AddrB>
; __device__ __forceinline__ void gemm_phase(const Sched S, const int lda, const int ldb, const int K, const AddrA addrA,
;                                            const AddrB addrB, const Epi E) {
;     ...
;   PG8_WAIT_V(0);
;   if (wr == 0) PG8_BAR;
;   PG8_BAR;
;   __device__ __forceinline__ void operator()(EPI_ARGS) const {
;     ...
;         for (int m = 0; m < 4; ++m) {
;           const size_t row = row0 + ai * HALF + m * 16;
;           const f32x4 v0 = acc[ai][bj][m][0], v1 = acc[ai][bj][m][1];
;           u32x4 o;
;           o.x = pack2(v0[0] * s0[0] * siluf_(bflo(z[m].x)), v0[1] * s0[1] * siluf_(bfhi(z[m].x)));
;           o.y = pack2(v0[2] * s0[2] * siluf_(bflo(z[m].y)), v0[3] * s0[3] * siluf_(bfhi(z[m].y)));
;           o.z = pack2(v1[0] * s1[0] * siluf_(bflo(z[m].z)), v1[1] * s1[1] * siluf_(bfhi(z[m].z)));
;           o.w = pack2(v1[2] * s1[2] * siluf_(bflo(z[m].w)), v1[3] * s1[3] * siluf_(bfhi(z[m].w)));
;           *(u32x4*)(y0 + row * DM + c) = o;
	v_add_f32_e32 v2, 1.0, v2
	v_rcp_f32_e32 v23, v2
	s_nop 0
	v_pk_mul_f32 v[20:21], v[22:23], v[20:21]
	s_nop 0
	v_mul_f32_e32 v2, v20, v21
	v_and_b32_e32 v21, 0xffff0000, v40
	v_mul_f32_e32 v16, 0xbfb8aa3b, v21
	v_exp_f32_e32 v16, v16
	v_mov_b32_e32 v22, v17
	v_mov_b32_e32 v20, v73
	v_add_f32_e32 v16, 1.0, v16
	v_rcp_f32_e32 v23, v16
	s_nop 0
	v_pk_mul_f32 v[16:17], v[22:23], v[20:21]
	s_nop 0
	v_mul_f32_e32 v16, v16, v17
	v_lshlrev_b32_e32 v21, 16, v41
	v_cvt_pk_bf16_f32 v16, v2, v16
	v_mul_f32_e32 v2, 0xbfb8aa3b, v21
	v_exp_f32_e32 v2, v2
	v_mov_b32_e32 v22, v18
	v_mov_b32_e32 v20, v74
	v_add_f32_e32 v2, 1.0, v2
	v_rcp_f32_e32 v23, v2
	s_nop 0
	v_pk_mul_f32 v[20:21], v[22:23], v[20:21]
	s_nop 0
	v_mul_f32_e32 v2, v20, v21
	v_and_b32_e32 v21, 0xffff0000, v41
	v_mul_f32_e32 v17, 0xbfb8aa3b, v21
	v_exp_f32_e32 v17, v17
	v_mov_b32_e32 v22, v19
	v_mov_b32_e32 v20, v75
	v_add_f32_e32 v17, 1.0, v17
	v_rcp_f32_e32 v23, v17
	s_nop 0
	v_pk_mul_f32 v[18:19], v[22:23], v[20:21]
	s_nop 0
	v_mul_f32_e32 v17, v18, v19
	v_lshlrev_b32_e32 v19, 16, v42
	v_cvt_pk_bf16_f32 v17, v2, v17
	v_mul_f32_e32 v2, 0xbfb8aa3b, v19
	v_exp_f32_e32 v2, v2
	v_mov_b32_e32 v20, v12
	v_mov_b32_e32 v18, v68
	v_add_f32_e32 v2, 1.0, v2
	v_rcp_f32_e32 v21, v2
	s_nop 0
	v_pk_mul_f32 v[18:19], v[20:21], v[18:19]
	s_nop 0
	v_mul_f32_e32 v2, v18, v19
	v_and_b32_e32 v19, 0xffff0000, v42
	v_mul_f32_e32 v12, 0xbfb8aa3b, v19
	v_exp_f32_e32 v12, v12
	v_mov_b32_e32 v20, v13
	v_mov_b32_e32 v18, v69
	v_add_f32_e32 v12, 1.0, v12
	v_rcp_f32_e32 v21, v12
	s_nop 0
	v_pk_mul_f32 v[12:13], v[20:21], v[18:19]
	s_nop 0
	v_mul_f32_e32 v12, v12, v13
	v_lshlrev_b32_e32 v13, 16, v43
	v_cvt_pk_bf16_f32 v18, v2, v12
	v_mul_f32_e32 v2, 0xbfb8aa3b, v13
	v_exp_f32_e32 v2, v2
	v_mov_b32_e32 v20, v14
	v_mov_b32_e32 v12, v70
	v_mov_b32_e32 v14, v8
	v_add_f32_e32 v2, 1.0, v2
	v_rcp_f32_e32 v21, v2
	s_nop 0
	v_pk_mul_f32 v[12:13], v[20:21], v[12:13]
	s_nop 0
	v_mul_f32_e32 v2, v12, v13
	v_and_b32_e32 v13, 0xffff0000, v43
	v_mul_f32_e32 v12, 0xbfb8aa3b, v13
	v_exp_f32_e32 v12, v12
	v_mov_b32_e32 v20, v15
	v_add_f32_e32 v12, 1.0, v12
	v_rcp_f32_e32 v21, v12
	v_mov_b32_e32 v12, v71
	v_pk_mul_f32 v[12:13], v[20:21], v[12:13]
	s_nop 0
	v_mul_f32_e32 v12, v12, v13
	v_lshlrev_b32_e32 v13, 16, v36
	v_cvt_pk_bf16_f32 v19, v2, v12
	v_mul_f32_e32 v2, 0xbfb8aa3b, v13
	v_exp_f32_e32 v2, v2
	v_mov_b32_e32 v12, v72
	flat_store_dwordx4 v[104:105], v[16:19] offset:256
	v_add_f32_e32 v2, 1.0, v2
	v_rcp_f32_e32 v15, v2
	s_nop 0
	v_pk_mul_f32 v[12:13], v[14:15], v[12:13]
	s_nop 0
	v_mul_f32_e32 v2, v12, v13
	v_and_b32_e32 v13, 0xffff0000, v36
	v_mul_f32_e32 v8, 0xbfb8aa3b, v13
	v_exp_f32_e32 v8, v8
	v_mov_b32_e32 v14, v9
	v_mov_b32_e32 v12, v73
	v_add_f32_e32 v8, 1.0, v8
	v_rcp_f32_e32 v15, v8
	s_nop 0
	v_pk_mul_f32 v[8:9], v[14:15], v[12:13]
	s_nop 0
	v_mul_f32_e32 v8, v8, v9
	v_lshlrev_b32_e32 v13, 16, v37
	v_cvt_pk_bf16_f32 v8, v2, v8
	v_mul_f32_e32 v2, 0xbfb8aa3b, v13
	v_exp_f32_e32 v2, v2
	v_mov_b32_e32 v14, v10
	v_mov_b32_e32 v12, v74
	v_add_f32_e32 v2, 1.0, v2
	v_rcp_f32_e32 v15, v2
	s_nop 0
	v_pk_mul_f32 v[12:13], v[14:15], v[12:13]
	s_nop 0
	v_mul_f32_e32 v2, v12, v13
	v_and_b32_e32 v13, 0xffff0000, v37
	v_mul_f32_e32 v9, 0xbfb8aa3b, v13
	v_exp_f32_e32 v9, v9
	v_mov_b32_e32 v14, v11
	v_mov_b32_e32 v12, v75
	v_add_f32_e32 v9, 1.0, v9
	v_rcp_f32_e32 v15, v9
	s_nop 0
	v_pk_mul_f32 v[10:11], v[14:15], v[12:13]
	s_nop 0
	v_mul_f32_e32 v9, v10, v11
	v_lshlrev_b32_e32 v11, 16, v38
	v_cvt_pk_bf16_f32 v9, v2, v9
	v_mul_f32_e32 v2, 0xbfb8aa3b, v11
	v_exp_f32_e32 v2, v2
	v_mov_b32_e32 v12, v4
	v_mov_b32_e32 v10, v68
	v_add_f32_e32 v2, 1.0, v2
	v_rcp_f32_e32 v13, v2
	s_nop 0
	v_pk_mul_f32 v[10:11], v[12:13], v[10:11]
	s_nop 0
	v_mul_f32_e32 v2, v10, v11
	v_and_b32_e32 v11, 0xffff0000, v38
	v_mul_f32_e32 v4, 0xbfb8aa3b, v11
	v_exp_f32_e32 v4, v4
	v_mov_b32_e32 v12, v5
	v_mov_b32_e32 v10, v69
	v_add_f32_e32 v4, 1.0, v4
	v_rcp_f32_e32 v13, v4
	s_nop 0
	v_pk_mul_f32 v[4:5], v[12:13], v[10:11]
	s_nop 0
	v_mul_f32_e32 v4, v4, v5
	v_lshlrev_b32_e32 v5, 16, v39
	v_cvt_pk_bf16_f32 v10, v2, v4
	v_mul_f32_e32 v2, 0xbfb8aa3b, v5
	v_exp_f32_e32 v2, v2
	v_mov_b32_e32 v12, v6
	v_mov_b32_e32 v4, v70
	v_add_f32_e32 v2, 1.0, v2
	v_rcp_f32_e32 v13, v2
	s_nop 0
	v_pk_mul_f32 v[4:5], v[12:13], v[4:5]
	s_nop 0
	v_mul_f32_e32 v2, v4, v5
	v_and_b32_e32 v5, 0xffff0000, v39
	v_mul_f32_e32 v4, 0xbfb8aa3b, v5
	v_exp_f32_e32 v4, v4
	v_mov_b32_e32 v12, v7
	v_add_f32_e32 v4, 1.0, v4
	v_rcp_f32_e32 v13, v4
	v_mov_b32_e32 v4, v71
	v_pk_mul_f32 v[4:5], v[12:13], v[4:5]
	s_nop 0
	v_mul_f32_e32 v4, v4, v5
	v_cvt_pk_bf16_f32 v11, v2, v4
	flat_store_dwordx4 v[92:93], v[8:11] offset:256
	s_cbranch_vccz .LBB0_482
	s_waitcnt vmcnt(0)
	v_readlane_b32 s44, v244, 59
	v_readlane_b32 s40, v243, 18
	s_cmpk_gt_u32 s24, 0xff
	s_mov_b32 s43, 0x800000
	v_readlane_b32 s45, v244, 60
	v_readlane_b32 s46, v244, 61
	v_readlane_b32 s47, v244, 62
	v_readlane_b32 s48, v244, 63
	v_readlane_b32 s49, v243, 0
	v_readlane_b32 s50, v243, 1
	v_readlane_b32 s51, v243, 2
	v_readlane_b32 s41, v243, 19
	s_cbranch_scc1 .LBB0_489
	s_barrier

; #define PG8_WAIT_V(n) asm volatile("s_waitcnt vmcnt(" #n ")" ::: "memory")
; #define PG8_WAIT_L(n) asm volatile("s_waitcnt lgkmcnt(" #n ")" ::: "memory")
; #define PG8_BAR __builtin_amdgcn_s_barrier()
; #define PG8_SCHED __builtin_amdgcn_sched_barrier(0)
; template <class Epi, class AddrA, class AddrB>
; __device__ __forceinline__ void gemm_phase(const Sched S, const int lda, const int ldb, const int K, const AddrA addrA,
;                                            const AddrB addrB, const Epi E) {
;     ...
;       PG8_LDB(B0, 0, 0); PG8_SCHED; PG8_LDA(At, 0, 0); PG8_STAGE(PG8_SA(1, 1), a1 + hstepA, voffA);
;       PG8_WAIT_L(8); PG8_BAR; PG8_WAIT_L(0); PG8_MMA(0, 0, At, B0); PG8_BAR; PG8_SCHED;
;       PG8_LDB(B1, 0, 1); PG8_STAGE(PG8_SB(0, 0), b2, voffB);
;       PG8_BAR; PG8_WAIT_L(0); PG8_MMA(0, 1, At, B1); PG8_BAR;
;       PG8_LDA(At, 0, 1); PG8_STAGE(PG8_SA(0, 0), a2, voffA);
;       PG8_BAR; PG8_WAIT_L(0); PG8_MMA(1, 0, At, B0); PG8_BAR; PG8_SCHED;
;       PG8_STAGE(PG8_SB(0, 1), b2 + hstepB, voffB);
;       PG8_WAIT_V(6); PG8_BAR; PG8_MMA(1, 1, At, B1); PG8_BAR;
.LBB0_543:
	s_add_i32 s43, 0, 0x10000
	v_add_u32_e32 v0, s43, v167
	ds_read_b128 v[132:135], v0
	ds_read_b128 v[136:139], v0 offset:1024
	ds_read_b128 v[140:143], v0 offset:2048
	ds_read_b128 v[144:147], v0 offset:3072
	v_lshl_add_u64 v[0:1], s[2:3], 0, v[180:181]
	s_add_i32 m0, s28, 0xc000
	ds_read_b128 v[148:151], v188
	ds_read_b128 v[152:155], v188 offset:1024
	ds_read_b128 v[156:159], v188 offset:2048
	ds_read_b128 v[160:163], v188 offset:3072
	ds_read_b128 v[182:185], v188 offset:4096
	ds_read_b128 v[190:193], v188 offset:5120
	ds_read_b128 v[194:197], v188 offset:6144
	ds_read_b128 v[212:215], v188 offset:7168
	global_load_lds_dwordx4 v[0:1], off
	v_lshl_add_u64 v[0:1], s[2:3], 0, v[178:179]
	s_add_i32 m0, s28, 0xe000
	s_nop 0
	global_load_lds_dwordx4 v[0:1], off
	s_waitcnt lgkmcnt(8)
	s_setprio 1
	s_barrier
	s_waitcnt lgkmcnt(0)
	v_mfma_f32_16x16x32_bf16 v[128:131], v[132:135], v[148:151], v[128:131]
	v_mfma_f32_16x16x32_bf16 v[128:131], v[136:139], v[152:155], v[128:131]
	v_mfma_f32_16x16x32_bf16 v[120:123], v[132:135], v[156:159], v[120:123]
	v_mfma_f32_16x16x32_bf16 v[120:123], v[136:139], v[160:163], v[120:123]
	v_mfma_f32_16x16x32_bf16 v[112:115], v[132:135], v[182:185], v[112:115]
	v_mfma_f32_16x16x32_bf16 v[112:115], v[136:139], v[190:193], v[112:115]
	v_mfma_f32_16x16x32_bf16 v[104:107], v[132:135], v[194:197], v[104:107]
	v_mfma_f32_16x16x32_bf16 v[104:107], v[136:139], v[212:215], v[104:107]
	v_mfma_f32_16x16x32_bf16 v[124:127], v[140:143], v[148:151], v[124:127]
	v_mfma_f32_16x16x32_bf16 v[124:127], v[144:147], v[152:155], v[124:127]
	v_mfma_f32_16x16x32_bf16 v[116:119], v[140:143], v[156:159], v[116:119]
	v_mfma_f32_16x16x32_bf16 v[116:119], v[144:147], v[160:163], v[116:119]
	v_mfma_f32_16x16x32_bf16 v[108:111], v[140:143], v[182:185], v[108:111]
	v_mfma_f32_16x16x32_bf16 v[108:111], v[144:147], v[190:193], v[108:111]
	v_mfma_f32_16x16x32_bf16 v[100:103], v[140:143], v[194:197], v[100:103]
	v_mfma_f32_16x16x32_bf16 v[100:103], v[144:147], v[212:215], v[100:103]
	s_barrier
	s_setprio 0
	s_add_u32 s4, s2, 0xfff80080
	s_addc_u32 s5, s3, -1
	s_cmp_eq_u32 s42, 28
	s_cselect_b32 s7, s1, s5
	s_cselect_b32 s6, s9, s4
	s_cselect_b32 s5, s13, s41
	s_cselect_b32 s4, s15, s33
	s_add_i32 s46, 0, 0x14000
	v_add_u32_e32 v0, s46, v167
	s_add_i32 s43, s43, s27
	ds_read_b128 v[216:219], v0
	ds_read_b128 v[220:223], v0 offset:1024
	ds_read_b128 v[224:227], v0 offset:2048
	ds_read_b128 v[228:231], v0 offset:3072
	v_lshl_add_u64 v[0:1], s[4:5], 0, v[172:173]
	s_mov_b32 m0, s43
	v_lshl_add_u64 v[232:233], s[4:5], 0, v[168:169]
	global_load_lds_dwordx4 v[0:1], off
	s_add_i32 m0, s43, 0x2000
	s_nop 0
	global_load_lds_dwordx4 v[232:233], off
	s_setprio 1
	s_barrier
	s_waitcnt lgkmcnt(0)
	v_mfma_f32_16x16x32_bf16 v[96:99], v[216:219], v[148:151], v[96:99]
	v_mfma_f32_16x16x32_bf16 v[96:99], v[220:223], v[152:155], v[96:99]
	v_mfma_f32_16x16x32_bf16 v[88:91], v[216:219], v[156:159], v[88:91]
	v_mfma_f32_16x16x32_bf16 v[88:91], v[220:223], v[160:163], v[88:91]
	v_mfma_f32_16x16x32_bf16 v[80:83], v[216:219], v[182:185], v[80:83]
	v_mfma_f32_16x16x32_bf16 v[80:83], v[220:223], v[190:193], v[80:83]
	v_mfma_f32_16x16x32_bf16 v[72:75], v[216:219], v[194:197], v[72:75]
	v_mfma_f32_16x16x32_bf16 v[72:75], v[220:223], v[212:215], v[72:75]
	v_mfma_f32_16x16x32_bf16 v[92:95], v[224:227], v[148:151], v[92:95]
	v_mfma_f32_16x16x32_bf16 v[92:95], v[228:231], v[152:155], v[92:95]
	v_mfma_f32_16x16x32_bf16 v[84:87], v[224:227], v[156:159], v[84:87]
	v_mfma_f32_16x16x32_bf16 v[84:87], v[228:231], v[160:163], v[84:87]
	v_mfma_f32_16x16x32_bf16 v[76:79], v[224:227], v[182:185], v[76:79]
	v_mfma_f32_16x16x32_bf16 v[76:79], v[228:231], v[190:193], v[76:79]
	v_mfma_f32_16x16x32_bf16 v[68:71], v[224:227], v[194:197], v[68:71]
	v_mfma_f32_16x16x32_bf16 v[68:71], v[228:231], v[212:215], v[68:71]
	s_barrier
	s_setprio 0
	s_mov_b32 m0, s28
	v_lshl_add_u64 v[234:235], s[6:7], 0, v[174:175]
	ds_read_b128 v[148:151], v188 offset:16384
	ds_read_b128 v[152:155], v188 offset:17408
	ds_read_b128 v[156:159], v188 offset:18432
	ds_read_b128 v[160:163], v188 offset:19456
	ds_read_b128 v[182:185], v188 offset:20480
	ds_read_b128 v[190:193], v188 offset:21504
	ds_read_b128 v[194:197], v188 offset:22528
	ds_read_b128 v[212:215], v188 offset:23552
	global_load_lds_dwordx4 v[234:235], off
	v_lshl_add_u64 v[236:237], s[6:7], 0, v[170:171]
	s_mov_b32 m0, s29
	s_nop 0
	global_load_lds_dwordx4 v[236:237], off
	s_setprio 1
	s_barrier
	s_waitcnt lgkmcnt(0)
	v_mfma_f32_16x16x32_bf16 v[64:67], v[132:135], v[148:151], v[64:67]
	v_mfma_f32_16x16x32_bf16 v[64:67], v[136:139], v[152:155], v[64:67]
	v_mfma_f32_16x16x32_bf16 v[56:59], v[132:135], v[156:159], v[56:59]
	v_mfma_f32_16x16x32_bf16 v[56:59], v[136:139], v[160:163], v[56:59]
	v_mfma_f32_16x16x32_bf16 v[48:51], v[132:135], v[182:185], v[48:51]
	v_mfma_f32_16x16x32_bf16 v[48:51], v[136:139], v[190:193], v[48:51]
	v_mfma_f32_16x16x32_bf16 v[40:43], v[132:135], v[194:197], v[40:43]
	v_mfma_f32_16x16x32_bf16 v[40:43], v[136:139], v[212:215], v[40:43]
	v_mfma_f32_16x16x32_bf16 v[60:63], v[140:143], v[148:151], v[60:63]
	v_mfma_f32_16x16x32_bf16 v[60:63], v[144:147], v[152:155], v[60:63]
	v_mfma_f32_16x16x32_bf16 v[52:55], v[140:143], v[156:159], v[52:55]
	v_mfma_f32_16x16x32_bf16 v[52:55], v[144:147], v[160:163], v[52:55]
	v_mfma_f32_16x16x32_bf16 v[44:47], v[140:143], v[182:185], v[44:47]
	v_mfma_f32_16x16x32_bf16 v[44:47], v[144:147], v[190:193], v[44:47]
	v_mfma_f32_16x16x32_bf16 v[36:39], v[140:143], v[194:197], v[36:39]
	v_mfma_f32_16x16x32_bf16 v[36:39], v[144:147], v[212:215], v[36:39]
	s_barrier
; #define PG8_WAIT_V(n) asm volatile("s_waitcnt vmcnt(" #n ")" ::: "memory")
; #define PG8_WAIT_L(n) asm volatile("s_waitcnt lgkmcnt(" #n ")" ::: "memory")
; #define PG8_BAR __builtin_amdgcn_s_barrier()
; #define PG8_SCHED __builtin_amdgcn_sched_barrier(0)
; template <class Epi, class AddrA, class AddrB>
; __device__ __forceinline__ void gemm_phase(const Sched S, const int lda, const int ldb, const int K, const AddrA addrA,
;                                            const AddrB addrB, const Epi E) {
;     ...
;       PG8_BAR; PG8_WAIT_L(0); PG8_MMA(1, 0, At, B0); PG8_BAR; PG8_SCHED;
;       PG8_STAGE(PG8_SB(0, 1), b2 + hstepB, voffB);
;       PG8_WAIT_V(6); PG8_BAR; PG8_MMA(1, 1, At, B1); PG8_BAR;
;       PG8_LDB(B0, 1, 0); PG8_SCHED; PG8_LDA(At, 1, 0); PG8_STAGE(PG8_SA(0, 1), a2 + hstepA, voffA);
;       PG8_WAIT_L(8); PG8_BAR; PG8_WAIT_L(0); PG8_MMA(0, 0, At, B0); PG8_BAR; PG8_SCHED;
;       PG8_LDB(B1, 1, 1); PG8_STAGE(PG8_SB(1, 0), b3, voffB);
;       PG8_BAR; PG8_WAIT_L(0); PG8_MMA(0, 1, At, B1); PG8_BAR;
;       PG8_LDA(At, 1, 1); PG8_STAGE(PG8_SA(1, 0), a3, voffA);
;       PG8_BAR; PG8_WAIT_L(0); PG8_MMA(1, 0, At, B0); PG8_BAR; PG8_SCHED;
	s_setprio 0
	s_add_u32 s44, s4, 0x80000
	s_addc_u32 s45, s5, 0
	s_add_i32 s43, s46, s27
	v_lshl_add_u64 v[132:133], s[44:45], 0, v[172:173]
	s_mov_b32 m0, s43
	s_nop 0
	global_load_lds_dwordx4 v[132:133], off
	v_lshl_add_u64 v[132:133], s[44:45], 0, v[168:169]
	s_add_i32 m0, s43, 0x2000
	s_nop 0
	global_load_lds_dwordx4 v[132:133], off
	s_waitcnt vmcnt(6)
	s_setprio 1
	s_barrier
	v_mfma_f32_16x16x32_bf16 v[32:35], v[216:219], v[148:151], v[32:35]
	v_mfma_f32_16x16x32_bf16 v[32:35], v[220:223], v[152:155], v[32:35]
	v_mfma_f32_16x16x32_bf16 v[24:27], v[216:219], v[156:159], v[24:27]
	v_mfma_f32_16x16x32_bf16 v[24:27], v[220:223], v[160:163], v[24:27]
	v_mfma_f32_16x16x32_bf16 v[16:19], v[216:219], v[182:185], v[16:19]
	v_mfma_f32_16x16x32_bf16 v[16:19], v[220:223], v[190:193], v[16:19]
	v_mfma_f32_16x16x32_bf16 v[8:11], v[216:219], v[194:197], v[8:11]
	v_mfma_f32_16x16x32_bf16 v[8:11], v[220:223], v[212:215], v[8:11]
	v_mfma_f32_16x16x32_bf16 v[28:31], v[224:227], v[148:151], v[28:31]
	v_mfma_f32_16x16x32_bf16 v[28:31], v[228:231], v[152:155], v[28:31]
	v_mfma_f32_16x16x32_bf16 v[20:23], v[224:227], v[156:159], v[20:23]
	v_mfma_f32_16x16x32_bf16 v[20:23], v[228:231], v[160:163], v[20:23]
	v_mfma_f32_16x16x32_bf16 v[12:15], v[224:227], v[182:185], v[12:15]
	v_mfma_f32_16x16x32_bf16 v[12:15], v[228:231], v[190:193], v[12:15]
	v_mfma_f32_16x16x32_bf16 v[4:7], v[224:227], v[194:197], v[4:7]
	v_mfma_f32_16x16x32_bf16 v[4:7], v[228:231], v[212:215], v[4:7]
	s_barrier
	s_setprio 0
	s_add_i32 s43, 0, 0x18000
	v_add_u32_e32 v2, s43, v167
	ds_read_b128 v[132:135], v2
	ds_read_b128 v[136:139], v2 offset:1024
	ds_read_b128 v[140:143], v2 offset:2048
	ds_read_b128 v[144:147], v2 offset:3072
	s_add_u32 s6, s6, 0x80000
	s_addc_u32 s7, s7, 0
	s_mov_b32 m0, s30
	v_lshl_add_u64 v[216:217], s[6:7], 0, v[174:175]
	ds_read_b128 v[148:151], v188 offset:32768
	ds_read_b128 v[152:155], v188 offset:33792
	ds_read_b128 v[156:159], v188 offset:34816
	ds_read_b128 v[160:163], v188 offset:35840
	ds_read_b128 v[182:185], v188 offset:36864
	ds_read_b128 v[190:193], v188 offset:37888
	ds_read_b128 v[194:197], v188 offset:38912
	ds_read_b128 v[212:215], v188 offset:39936
	global_load_lds_dwordx4 v[216:217], off
	v_lshl_add_u64 v[216:217], s[6:7], 0, v[170:171]
	s_mov_b32 m0, s31
	s_nop 0
	global_load_lds_dwordx4 v[216:217], off
	s_waitcnt lgkmcnt(8)
	s_setprio 1
	s_barrier
	s_waitcnt lgkmcnt(0)
	v_mfma_f32_16x16x32_bf16 v[128:131], v[132:135], v[148:151], v[128:131]
	v_mfma_f32_16x16x32_bf16 v[128:131], v[136:139], v[152:155], v[128:131]
	v_mfma_f32_16x16x32_bf16 v[120:123], v[132:135], v[156:159], v[120:123]
	v_mfma_f32_16x16x32_bf16 v[120:123], v[136:139], v[160:163], v[120:123]
	v_mfma_f32_16x16x32_bf16 v[112:115], v[132:135], v[182:185], v[112:115]
	v_mfma_f32_16x16x32_bf16 v[112:115], v[136:139], v[190:193], v[112:115]
	v_mfma_f32_16x16x32_bf16 v[104:107], v[132:135], v[194:197], v[104:107]
	v_mfma_f32_16x16x32_bf16 v[104:107], v[136:139], v[212:215], v[104:107]
	v_mfma_f32_16x16x32_bf16 v[124:127], v[140:143], v[148:151], v[124:127]
	v_mfma_f32_16x16x32_bf16 v[124:127], v[144:147], v[152:155], v[124:127]
	v_mfma_f32_16x16x32_bf16 v[116:119], v[140:143], v[156:159], v[116:119]
	v_mfma_f32_16x16x32_bf16 v[116:119], v[144:147], v[160:163], v[116:119]
	v_mfma_f32_16x16x32_bf16 v[108:111], v[140:143], v[182:185], v[108:111]
	v_mfma_f32_16x16x32_bf16 v[108:111], v[144:147], v[190:193], v[108:111]
	v_mfma_f32_16x16x32_bf16 v[100:103], v[140:143], v[194:197], v[100:103]
	v_mfma_f32_16x16x32_bf16 v[100:103], v[144:147], v[212:215], v[100:103]
	s_barrier
	s_setprio 0
	s_add_i32 s6, 0, 0x1c000
	s_add_i32 s7, s43, s27
	v_add_u32_e32 v2, s6, v167
	v_lshl_add_u64 v[0:1], v[0:1], 0, s[52:53]
	s_mov_b32 m0, s7
	ds_read_b128 v[216:219], v2
	ds_read_b128 v[220:223], v2 offset:1024
	ds_read_b128 v[224:227], v2 offset:2048
	ds_read_b128 v[228:231], v2 offset:3072
	global_load_lds_dwordx4 v[0:1], off
	v_lshl_add_u64 v[0:1], v[232:233], 0, s[52:53]
	s_add_i32 m0, s7, 0x2000
	s_nop 0
	global_load_lds_dwordx4 v[0:1], off
	s_setprio 1
	s_barrier
	s_waitcnt lgkmcnt(0)
	v_mfma_f32_16x16x32_bf16 v[96:99], v[216:219], v[148:151], v[96:99]
	v_mfma_f32_16x16x32_bf16 v[96:99], v[220:223], v[152:155], v[96:99]
	v_mfma_f32_16x16x32_bf16 v[88:91], v[216:219], v[156:159], v[88:91]
	v_mfma_f32_16x16x32_bf16 v[88:91], v[220:223], v[160:163], v[88:91]
	v_mfma_f32_16x16x32_bf16 v[80:83], v[216:219], v[182:185], v[80:83]
	v_mfma_f32_16x16x32_bf16 v[80:83], v[220:223], v[190:193], v[80:83]
	v_mfma_f32_16x16x32_bf16 v[72:75], v[216:219], v[194:197], v[72:75]
	v_mfma_f32_16x16x32_bf16 v[72:75], v[220:223], v[212:215], v[72:75]
	v_mfma_f32_16x16x32_bf16 v[92:95], v[224:227], v[148:151], v[92:95]
	v_mfma_f32_16x16x32_bf16 v[92:95], v[228:231], v[152:155], v[92:95]
	v_mfma_f32_16x16x32_bf16 v[84:87], v[224:227], v[156:159], v[84:87]
	v_mfma_f32_16x16x32_bf16 v[84:87], v[228:231], v[160:163], v[84:87]
	v_mfma_f32_16x16x32_bf16 v[76:79], v[224:227], v[182:185], v[76:79]
	v_mfma_f32_16x16x32_bf16 v[76:79], v[228:231], v[190:193], v[76:79]
	v_mfma_f32_16x16x32_bf16 v[68:71], v[224:227], v[194:197], v[68:71]
	v_mfma_f32_16x16x32_bf16 v[68:71], v[228:231], v[212:215], v[68:71]
	s_barrier
	s_setprio 0
	s_mov_b32 m0, s38
	v_lshl_add_u64 v[0:1], v[234:235], 0, s[52:53]
	ds_read_b128 v[148:151], v188 offset:49152
	ds_read_b128 v[152:155], v188 offset:50176
	ds_read_b128 v[156:159], v188 offset:51200
	ds_read_b128 v[160:163], v188 offset:52224
	ds_read_b128 v[182:185], v188 offset:53248
	ds_read_b128 v[190:193], v188 offset:54272
	ds_read_b128 v[194:197], v188 offset:55296
	ds_read_b128 v[212:215], v188 offset:56320
	global_load_lds_dwordx4 v[0:1], off
	v_lshl_add_u64 v[0:1], v[236:237], 0, s[52:53]
	s_mov_b32 m0, s39
	s_nop 0
	global_load_lds_dwordx4 v[0:1], off
	s_setprio 1
	s_barrier
; #define PG8_WAIT_V(n) asm volatile("s_waitcnt vmcnt(" #n ")" ::: "memory")
; #define PG8_WAIT_L(n) asm volatile("s_waitcnt lgkmcnt(" #n ")" ::: "memory")
; #define PG8_BAR __builtin_amdgcn_s_barrier()
; #define PG8_SCHED __builtin_amdgcn_sched_barrier(0)
; template <class Epi, class AddrA, class AddrB>
; __device__ __forceinline__ void gemm_phase(const Sched S, const int lda, const int ldb, const int K, const AddrA addrA,
;                                            const AddrB addrB, const Epi E) {
;     ...
;       PG8_BAR; PG8_WAIT_L(0); PG8_MMA(1, 0, At, B0); PG8_BAR; PG8_SCHED;
;       PG8_STAGE(PG8_SB(1, 1), b3 + hstepB, voffB);
;       PG8_WAIT_V(6); PG8_BAR; PG8_MMA(1, 1, At, B1); PG8_BAR;
;   __device__ __forceinline__ void operator()(EPI_ARGS) const {
;     const int col0 = u.pn * 256 + wc * 32 + 8 * fq;
;     const int br = u.br, brn = br < 2 ? br + 1 : 2;
;     const unsigned loff0 = (unsigned)((wr * 64 + fr) * PLD + wc * 32 + 8 * fq);
;     const bf16_t* pc = proj + ((size_t)((GT + br * DM) / 256 + u.pn) * MTOK + (size_t)u.pm * 256) * PLD;
;     const bf16_t* pn_ = proj + ((size_t)((GT + brn * DM) / 256 + u.pn) * MTOK + (size_t)u.pm * 256) * PLD;
;     bf16_t* mrow = merged + ((size_t)u.pm * 256 + wr * 64 + fr) * DM + col0;
; #pragma unroll
;     for (int bj = 0; bj < 2; ++bj) {
;       const int c = col0 + bj * HALF;
;       float gc[8], gn[8];
;       {
;         const f32x4 a0 = *(const f32x4*)(bg + br * DM + c), a1 = *(const f32x4*)(bg + br * DM + c + 4);
;         const f32x4 b0 = *(const f32x4*)(bg + brn * DM + c), b1 = *(const f32x4*)(bg + brn * DM + c + 4);
; #pragma unroll
;         for (int k = 0; k < 4; ++k) { gc[k] = a0[k]; gc[4 + k] = a1[k]; gn[k] = b0[k]; gn[4 + k] = b1[k]; }
;       }
; #pragma unroll
;       for (int ai = 0; ai < 2; ++ai) {
;         unsigned loff = loff0;
;         asm volatile("" : "+v"(loff));
;         u32x4 zc[4], zn[4];
; #pragma unroll
;         for (int m = 0; m < 4; ++m) {
;           const unsigned o = loff + (unsigned)((ai * HALF + m * 16) * PLD + bj * HALF);
;           zc[m] = *(const u32x4*)(pc + o);
;           zn[m] = *(const u32x4*)(pn_ + o);
;         }
	s_waitcnt lgkmcnt(0)
	v_mfma_f32_16x16x32_bf16 v[64:67], v[132:135], v[148:151], v[64:67]
	v_mfma_f32_16x16x32_bf16 v[64:67], v[136:139], v[152:155], v[64:67]
	v_mfma_f32_16x16x32_bf16 v[56:59], v[132:135], v[156:159], v[56:59]
	v_mfma_f32_16x16x32_bf16 v[56:59], v[136:139], v[160:163], v[56:59]
	v_mfma_f32_16x16x32_bf16 v[48:51], v[132:135], v[182:185], v[48:51]
	v_mfma_f32_16x16x32_bf16 v[48:51], v[136:139], v[190:193], v[48:51]
	v_mfma_f32_16x16x32_bf16 v[40:43], v[132:135], v[194:197], v[40:43]
	v_mfma_f32_16x16x32_bf16 v[40:43], v[136:139], v[212:215], v[40:43]
	v_mfma_f32_16x16x32_bf16 v[60:63], v[140:143], v[148:151], v[60:63]
	v_mfma_f32_16x16x32_bf16 v[60:63], v[144:147], v[152:155], v[60:63]
	v_mfma_f32_16x16x32_bf16 v[52:55], v[140:143], v[156:159], v[52:55]
	v_mfma_f32_16x16x32_bf16 v[52:55], v[144:147], v[160:163], v[52:55]
	v_mfma_f32_16x16x32_bf16 v[44:47], v[140:143], v[182:185], v[44:47]
	v_mfma_f32_16x16x32_bf16 v[44:47], v[144:147], v[190:193], v[44:47]
	v_mfma_f32_16x16x32_bf16 v[36:39], v[140:143], v[194:197], v[36:39]
	v_mfma_f32_16x16x32_bf16 v[36:39], v[144:147], v[212:215], v[36:39]
	s_barrier
	s_setprio 0
	s_add_u32 s4, s4, 0x80080
	s_addc_u32 s5, s5, 0
	s_add_i32 s6, s6, s27
	v_lshl_add_u64 v[0:1], s[4:5], 0, v[172:173]
	s_mov_b32 m0, s6
	s_nop 0
	global_load_lds_dwordx4 v[0:1], off
	v_lshl_add_u64 v[0:1], s[4:5], 0, v[168:169]
	s_add_i32 m0, s6, 0x2000
	s_nop 0
	global_load_lds_dwordx4 v[0:1], off
	s_add_i32 s42, s42, 2
	s_add_u32 s33, s33, 0x100
	s_addc_u32 s41, s41, 0
	s_add_u32 s2, s2, 0x100
	s_addc_u32 s3, s3, 0
	s_waitcnt vmcnt(6)
	s_setprio 1
	s_barrier
	v_mfma_f32_16x16x32_bf16 v[32:35], v[216:219], v[148:151], v[32:35]
	v_mfma_f32_16x16x32_bf16 v[32:35], v[220:223], v[152:155], v[32:35]
	v_mfma_f32_16x16x32_bf16 v[24:27], v[216:219], v[156:159], v[24:27]
	v_mfma_f32_16x16x32_bf16 v[24:27], v[220:223], v[160:163], v[24:27]
	v_mfma_f32_16x16x32_bf16 v[16:19], v[216:219], v[182:185], v[16:19]
	v_mfma_f32_16x16x32_bf16 v[16:19], v[220:223], v[190:193], v[16:19]
	v_mfma_f32_16x16x32_bf16 v[8:11], v[216:219], v[194:197], v[8:11]
	v_mfma_f32_16x16x32_bf16 v[8:11], v[220:223], v[212:215], v[8:11]
	v_mfma_f32_16x16x32_bf16 v[28:31], v[224:227], v[148:151], v[28:31]
	v_mfma_f32_16x16x32_bf16 v[28:31], v[228:231], v[152:155], v[28:31]
	v_mfma_f32_16x16x32_bf16 v[20:23], v[224:227], v[156:159], v[20:23]
	v_mfma_f32_16x16x32_bf16 v[20:23], v[228:231], v[160:163], v[20:23]
	v_mfma_f32_16x16x32_bf16 v[12:15], v[224:227], v[182:185], v[12:15]
	v_mfma_f32_16x16x32_bf16 v[12:15], v[228:231], v[190:193], v[12:15]
	v_mfma_f32_16x16x32_bf16 v[4:7], v[224:227], v[194:197], v[4:7]
	v_mfma_f32_16x16x32_bf16 v[4:7], v[228:231], v[212:215], v[4:7]
	s_barrier
	s_setprio 0
	s_cmp_gt_u32 s42, 29
	s_cbranch_scc0 .LBB0_543
	s_cmp_gt_i32 s10, 1
	s_cselect_b64 s[6:7], -1, 0
	s_lshl_b32 s42, s10, 11
	s_add_i32 s2, s42, 0x4c00
	s_ashr_i32 s2, s2, 8
	s_add_i32 s2, s2, s11
	s_ashr_i32 s3, s2, 31
	s_min_i32 s1, s10, 1
	s_ashr_i32 s9, s8, 31
	s_lshl_b64 s[2:3], s[2:3], 23
	s_add_u32 s2, s34, s2
	s_addc_u32 s3, s35, s3
	s_lshl_b64 s[4:5], s[8:9], 17
	s_add_u32 s2, s2, s4
	s_addc_u32 s3, s3, s5
	s_lshl_b32 s1, s1, 11
	s_add_i32 s44, s1, 0x800
	s_addk_i32 s1, 0x5400
	s_ashr_i32 s1, s1, 8
	s_add_i32 s46, s1, s11
	s_ashr_i32 s47, s46, 31
	s_lshl_b64 s[46:47], s[46:47], 23
	s_add_u32 s1, s34, s46
	v_lshl_or_b32 v132, s11, 8, v187
	s_addc_u32 s11, s35, s47
	s_add_u32 s4, s1, s4
	s_addc_u32 s5, s11, s5
	s_ashr_i32 s43, s42, 31
	s_lshl_b64 s[8:9], s[8:9], 20
	s_ashr_i32 s45, s44, 31
	s_lshl_b64 s[42:43], s[42:43], 2
	s_add_u32 s42, s36, s42
	s_addc_u32 s43, s37, s43
	s_lshl_b64 s[44:45], s[44:45], 2
	s_add_u32 s44, s36, s44
	v_lshl_add_u64 v[0:1], v[176:177], 0, s[8:9]
	v_ashrrev_i32_e32 v133, 31, v132
	s_addc_u32 s45, s37, s45
	v_lshl_add_u64 v[0:1], v[132:133], 1, v[0:1]
	v_lshlrev_b64 v[132:133], 2, v[132:133]
	v_lshl_add_u64 v[182:183], s[42:43], 0, v[132:133]
	v_lshl_add_u64 v[184:185], s[44:45], 0, v[132:133]
	v_mov_b32_e32 v2, v186
	global_load_dwordx4 v[144:147], v[182:183], off
	global_load_dwordx4 v[136:139], v[182:183], off offset:16
	global_load_dwordx4 v[140:143], v[184:185], off
	global_load_dwordx4 v[132:135], v[184:185], off offset:16
	s_cmp_lt_i32 s10, 2
	v_lshlrev_b64 v[148:149], 1, v[2:3]
	v_lshl_add_u64 v[150:151], s[2:3], 0, v[148:149]
	v_lshl_add_u64 v[148:149], s[4:5], 0, v[148:149]
	flat_load_dwordx4 v[190:193], v[150:151]
	flat_load_dwordx4 v[160:163], v[148:149]
	v_add_u32_e32 v148, 0x1000, v2
	v_mov_b32_e32 v149, v3
	v_lshlrev_b64 v[148:149], 1, v[148:149]
	v_lshl_add_u64 v[150:151], s[2:3], 0, v[148:149]
	v_lshl_add_u64 v[148:149], s[4:5], 0, v[148:149]
	flat_load_dwordx4 v[194:197], v[150:151]
	flat_load_dwordx4 v[156:159], v[148:149]
	v_add_u32_e32 v148, 0x2000, v2
	v_mov_b32_e32 v149, v3
	v_lshlrev_b64 v[148:149], 1, v[148:149]
	v_lshl_add_u64 v[150:151], s[2:3], 0, v[148:149]
	v_lshl_add_u64 v[148:149], s[4:5], 0, v[148:149]
	v_add_u32_e32 v2, 0x3000, v2
	flat_load_dwordx4 v[234:237], v[150:151]
	flat_load_dwordx4 v[152:155], v[148:149]
	v_lshlrev_b64 v[148:149], 1, v[2:3]
	v_lshl_add_u64 v[150:151], s[2:3], 0, v[148:149]
	v_lshl_add_u64 v[148:149], s[4:5], 0, v[148:149]
	flat_load_dwordx4 v[238:241], v[150:151]
	s_nop 0
	flat_load_dwordx4 v[148:151], v[148:149]
	s_waitcnt vmcnt(0) lgkmcnt(0)
; __device__ __forceinline__ float sigmoidf_(float x) { return __builtin_amdgcn_rcpf(1.0f + __expf(-x)); }
;   __device__ __forceinline__ void operator()(EPI_ARGS) const {
;     ...
;             unpack8(zc[m], xc);
;             unpack8(zn[m], xn);
; #pragma unroll
;             for (int k = 0; k < 8; ++k) {
;               const float ec = __expf(-fmaxf(xc[k] + gc[k], -40.f)), en = __expf(-fmaxf(xn[k] + gn[k], -40.f));
;               const float f = (1.0f + en) * __builtin_amdgcn_rcpf(1.0f + ec);
;               acc[ai][bj][m][k >> 2][k & 3] *= f;
;             }
;           }
;         } else {
; #pragma unroll
;           for (int m = 0; m < 4; ++m) {
;             float xc[8], y[8];
;             unpack8(zc[m], xc);
; #pragma unroll
;             for (int k = 0; k < 8; ++k) y[k] = acc[ai][bj][m][k >> 2][k & 3] * sigmoidf_(fmaxf(xc[k] + gc[k], -40.f));
;             u32x4 o;
;             o.x = pack2(y[0], y[1]); o.y = pack2(y[2], y[3]); o.z = pack2(y[4], y[5]); o.w = pack2(y[6], y[7]);
;             *(u32x4*)(mrow + (size_t)(ai * HALF + m * 16) * DM + bj * HALF) = o;
	v_lshlrev_b32_e32 v2, 16, v190
	v_and_b32_e32 v189, 0xffff0000, v190
	v_lshlrev_b32_e32 v190, 16, v191
	v_and_b32_e32 v191, 0xffff0000, v191
	v_lshlrev_b32_e32 v212, 16, v192
	v_and_b32_e32 v192, 0xffff0000, v192
	v_lshlrev_b32_e32 v213, 16, v193
	v_and_b32_e32 v193, 0xffff0000, v193
	v_add_f32_e32 v2, v144, v2
	v_add_f32_e32 v189, v145, v189
	v_add_f32_e32 v190, v146, v190
	v_add_f32_e32 v191, v147, v191
	v_add_f32_e32 v212, v136, v212
	v_add_f32_e32 v192, v137, v192
	v_add_f32_e32 v213, v138, v213
	v_add_f32_e32 v193, v139, v193
	s_mov_b64 s[8:9], -1
	v_max_f32_e32 v233, 0xc2200000, v2
	v_max_f32_e32 v232, 0xc2200000, v189
	v_max_f32_e32 v231, 0xc2200000, v190
	v_max_f32_e32 v230, 0xc2200000, v191
	v_max_f32_e32 v229, 0xc2200000, v212
	v_max_f32_e32 v228, 0xc2200000, v192
	v_max_f32_e32 v227, 0xc2200000, v213
	v_max_f32_e32 v226, 0xc2200000, v193
	v_lshlrev_b32_e32 v225, 16, v194
	v_and_b32_e32 v224, 0xffff0000, v194
	v_lshlrev_b32_e32 v223, 16, v195
	v_and_b32_e32 v222, 0xffff0000, v195
	v_lshlrev_b32_e32 v221, 16, v196
	v_and_b32_e32 v220, 0xffff0000, v196
	v_lshlrev_b32_e32 v219, 16, v197
	v_and_b32_e32 v218, 0xffff0000, v197
	v_lshlrev_b32_e32 v217, 16, v234
	v_and_b32_e32 v216, 0xffff0000, v234
	v_lshlrev_b32_e32 v215, 16, v235
	v_and_b32_e32 v214, 0xffff0000, v235
	v_lshlrev_b32_e32 v213, 16, v236
	v_and_b32_e32 v212, 0xffff0000, v236
	v_lshlrev_b32_e32 v197, 16, v237
	v_and_b32_e32 v196, 0xffff0000, v237
	v_lshlrev_b32_e32 v195, 16, v238
	v_and_b32_e32 v194, 0xffff0000, v238
	v_lshlrev_b32_e32 v193, 16, v239
	v_and_b32_e32 v192, 0xffff0000, v239
	v_lshlrev_b32_e32 v191, 16, v240
	v_and_b32_e32 v190, 0xffff0000, v240
	v_lshlrev_b32_e32 v189, 16, v241
	v_and_b32_e32 v2, 0xffff0000, v241
	s_cbranch_scc1 .LBB0_546
	v_mul_f32_e32 v234, 0xbfb8aa3b, v233
	v_mul_f32_e32 v235, 0xbfb8aa3b, v232
	v_mul_f32_e32 v236, 0xbfb8aa3b, v231
	v_exp_f32_e32 v234, v234
	v_exp_f32_e32 v235, v235
	v_exp_f32_e32 v236, v236
	v_mul_f32_e32 v237, 0xbfb8aa3b, v230
	v_exp_f32_e32 v237, v237
	v_mul_f32_e32 v238, 0xbfb8aa3b, v229
	v_mul_f32_e32 v239, 0xbfb8aa3b, v228
	v_add_f32_e32 v234, 1.0, v234
	v_add_f32_e32 v235, 1.0, v235
	v_add_f32_e32 v236, 1.0, v236
	v_exp_f32_e32 v238, v238
	v_exp_f32_e32 v239, v239
	v_mul_f32_e32 v240, 0xbfb8aa3b, v227
	v_mul_f32_e32 v241, 0xbfb8aa3b, v226
	v_rcp_f32_e32 v234, v234
	v_rcp_f32_e32 v235, v235
	v_rcp_f32_e32 v236, v236
	v_add_f32_e32 v237, 1.0, v237
	v_exp_f32_e32 v240, v240
	v_exp_f32_e32 v241, v241
	v_rcp_f32_e32 v237, v237
	v_add_f32_e32 v238, 1.0, v238
	v_add_f32_e32 v239, 1.0, v239
	v_mul_f32_e32 v234, v128, v234
	v_mul_f32_e32 v235, v129, v235
	v_mul_f32_e32 v236, v130, v236
	v_rcp_f32_e32 v238, v238
	v_rcp_f32_e32 v239, v239
	v_add_f32_e32 v240, 1.0, v240
	v_add_f32_e32 v241, 1.0, v241
	v_mul_f32_e32 v237, v131, v237
	v_rcp_f32_e32 v240, v240
	v_rcp_f32_e32 v241, v241
	v_cvt_pk_bf16_f32 v234, v234, v235
	v_cvt_pk_bf16_f32 v235, v236, v237
	v_add_f32_e32 v236, v144, v225
	v_max_f32_e32 v236, 0xc2200000, v236
	v_mul_f32_e32 v236, 0xbfb8aa3b, v236
	v_mul_f32_e32 v238, v124, v238
	v_mul_f32_e32 v239, v125, v239
	v_exp_f32_e32 v242, v236
	v_cvt_pk_bf16_f32 v236, v238, v239
	v_mul_f32_e32 v240, v126, v240
	v_mul_f32_e32 v241, v127, v241
	v_cvt_pk_bf16_f32 v237, v240, v241
	flat_store_dwordx4 v[0:1], v[234:237]
	v_add_f32_e32 v238, v136, v221
	v_max_f32_e32 v238, 0xc2200000, v238
	v_add_f32_e32 v235, v145, v224
	v_add_f32_e32 v236, v146, v223
	v_max_f32_e32 v235, 0xc2200000, v235
	v_max_f32_e32 v236, 0xc2200000, v236
	v_add_f32_e32 v237, v147, v222
	v_add_f32_e32 v239, v137, v220
	v_mul_f32_e32 v235, 0xbfb8aa3b, v235
	v_mul_f32_e32 v236, 0xbfb8aa3b, v236
	v_max_f32_e32 v237, 0xc2200000, v237
	v_mul_f32_e32 v238, 0xbfb8aa3b, v238
	v_max_f32_e32 v239, 0xc2200000, v239
	v_exp_f32_e32 v235, v235
	v_exp_f32_e32 v236, v236
	v_mul_f32_e32 v237, 0xbfb8aa3b, v237
	v_exp_f32_e32 v238, v238
	v_mul_f32_e32 v239, 0xbfb8aa3b, v239
	v_add_f32_e32 v240, v138, v219
	v_exp_f32_e32 v237, v237
	v_exp_f32_e32 v239, v239
	v_max_f32_e32 v240, 0xc2200000, v240
	v_add_f32_e32 v241, v139, v218
	v_mul_f32_e32 v240, 0xbfb8aa3b, v240
	v_max_f32_e32 v241, 0xc2200000, v241
	v_exp_f32_e32 v240, v240
	v_mul_f32_e32 v241, 0xbfb8aa3b, v241
	v_add_f32_e32 v234, 1.0, v242
	v_add_f32_e32 v235, 1.0, v235
	v_add_f32_e32 v236, 1.0, v236
	v_add_f32_e32 v238, 1.0, v238
	v_exp_f32_e32 v241, v241
	v_rcp_f32_e32 v234, v234
	v_rcp_f32_e32 v235, v235
	v_rcp_f32_e32 v236, v236
	v_add_f32_e32 v237, 1.0, v237
	v_rcp_f32_e32 v238, v238
	v_add_f32_e32 v239, 1.0, v239
	v_rcp_f32_e32 v237, v237
	v_rcp_f32_e32 v239, v239
	v_add_f32_e32 v240, 1.0, v240
	v_rcp_f32_e32 v240, v240
	v_add_f32_e32 v241, 1.0, v241
	v_mul_f32_e32 v234, v120, v234
; __device__ __forceinline__ float sigmoidf_(float x) { return __builtin_amdgcn_rcpf(1.0f + __expf(-x)); }
;   __device__ __forceinline__ void operator()(EPI_ARGS) const {
;     ...
;           for (int m = 0; m < 4; ++m) {
;             float xc[8], y[8];
;             unpack8(zc[m], xc);
; #pragma unroll
;             for (int k = 0; k < 8; ++k) y[k] = acc[ai][bj][m][k >> 2][k & 3] * sigmoidf_(fmaxf(xc[k] + gc[k], -40.f));
;             u32x4 o;
;             o.x = pack2(y[0], y[1]); o.y = pack2(y[2], y[3]); o.z = pack2(y[4], y[5]); o.w = pack2(y[6], y[7]);
;             *(u32x4*)(mrow + (size_t)(ai * HALF + m * 16) * DM + bj * HALF) = o;
;           }
	v_mul_f32_e32 v235, v121, v235
	v_mul_f32_e32 v236, v122, v236
	v_rcp_f32_e32 v241, v241
	v_mul_f32_e32 v238, v116, v238
	v_mul_f32_e32 v237, v123, v237
	v_mul_f32_e32 v239, v117, v239
	v_cvt_pk_bf16_f32 v234, v234, v235
	v_cvt_pk_bf16_f32 v235, v236, v237
	v_cvt_pk_bf16_f32 v236, v238, v239
	v_add_f32_e32 v238, v144, v217
	v_max_f32_e32 v238, 0xc2200000, v238
	v_mul_f32_e32 v240, v118, v240
	v_mul_f32_e32 v238, 0xbfb8aa3b, v238
	v_mul_f32_e32 v241, v119, v241
	v_cvt_pk_bf16_f32 v237, v240, v241
	v_exp_f32_e32 v240, v238
	v_add_co_u32_e32 v238, vcc, s67, v0
	v_add_f32_e32 v241, v139, v196
	s_nop 0
	v_addc_co_u32_e32 v239, vcc, 0, v1, vcc
	flat_store_dwordx4 v[238:239], v[234:237]
	v_add_f32_e32 v238, v136, v213
	v_max_f32_e32 v238, 0xc2200000, v238
	v_add_f32_e32 v235, v145, v216
	v_add_f32_e32 v236, v146, v215
	v_max_f32_e32 v235, 0xc2200000, v235
	v_max_f32_e32 v236, 0xc2200000, v236
	v_add_f32_e32 v237, v147, v214
	v_add_f32_e32 v239, v137, v212
	v_mul_f32_e32 v235, 0xbfb8aa3b, v235
	v_mul_f32_e32 v236, 0xbfb8aa3b, v236
	v_max_f32_e32 v237, 0xc2200000, v237
	v_mul_f32_e32 v238, 0xbfb8aa3b, v238
	v_max_f32_e32 v239, 0xc2200000, v239
	v_add_f32_e32 v234, 1.0, v240
	v_exp_f32_e32 v235, v235
	v_exp_f32_e32 v236, v236
	v_mul_f32_e32 v237, 0xbfb8aa3b, v237
	v_exp_f32_e32 v238, v238
	v_mul_f32_e32 v239, 0xbfb8aa3b, v239
	v_add_f32_e32 v240, v138, v197
	v_exp_f32_e32 v237, v237
	v_exp_f32_e32 v239, v239
	v_max_f32_e32 v240, 0xc2200000, v240
	v_mul_f32_e32 v240, 0xbfb8aa3b, v240
	v_max_f32_e32 v241, 0xc2200000, v241
	v_exp_f32_e32 v240, v240
	v_mul_f32_e32 v241, 0xbfb8aa3b, v241
	v_add_f32_e32 v235, 1.0, v235
	v_add_f32_e32 v236, 1.0, v236
	v_add_f32_e32 v238, 1.0, v238
	v_exp_f32_e32 v241, v241
	v_rcp_f32_e32 v234, v234
	v_rcp_f32_e32 v235, v235
	v_rcp_f32_e32 v236, v236
	v_add_f32_e32 v237, 1.0, v237
	v_rcp_f32_e32 v238, v238
	v_add_f32_e32 v239, 1.0, v239
	v_rcp_f32_e32 v237, v237
	v_rcp_f32_e32 v239, v239
	v_add_f32_e32 v240, 1.0, v240
	v_rcp_f32_e32 v240, v240
	v_add_f32_e32 v241, 1.0, v241
	v_mul_f32_e32 v234, v112, v234
	v_mul_f32_e32 v235, v113, v235
	v_mul_f32_e32 v236, v114, v236
	v_rcp_f32_e32 v241, v241
	v_mul_f32_e32 v238, v108, v238
	v_mul_f32_e32 v237, v115, v237
	v_mul_f32_e32 v239, v109, v239
	v_cvt_pk_bf16_f32 v234, v234, v235
	v_cvt_pk_bf16_f32 v235, v236, v237
	v_cvt_pk_bf16_f32 v236, v238, v239
	v_add_f32_e32 v238, v144, v195
	v_max_f32_e32 v238, 0xc2200000, v238
	v_mul_f32_e32 v240, v110, v240
	v_mul_f32_e32 v238, 0xbfb8aa3b, v238
	s_mov_b32 s1, 0x20000
	v_mul_f32_e32 v241, v111, v241
	v_cvt_pk_bf16_f32 v237, v240, v241
	v_exp_f32_e32 v240, v238
	v_add_co_u32_e32 v238, vcc, s1, v0
	v_add_f32_e32 v241, v139, v2
	s_nop 0
	v_addc_co_u32_e32 v239, vcc, 0, v1, vcc
	flat_store_dwordx4 v[238:239], v[234:237]
	v_add_f32_e32 v238, v136, v191
	v_max_f32_e32 v238, 0xc2200000, v238
	v_add_f32_e32 v235, v145, v194
	v_add_f32_e32 v236, v146, v193
	v_max_f32_e32 v235, 0xc2200000, v235
	v_max_f32_e32 v236, 0xc2200000, v236
	v_add_f32_e32 v237, v147, v192
	v_add_f32_e32 v239, v137, v190
	v_mul_f32_e32 v235, 0xbfb8aa3b, v235
	v_mul_f32_e32 v236, 0xbfb8aa3b, v236
	v_max_f32_e32 v237, 0xc2200000, v237
	v_mul_f32_e32 v238, 0xbfb8aa3b, v238
	v_max_f32_e32 v239, 0xc2200000, v239
	v_add_f32_e32 v234, 1.0, v240
	v_exp_f32_e32 v235, v235
	v_exp_f32_e32 v236, v236
	v_mul_f32_e32 v237, 0xbfb8aa3b, v237
	v_exp_f32_e32 v238, v238
	v_mul_f32_e32 v239, 0xbfb8aa3b, v239
	v_add_f32_e32 v240, v138, v189
	v_exp_f32_e32 v237, v237
	v_exp_f32_e32 v239, v239
	v_max_f32_e32 v240, 0xc2200000, v240
	v_max_f32_e32 v241, 0xc2200000, v241
	v_mul_f32_e32 v240, 0xbfb8aa3b, v240
	v_mul_f32_e32 v241, 0xbfb8aa3b, v241
	v_exp_f32_e32 v240, v240
	v_exp_f32_e32 v241, v241
	v_add_f32_e32 v235, 1.0, v235
	v_add_f32_e32 v236, 1.0, v236
	v_add_f32_e32 v238, 1.0, v238
	v_rcp_f32_e32 v234, v234
	v_rcp_f32_e32 v235, v235
	v_rcp_f32_e32 v236, v236
	v_add_f32_e32 v237, 1.0, v237
	v_rcp_f32_e32 v238, v238
	v_add_f32_e32 v239, 1.0, v239
	v_rcp_f32_e32 v237, v237
	v_rcp_f32_e32 v239, v239
	v_add_f32_e32 v240, 1.0, v240
	v_add_f32_e32 v241, 1.0, v241
	v_rcp_f32_e32 v240, v240
	v_rcp_f32_e32 v241, v241
	v_mul_f32_e32 v234, v104, v234
	v_mul_f32_e32 v235, v105, v235
	v_mul_f32_e32 v236, v106, v236
	v_mul_f32_e32 v238, v100, v238
	v_mul_f32_e32 v237, v107, v237
	v_mul_f32_e32 v239, v101, v239
	v_cvt_pk_bf16_f32 v234, v234, v235
	v_cvt_pk_bf16_f32 v235, v236, v237
	v_cvt_pk_bf16_f32 v236, v238, v239
	v_add_co_u32_e32 v238, vcc, 0x30000, v0
	s_mov_b64 s[8:9], 0
	s_nop 0
	v_addc_co_u32_e32 v239, vcc, 0, v1, vcc
	v_mul_f32_e32 v240, v102, v240
	v_mul_f32_e32 v241, v103, v241
	v_cvt_pk_bf16_f32 v237, v240, v241
	flat_store_dwordx4 v[238:239], v[234:237]

; #define PG8_WAIT_L(n) asm volatile("s_waitcnt lgkmcnt(" #n ")" ::: "memory")
; #define PG8_BAR __builtin_amdgcn_s_barrier()
; #define PG8_SCHED __builtin_amdgcn_sched_barrier(0)
; template <class Epi, class AddrA, class AddrB>
; __device__ __forceinline__ void gemm_phase(const Sched S, const int lda, const int ldb, const int K, const AddrA addrA,
;                                            const AddrB addrB, const Epi E) {
;     ...
;     const bool has_next = S.next(ui + 1, nxt);
;     const char* nA = has_next ? addrA(nxt) : cA;
;     const char* nB = has_next ? addrB(nxt) : cB;
;     for (int t = 0; t < nt; t += 2) {
;       const bool last = (t == nt - 2);
;       const char* a1 = cA + (size_t)(t + 1) * kstep;
;       const char* a2 = last ? nA : cA + (size_t)(t + 2) * kstep;
;       const char* b2 = last ? nB : cB + (size_t)(t + 2) * kstep;
;       const char* a3 = a2 + kstep;
;       const char* b3 = b2 + kstep;
;       PG8_LDB(B0, 0, 0); PG8_SCHED; PG8_LDA(At, 0, 0); PG8_STAGE(PG8_SA(1, 1), a1 + hstepA, voffA);
;       PG8_WAIT_L(8); PG8_BAR; PG8_WAIT_L(0); PG8_MMA(0, 0, At, B0); PG8_BAR; PG8_SCHED;
;       PG8_LDB(B1, 0, 1); PG8_STAGE(PG8_SB(0, 0), b2, voffB);
;       PG8_BAR; PG8_WAIT_L(0); PG8_MMA(0, 1, At, B1); PG8_BAR;
;       PG8_LDA(At, 0, 1); PG8_STAGE(PG8_SA(0, 0), a2, voffA);
;       PG8_BAR; PG8_WAIT_L(0); PG8_MMA(1, 0, At, B0); PG8_BAR; PG8_SCHED;
.LBB0_618:
	s_ashr_i32 s3, s2, 31
	s_lshl_b64 s[8:9], s[2:3], 20
	s_add_u32 s8, s23, s8
	s_addc_u32 s9, s24, s9
	s_and_b64 s[10:11], s[18:19], exec
	s_cselect_b32 s3, s9, s17
	s_cselect_b32 s13, s8, s16
	s_ashr_i32 s5, s4, 31
	s_lshl_b64 s[10:11], s[4:5], 20
	s_add_u32 s10, s21, s10
	s_addc_u32 s11, s22, s11
	s_and_b64 s[18:19], s[18:19], exec
	s_cselect_b32 s5, s11, s15
	s_cselect_b32 s35, s10, s14
	s_add_u32 s36, s14, 0x100
	s_addc_u32 s37, s15, 0
	s_add_u32 s14, s16, 0x80080
	s_addc_u32 s15, s17, 0
	s_mov_b32 s38, -2
	s_add_i32 s39, 0, 0x10000
	v_add_u32_e32 v142, s39, v144
	ds_read_b128 v[148:151], v142
	ds_read_b128 v[152:155], v142 offset:1024
	ds_read_b128 v[156:159], v142 offset:2048
	ds_read_b128 v[160:163], v142 offset:3072
	v_lshl_add_u64 v[142:143], s[14:15], 0, v[140:141]
	s_add_i32 m0, s26, 0xc000
	ds_read_b128 v[168:171], v146
	ds_read_b128 v[172:175], v146 offset:1024
	ds_read_b128 v[176:179], v146 offset:2048
	ds_read_b128 v[180:183], v146 offset:3072
	ds_read_b128 v[184:187], v146 offset:4096
	ds_read_b128 v[188:191], v146 offset:5120
	ds_read_b128 v[192:195], v146 offset:6144
	ds_read_b128 v[212:215], v146 offset:7168
	global_load_lds_dwordx4 v[142:143], off
	v_lshl_add_u64 v[142:143], s[14:15], 0, v[138:139]
	s_add_i32 m0, s26, 0xe000
	s_nop 0
	global_load_lds_dwordx4 v[142:143], off
	s_waitcnt lgkmcnt(8)
	s_setprio 1
	s_barrier
	s_waitcnt lgkmcnt(0)
	v_mfma_f32_16x16x32_bf16 v[128:131], v[148:151], v[168:171], 0
	v_mfma_f32_16x16x32_bf16 v[128:131], v[152:155], v[172:175], v[128:131]
	v_mfma_f32_16x16x32_bf16 v[120:123], v[148:151], v[176:179], 0
	v_mfma_f32_16x16x32_bf16 v[120:123], v[152:155], v[180:183], v[120:123]
	v_mfma_f32_16x16x32_bf16 v[112:115], v[148:151], v[184:187], 0
	v_mfma_f32_16x16x32_bf16 v[112:115], v[152:155], v[188:191], v[112:115]
	v_mfma_f32_16x16x32_bf16 v[104:107], v[148:151], v[192:195], 0
	v_mfma_f32_16x16x32_bf16 v[104:107], v[152:155], v[212:215], v[104:107]
	v_mfma_f32_16x16x32_bf16 v[124:127], v[156:159], v[168:171], 0
	v_mfma_f32_16x16x32_bf16 v[124:127], v[160:163], v[172:175], v[124:127]
	v_mfma_f32_16x16x32_bf16 v[116:119], v[156:159], v[176:179], 0
	v_mfma_f32_16x16x32_bf16 v[116:119], v[160:163], v[180:183], v[116:119]
	v_mfma_f32_16x16x32_bf16 v[108:111], v[156:159], v[184:187], 0
	v_mfma_f32_16x16x32_bf16 v[108:111], v[160:163], v[188:191], v[108:111]
	v_mfma_f32_16x16x32_bf16 v[100:103], v[156:159], v[192:195], 0
	v_mfma_f32_16x16x32_bf16 v[100:103], v[160:163], v[212:215], v[100:103]
	s_barrier
	s_setprio 0
	s_add_u32 s16, s14, 0xfff80080
	s_addc_u32 s17, s15, -1
	s_cmp_eq_u32 s38, 28
	s_cselect_b32 s19, s3, s17
	s_cselect_b32 s18, s13, s16
	s_cselect_b32 s17, s5, s37
	s_cselect_b32 s16, s35, s36
	s_add_i32 s42, 0, 0x14000
	v_add_u32_e32 v142, s42, v144
	s_add_i32 s39, s39, s25
	ds_read_b128 v[216:219], v142
	ds_read_b128 v[220:223], v142 offset:1024
	ds_read_b128 v[224:227], v142 offset:2048
	ds_read_b128 v[228:231], v142 offset:3072
	v_lshl_add_u64 v[142:143], s[16:17], 0, v[2:3]
	s_mov_b32 m0, s39
	v_lshl_add_u64 v[196:197], s[16:17], 0, v[0:1]
	global_load_lds_dwordx4 v[142:143], off
	s_add_i32 m0, s39, 0x2000
	s_nop 0
	global_load_lds_dwordx4 v[196:197], off
	s_setprio 1
	s_barrier
	s_waitcnt lgkmcnt(0)
	v_mfma_f32_16x16x32_bf16 v[96:99], v[216:219], v[168:171], 0
	v_mfma_f32_16x16x32_bf16 v[96:99], v[220:223], v[172:175], v[96:99]
	v_mfma_f32_16x16x32_bf16 v[88:91], v[216:219], v[176:179], 0
	v_mfma_f32_16x16x32_bf16 v[88:91], v[220:223], v[180:183], v[88:91]
	v_mfma_f32_16x16x32_bf16 v[80:83], v[216:219], v[184:187], 0
	v_mfma_f32_16x16x32_bf16 v[80:83], v[220:223], v[188:191], v[80:83]
	v_mfma_f32_16x16x32_bf16 v[72:75], v[216:219], v[192:195], 0
	v_mfma_f32_16x16x32_bf16 v[72:75], v[220:223], v[212:215], v[72:75]
	v_mfma_f32_16x16x32_bf16 v[92:95], v[224:227], v[168:171], 0
	v_mfma_f32_16x16x32_bf16 v[92:95], v[228:231], v[172:175], v[92:95]
	v_mfma_f32_16x16x32_bf16 v[84:87], v[224:227], v[176:179], 0
	v_mfma_f32_16x16x32_bf16 v[84:87], v[228:231], v[180:183], v[84:87]
	v_mfma_f32_16x16x32_bf16 v[76:79], v[224:227], v[184:187], 0
	v_mfma_f32_16x16x32_bf16 v[76:79], v[228:231], v[188:191], v[76:79]
	v_mfma_f32_16x16x32_bf16 v[68:71], v[224:227], v[192:195], 0
	v_mfma_f32_16x16x32_bf16 v[68:71], v[228:231], v[212:215], v[68:71]
	s_barrier
	s_setprio 0
	s_mov_b32 m0, s26
	v_lshl_add_u64 v[232:233], s[18:19], 0, v[134:135]
	ds_read_b128 v[168:171], v146 offset:16384
	ds_read_b128 v[172:175], v146 offset:17408
	ds_read_b128 v[176:179], v146 offset:18432
	ds_read_b128 v[180:183], v146 offset:19456
	ds_read_b128 v[184:187], v146 offset:20480
	ds_read_b128 v[188:191], v146 offset:21504
	ds_read_b128 v[192:195], v146 offset:22528
	ds_read_b128 v[212:215], v146 offset:23552
	global_load_lds_dwordx4 v[232:233], off
	v_lshl_add_u64 v[234:235], s[18:19], 0, v[132:133]
	s_mov_b32 m0, s27
	s_nop 0
	global_load_lds_dwordx4 v[234:235], off
	s_setprio 1
	s_barrier
	s_waitcnt lgkmcnt(0)
	v_mfma_f32_16x16x32_bf16 v[64:67], v[148:151], v[168:171], 0
	v_mfma_f32_16x16x32_bf16 v[64:67], v[152:155], v[172:175], v[64:67]
	v_mfma_f32_16x16x32_bf16 v[56:59], v[148:151], v[176:179], 0
	v_mfma_f32_16x16x32_bf16 v[56:59], v[152:155], v[180:183], v[56:59]
	v_mfma_f32_16x16x32_bf16 v[48:51], v[148:151], v[184:187], 0
	v_mfma_f32_16x16x32_bf16 v[48:51], v[152:155], v[188:191], v[48:51]
	v_mfma_f32_16x16x32_bf16 v[40:43], v[148:151], v[192:195], 0
	v_mfma_f32_16x16x32_bf16 v[40:43], v[152:155], v[212:215], v[40:43]
	v_mfma_f32_16x16x32_bf16 v[60:63], v[156:159], v[168:171], 0
	v_mfma_f32_16x16x32_bf16 v[60:63], v[160:163], v[172:175], v[60:63]
	v_mfma_f32_16x16x32_bf16 v[52:55], v[156:159], v[176:179], 0
	v_mfma_f32_16x16x32_bf16 v[52:55], v[160:163], v[180:183], v[52:55]
	v_mfma_f32_16x16x32_bf16 v[44:47], v[156:159], v[184:187], 0
	v_mfma_f32_16x16x32_bf16 v[44:47], v[160:163], v[188:191], v[44:47]
	v_mfma_f32_16x16x32_bf16 v[36:39], v[156:159], v[192:195], 0
	v_mfma_f32_16x16x32_bf16 v[36:39], v[160:163], v[212:215], v[36:39]
	s_barrier
; #define PG8_WAIT_V(n) asm volatile("s_waitcnt vmcnt(" #n ")" ::: "memory")
; #define PG8_WAIT_L(n) asm volatile("s_waitcnt lgkmcnt(" #n ")" ::: "memory")
; #define PG8_BAR __builtin_amdgcn_s_barrier()
; #define PG8_SCHED __builtin_amdgcn_sched_barrier(0)
; template <class Epi, class AddrA, class AddrB>
; __device__ __forceinline__ void gemm_phase(const Sched S, const int lda, const int ldb, const int K, const AddrA addrA,
;                                            const AddrB addrB, const Epi E) {
;     ...
;       PG8_BAR; PG8_WAIT_L(0); PG8_MMA(1, 0, At, B0); PG8_BAR; PG8_SCHED;
;       PG8_STAGE(PG8_SB(0, 1), b2 + hstepB, voffB);
;       PG8_WAIT_V(6); PG8_BAR; PG8_MMA(1, 1, At, B1); PG8_BAR;
;       PG8_LDB(B0, 1, 0); PG8_SCHED; PG8_LDA(At, 1, 0); PG8_STAGE(PG8_SA(0, 1), a2 + hstepA, voffA);
;       PG8_WAIT_L(8); PG8_BAR; PG8_WAIT_L(0); PG8_MMA(0, 0, At, B0); PG8_BAR; PG8_SCHED;
;       PG8_LDB(B1, 1, 1); PG8_STAGE(PG8_SB(1, 0), b3, voffB);
;       PG8_BAR; PG8_WAIT_L(0); PG8_MMA(0, 1, At, B1); PG8_BAR;
;       PG8_LDA(At, 1, 1); PG8_STAGE(PG8_SA(1, 0), a3, voffA);
;       PG8_BAR; PG8_WAIT_L(0); PG8_MMA(1, 0, At, B0); PG8_BAR; PG8_SCHED;
	s_setprio 0
	s_add_u32 s40, s16, 0x80000
	s_addc_u32 s41, s17, 0
	s_add_i32 s39, s42, s25
	v_lshl_add_u64 v[148:149], s[40:41], 0, v[2:3]
	s_mov_b32 m0, s39
	s_nop 0
	global_load_lds_dwordx4 v[148:149], off
	v_lshl_add_u64 v[148:149], s[40:41], 0, v[0:1]
	s_add_i32 m0, s39, 0x2000
	s_nop 0
	global_load_lds_dwordx4 v[148:149], off
	s_waitcnt vmcnt(6)
	s_setprio 1
	s_barrier
	v_mfma_f32_16x16x32_bf16 v[32:35], v[216:219], v[168:171], 0
	v_mfma_f32_16x16x32_bf16 v[32:35], v[220:223], v[172:175], v[32:35]
	v_mfma_f32_16x16x32_bf16 v[24:27], v[216:219], v[176:179], 0
	v_mfma_f32_16x16x32_bf16 v[24:27], v[220:223], v[180:183], v[24:27]
	v_mfma_f32_16x16x32_bf16 v[16:19], v[216:219], v[184:187], 0
	v_mfma_f32_16x16x32_bf16 v[16:19], v[220:223], v[188:191], v[16:19]
	v_mfma_f32_16x16x32_bf16 v[8:11], v[216:219], v[192:195], 0
	v_mfma_f32_16x16x32_bf16 v[8:11], v[220:223], v[212:215], v[8:11]
	v_mfma_f32_16x16x32_bf16 v[28:31], v[224:227], v[168:171], 0
	v_mfma_f32_16x16x32_bf16 v[28:31], v[228:231], v[172:175], v[28:31]
	v_mfma_f32_16x16x32_bf16 v[20:23], v[224:227], v[176:179], 0
	v_mfma_f32_16x16x32_bf16 v[20:23], v[228:231], v[180:183], v[20:23]
	v_mfma_f32_16x16x32_bf16 v[12:15], v[224:227], v[184:187], 0
	v_mfma_f32_16x16x32_bf16 v[12:15], v[228:231], v[188:191], v[12:15]
	v_mfma_f32_16x16x32_bf16 v[4:7], v[224:227], v[192:195], 0
	v_mfma_f32_16x16x32_bf16 v[4:7], v[228:231], v[212:215], v[4:7]
	s_barrier
	s_setprio 0
	s_add_i32 s39, 0, 0x18000
	v_add_u32_e32 v147, s39, v144
	ds_read_b128 v[148:151], v147
	ds_read_b128 v[152:155], v147 offset:1024
	ds_read_b128 v[156:159], v147 offset:2048
	ds_read_b128 v[160:163], v147 offset:3072
	s_add_u32 s18, s18, 0x80000
	s_addc_u32 s19, s19, 0
	s_mov_b32 m0, s28
	v_lshl_add_u64 v[216:217], s[18:19], 0, v[134:135]
	ds_read_b128 v[168:171], v146 offset:32768
	ds_read_b128 v[172:175], v146 offset:33792
	ds_read_b128 v[176:179], v146 offset:34816
	ds_read_b128 v[180:183], v146 offset:35840
	ds_read_b128 v[184:187], v146 offset:36864
	ds_read_b128 v[188:191], v146 offset:37888
	ds_read_b128 v[192:195], v146 offset:38912
	ds_read_b128 v[212:215], v146 offset:39936
	global_load_lds_dwordx4 v[216:217], off
	v_lshl_add_u64 v[216:217], s[18:19], 0, v[132:133]
	s_mov_b32 m0, s29
	s_nop 0
	global_load_lds_dwordx4 v[216:217], off
	s_waitcnt lgkmcnt(8)
	s_setprio 1
	s_barrier
	s_waitcnt lgkmcnt(0)
	v_mfma_f32_16x16x32_bf16 v[128:131], v[148:151], v[168:171], v[128:131]
	v_mfma_f32_16x16x32_bf16 v[128:131], v[152:155], v[172:175], v[128:131]
	v_mfma_f32_16x16x32_bf16 v[120:123], v[148:151], v[176:179], v[120:123]
	v_mfma_f32_16x16x32_bf16 v[120:123], v[152:155], v[180:183], v[120:123]
	v_mfma_f32_16x16x32_bf16 v[112:115], v[148:151], v[184:187], v[112:115]
	v_mfma_f32_16x16x32_bf16 v[112:115], v[152:155], v[188:191], v[112:115]
	v_mfma_f32_16x16x32_bf16 v[104:107], v[148:151], v[192:195], v[104:107]
	v_mfma_f32_16x16x32_bf16 v[104:107], v[152:155], v[212:215], v[104:107]
	v_mfma_f32_16x16x32_bf16 v[124:127], v[156:159], v[168:171], v[124:127]
	v_mfma_f32_16x16x32_bf16 v[124:127], v[160:163], v[172:175], v[124:127]
	v_mfma_f32_16x16x32_bf16 v[116:119], v[156:159], v[176:179], v[116:119]
	v_mfma_f32_16x16x32_bf16 v[116:119], v[160:163], v[180:183], v[116:119]
	v_mfma_f32_16x16x32_bf16 v[108:111], v[156:159], v[184:187], v[108:111]
	v_mfma_f32_16x16x32_bf16 v[108:111], v[160:163], v[188:191], v[108:111]
	v_mfma_f32_16x16x32_bf16 v[100:103], v[156:159], v[192:195], v[100:103]
	v_mfma_f32_16x16x32_bf16 v[100:103], v[160:163], v[212:215], v[100:103]
	s_barrier
	s_setprio 0
	s_add_i32 s18, 0, 0x1c000
	s_add_i32 s19, s39, s25
	v_add_u32_e32 v147, s18, v144
	v_lshl_add_u64 v[142:143], v[142:143], 0, s[52:53]
	s_mov_b32 m0, s19
	ds_read_b128 v[216:219], v147
	ds_read_b128 v[220:223], v147 offset:1024
	ds_read_b128 v[224:227], v147 offset:2048
	ds_read_b128 v[228:231], v147 offset:3072
	global_load_lds_dwordx4 v[142:143], off
	v_lshl_add_u64 v[142:143], v[196:197], 0, s[52:53]
	s_add_i32 m0, s19, 0x2000
	s_nop 0
	global_load_lds_dwordx4 v[142:143], off
	s_setprio 1
	s_barrier
	s_waitcnt lgkmcnt(0)
	v_mfma_f32_16x16x32_bf16 v[96:99], v[216:219], v[168:171], v[96:99]
	v_mfma_f32_16x16x32_bf16 v[96:99], v[220:223], v[172:175], v[96:99]
	v_mfma_f32_16x16x32_bf16 v[88:91], v[216:219], v[176:179], v[88:91]
	v_mfma_f32_16x16x32_bf16 v[88:91], v[220:223], v[180:183], v[88:91]
	v_mfma_f32_16x16x32_bf16 v[80:83], v[216:219], v[184:187], v[80:83]
	v_mfma_f32_16x16x32_bf16 v[80:83], v[220:223], v[188:191], v[80:83]
	v_mfma_f32_16x16x32_bf16 v[72:75], v[216:219], v[192:195], v[72:75]
	v_mfma_f32_16x16x32_bf16 v[72:75], v[220:223], v[212:215], v[72:75]
	v_mfma_f32_16x16x32_bf16 v[92:95], v[224:227], v[168:171], v[92:95]
	v_mfma_f32_16x16x32_bf16 v[92:95], v[228:231], v[172:175], v[92:95]
	v_mfma_f32_16x16x32_bf16 v[84:87], v[224:227], v[176:179], v[84:87]
	v_mfma_f32_16x16x32_bf16 v[84:87], v[228:231], v[180:183], v[84:87]
	v_mfma_f32_16x16x32_bf16 v[76:79], v[224:227], v[184:187], v[76:79]
	v_mfma_f32_16x16x32_bf16 v[76:79], v[228:231], v[188:191], v[76:79]
	v_mfma_f32_16x16x32_bf16 v[68:71], v[224:227], v[192:195], v[68:71]
	v_mfma_f32_16x16x32_bf16 v[68:71], v[228:231], v[212:215], v[68:71]
	s_barrier
	s_setprio 0
	s_mov_b32 m0, s30
	v_lshl_add_u64 v[142:143], v[232:233], 0, s[52:53]
	ds_read_b128 v[168:171], v146 offset:49152
	ds_read_b128 v[172:175], v146 offset:50176
	ds_read_b128 v[176:179], v146 offset:51200
	ds_read_b128 v[180:183], v146 offset:52224
	ds_read_b128 v[184:187], v146 offset:53248
	ds_read_b128 v[188:191], v146 offset:54272
	ds_read_b128 v[192:195], v146 offset:55296
	ds_read_b128 v[212:215], v146 offset:56320
	global_load_lds_dwordx4 v[142:143], off
	v_lshl_add_u64 v[142:143], v[234:235], 0, s[52:53]
	s_mov_b32 m0, s31
	s_nop 0
	global_load_lds_dwordx4 v[142:143], off
	s_setprio 1
	s_barrier
; #define PG8_WAIT_V(n) asm volatile("s_waitcnt vmcnt(" #n ")" ::: "memory")
; #define PG8_WAIT_L(n) asm volatile("s_waitcnt lgkmcnt(" #n ")" ::: "memory")
; #define PG8_BAR __builtin_amdgcn_s_barrier()
; #define PG8_SCHED __builtin_amdgcn_sched_barrier(0)
; template <class Epi, class AddrA, class AddrB>
; __device__ __forceinline__ void gemm_phase(const Sched S, const int lda, const int ldb, const int K, const AddrA addrA,
;                                            const AddrB addrB, const Epi E) {
;     ...
;       PG8_LDB(B0, 0, 0); PG8_SCHED; PG8_LDA(At, 0, 0); PG8_STAGE(PG8_SA(1, 1), a1 + hstepA, voffA);
;       PG8_WAIT_L(8); PG8_BAR; PG8_WAIT_L(0); PG8_MMA(0, 0, At, B0); PG8_BAR; PG8_SCHED;
;       PG8_LDB(B1, 0, 1); PG8_STAGE(PG8_SB(0, 0), b2, voffB);
;       PG8_BAR; PG8_WAIT_L(0); PG8_MMA(0, 1, At, B1); PG8_BAR;
;       PG8_LDA(At, 0, 1); PG8_STAGE(PG8_SA(0, 0), a2, voffA);
;       PG8_BAR; PG8_WAIT_L(0); PG8_MMA(1, 0, At, B0); PG8_BAR; PG8_SCHED;
;       PG8_STAGE(PG8_SB(0, 1), b2 + hstepB, voffB);
;       PG8_WAIT_V(6); PG8_BAR; PG8_MMA(1, 1, At, B1); PG8_BAR;
;       PG8_LDB(B0, 1, 0); PG8_SCHED; PG8_LDA(At, 1, 0); PG8_STAGE(PG8_SA(0, 1), a2 + hstepA, voffA);
;       PG8_WAIT_L(8); PG8_BAR; PG8_WAIT_L(0); PG8_MMA(0, 0, At, B0); PG8_BAR; PG8_SCHED;
;       PG8_LDB(B1, 1, 1); PG8_STAGE(PG8_SB(1, 0), b3, voffB);
;       PG8_BAR; PG8_WAIT_L(0); PG8_MMA(0, 1, At, B1); PG8_BAR;
;       PG8_LDA(At, 1, 1); PG8_STAGE(PG8_SA(1, 0), a3, voffA);
;       PG8_BAR; PG8_WAIT_L(0); PG8_MMA(1, 0, At, B0); PG8_BAR; PG8_SCHED;
;       PG8_STAGE(PG8_SB(1, 1), b3 + hstepB, voffB);
;       PG8_WAIT_V(6); PG8_BAR; PG8_MMA(1, 1, At, B1); PG8_BAR;
	s_waitcnt lgkmcnt(0)
	v_mfma_f32_16x16x32_bf16 v[64:67], v[148:151], v[168:171], v[64:67]
	v_mfma_f32_16x16x32_bf16 v[64:67], v[152:155], v[172:175], v[64:67]
	v_mfma_f32_16x16x32_bf16 v[56:59], v[148:151], v[176:179], v[56:59]
	v_mfma_f32_16x16x32_bf16 v[56:59], v[152:155], v[180:183], v[56:59]
	v_mfma_f32_16x16x32_bf16 v[48:51], v[148:151], v[184:187], v[48:51]
	v_mfma_f32_16x16x32_bf16 v[48:51], v[152:155], v[188:191], v[48:51]
	v_mfma_f32_16x16x32_bf16 v[40:43], v[148:151], v[192:195], v[40:43]
	v_mfma_f32_16x16x32_bf16 v[40:43], v[152:155], v[212:215], v[40:43]
	v_mfma_f32_16x16x32_bf16 v[60:63], v[156:159], v[168:171], v[60:63]
	v_mfma_f32_16x16x32_bf16 v[60:63], v[160:163], v[172:175], v[60:63]
	v_mfma_f32_16x16x32_bf16 v[52:55], v[156:159], v[176:179], v[52:55]
	v_mfma_f32_16x16x32_bf16 v[52:55], v[160:163], v[180:183], v[52:55]
	v_mfma_f32_16x16x32_bf16 v[44:47], v[156:159], v[184:187], v[44:47]
	v_mfma_f32_16x16x32_bf16 v[44:47], v[160:163], v[188:191], v[44:47]
	v_mfma_f32_16x16x32_bf16 v[36:39], v[156:159], v[192:195], v[36:39]
	v_mfma_f32_16x16x32_bf16 v[36:39], v[160:163], v[212:215], v[36:39]
	s_barrier
	s_setprio 0
	s_add_u32 s16, s16, 0x80080
	s_addc_u32 s17, s17, 0
	s_add_i32 s18, s18, s25
	v_lshl_add_u64 v[142:143], s[16:17], 0, v[2:3]
	s_mov_b32 m0, s18
	s_nop 0
	global_load_lds_dwordx4 v[142:143], off
	v_lshl_add_u64 v[142:143], s[16:17], 0, v[0:1]
	s_add_i32 m0, s18, 0x2000
	s_nop 0
	global_load_lds_dwordx4 v[142:143], off
	s_add_i32 s38, s38, 2
	s_add_u32 s36, s36, 0x100
	s_addc_u32 s37, s37, 0
	s_add_u32 s14, s14, 0x100
	s_addc_u32 s15, s15, 0
	s_waitcnt vmcnt(6)
	s_setprio 1
	s_barrier
	v_mfma_f32_16x16x32_bf16 v[32:35], v[216:219], v[168:171], v[32:35]
	v_mfma_f32_16x16x32_bf16 v[32:35], v[220:223], v[172:175], v[32:35]
	v_mfma_f32_16x16x32_bf16 v[24:27], v[216:219], v[176:179], v[24:27]
	v_mfma_f32_16x16x32_bf16 v[24:27], v[220:223], v[180:183], v[24:27]
	v_mfma_f32_16x16x32_bf16 v[16:19], v[216:219], v[184:187], v[16:19]
	v_mfma_f32_16x16x32_bf16 v[16:19], v[220:223], v[188:191], v[16:19]
	v_mfma_f32_16x16x32_bf16 v[8:11], v[216:219], v[192:195], v[8:11]
	v_mfma_f32_16x16x32_bf16 v[8:11], v[220:223], v[212:215], v[8:11]
	v_mfma_f32_16x16x32_bf16 v[28:31], v[224:227], v[168:171], v[28:31]
	v_mfma_f32_16x16x32_bf16 v[28:31], v[228:231], v[172:175], v[28:31]
	v_mfma_f32_16x16x32_bf16 v[20:23], v[224:227], v[176:179], v[20:23]
	v_mfma_f32_16x16x32_bf16 v[20:23], v[228:231], v[180:183], v[20:23]
	v_mfma_f32_16x16x32_bf16 v[12:15], v[224:227], v[184:187], v[12:15]
	v_mfma_f32_16x16x32_bf16 v[12:15], v[228:231], v[188:191], v[12:15]
	v_mfma_f32_16x16x32_bf16 v[4:7], v[224:227], v[192:195], v[4:7]
	v_mfma_f32_16x16x32_bf16 v[4:7], v[228:231], v[212:215], v[4:7]
	s_barrier
	s_setprio 0
	s_cmp_gt_u32 s38, 29
.LBB0_619:
	s_add_i32 s39, 0, 0x10000
	v_add_u32_e32 v142, s39, v144
	ds_read_b128 v[148:151], v142
	ds_read_b128 v[152:155], v142 offset:1024
	ds_read_b128 v[156:159], v142 offset:2048
	ds_read_b128 v[160:163], v142 offset:3072
	v_lshl_add_u64 v[142:143], s[14:15], 0, v[140:141]
	s_add_i32 m0, s26, 0xc000
	ds_read_b128 v[168:171], v146
	ds_read_b128 v[172:175], v146 offset:1024
	ds_read_b128 v[176:179], v146 offset:2048
	ds_read_b128 v[180:183], v146 offset:3072
	ds_read_b128 v[184:187], v146 offset:4096
	ds_read_b128 v[188:191], v146 offset:5120
	ds_read_b128 v[192:195], v146 offset:6144
	ds_read_b128 v[212:215], v146 offset:7168
	global_load_lds_dwordx4 v[142:143], off
	v_lshl_add_u64 v[142:143], s[14:15], 0, v[138:139]
	s_add_i32 m0, s26, 0xe000
	s_nop 0
	global_load_lds_dwordx4 v[142:143], off
	s_waitcnt lgkmcnt(8)
	s_setprio 1
	s_barrier
	s_waitcnt lgkmcnt(0)
	v_mfma_f32_16x16x32_bf16 v[128:131], v[148:151], v[168:171], v[128:131]
	v_mfma_f32_16x16x32_bf16 v[128:131], v[152:155], v[172:175], v[128:131]
	v_mfma_f32_16x16x32_bf16 v[120:123], v[148:151], v[176:179], v[120:123]
	v_mfma_f32_16x16x32_bf16 v[120:123], v[152:155], v[180:183], v[120:123]
	v_mfma_f32_16x16x32_bf16 v[112:115], v[148:151], v[184:187], v[112:115]
	v_mfma_f32_16x16x32_bf16 v[112:115], v[152:155], v[188:191], v[112:115]
	v_mfma_f32_16x16x32_bf16 v[104:107], v[148:151], v[192:195], v[104:107]
	v_mfma_f32_16x16x32_bf16 v[104:107], v[152:155], v[212:215], v[104:107]
	v_mfma_f32_16x16x32_bf16 v[124:127], v[156:159], v[168:171], v[124:127]
	v_mfma_f32_16x16x32_bf16 v[124:127], v[160:163], v[172:175], v[124:127]
	v_mfma_f32_16x16x32_bf16 v[116:119], v[156:159], v[176:179], v[116:119]
	v_mfma_f32_16x16x32_bf16 v[116:119], v[160:163], v[180:183], v[116:119]
	v_mfma_f32_16x16x32_bf16 v[108:111], v[156:159], v[184:187], v[108:111]
	v_mfma_f32_16x16x32_bf16 v[108:111], v[160:163], v[188:191], v[108:111]
	v_mfma_f32_16x16x32_bf16 v[100:103], v[156:159], v[192:195], v[100:103]
	v_mfma_f32_16x16x32_bf16 v[100:103], v[160:163], v[212:215], v[100:103]
	s_barrier
	s_setprio 0
	s_add_u32 s16, s14, 0xfff80080
	s_addc_u32 s17, s15, -1
	s_cmp_eq_u32 s38, 28
	s_cselect_b32 s19, s3, s17
	s_cselect_b32 s18, s13, s16
	s_cselect_b32 s17, s5, s37
	s_cselect_b32 s16, s35, s36
	s_add_i32 s42, 0, 0x14000
	v_add_u32_e32 v142, s42, v144
	s_add_i32 s39, s39, s25
	ds_read_b128 v[216:219], v142
	ds_read_b128 v[220:223], v142 offset:1024
	ds_read_b128 v[224:227], v142 offset:2048
	ds_read_b128 v[228:231], v142 offset:3072
	v_lshl_add_u64 v[142:143], s[16:17], 0, v[2:3]
	s_mov_b32 m0, s39
	v_lshl_add_u64 v[196:197], s[16:17], 0, v[0:1]
	global_load_lds_dwordx4 v[142:143], off
	s_add_i32 m0, s39, 0x2000
	s_nop 0
	global_load_lds_dwordx4 v[196:197], off
	s_setprio 1
	s_barrier
; #define PG8_WAIT_V(n) asm volatile("s_waitcnt vmcnt(" #n ")" ::: "memory")
; #define PG8_WAIT_L(n) asm volatile("s_waitcnt lgkmcnt(" #n ")" ::: "memory")
; #define PG8_BAR __builtin_amdgcn_s_barrier()
; #define PG8_SCHED __builtin_amdgcn_sched_barrier(0)
; template <class Epi, class AddrA, class AddrB>
; __device__ __forceinline__ void gemm_phase(const Sched S, const int lda, const int ldb, const int K, const AddrA addrA,
;                                            const AddrB addrB, const Epi E) {
;     ...
;       PG8_BAR; PG8_WAIT_L(0); PG8_MMA(0, 1, At, B1); PG8_BAR;
;       PG8_LDA(At, 0, 1); PG8_STAGE(PG8_SA(0, 0), a2, voffA);
;       PG8_BAR; PG8_WAIT_L(0); PG8_MMA(1, 0, At, B0); PG8_BAR; PG8_SCHED;
;       PG8_STAGE(PG8_SB(0, 1), b2 + hstepB, voffB);
;       PG8_WAIT_V(6); PG8_BAR; PG8_MMA(1, 1, At, B1); PG8_BAR;
;       PG8_LDB(B0, 1, 0); PG8_SCHED; PG8_LDA(At, 1, 0); PG8_STAGE(PG8_SA(0, 1), a2 + hstepA, voffA);
;       PG8_WAIT_L(8); PG8_BAR; PG8_WAIT_L(0); PG8_MMA(0, 0, At, B0); PG8_BAR; PG8_SCHED;
;       PG8_LDB(B1, 1, 1); PG8_STAGE(PG8_SB(1, 0), b3, voffB);
	s_waitcnt lgkmcnt(0)
	v_mfma_f32_16x16x32_bf16 v[96:99], v[216:219], v[168:171], v[96:99]
	v_mfma_f32_16x16x32_bf16 v[96:99], v[220:223], v[172:175], v[96:99]
	v_mfma_f32_16x16x32_bf16 v[88:91], v[216:219], v[176:179], v[88:91]
	v_mfma_f32_16x16x32_bf16 v[88:91], v[220:223], v[180:183], v[88:91]
	v_mfma_f32_16x16x32_bf16 v[80:83], v[216:219], v[184:187], v[80:83]
	v_mfma_f32_16x16x32_bf16 v[80:83], v[220:223], v[188:191], v[80:83]
	v_mfma_f32_16x16x32_bf16 v[72:75], v[216:219], v[192:195], v[72:75]
	v_mfma_f32_16x16x32_bf16 v[72:75], v[220:223], v[212:215], v[72:75]
	v_mfma_f32_16x16x32_bf16 v[92:95], v[224:227], v[168:171], v[92:95]
	v_mfma_f32_16x16x32_bf16 v[92:95], v[228:231], v[172:175], v[92:95]
	v_mfma_f32_16x16x32_bf16 v[84:87], v[224:227], v[176:179], v[84:87]
	v_mfma_f32_16x16x32_bf16 v[84:87], v[228:231], v[180:183], v[84:87]
	v_mfma_f32_16x16x32_bf16 v[76:79], v[224:227], v[184:187], v[76:79]
	v_mfma_f32_16x16x32_bf16 v[76:79], v[228:231], v[188:191], v[76:79]
	v_mfma_f32_16x16x32_bf16 v[68:71], v[224:227], v[192:195], v[68:71]
	v_mfma_f32_16x16x32_bf16 v[68:71], v[228:231], v[212:215], v[68:71]
	s_barrier
	s_setprio 0
	s_mov_b32 m0, s26
	v_lshl_add_u64 v[232:233], s[18:19], 0, v[134:135]
	ds_read_b128 v[168:171], v146 offset:16384
	ds_read_b128 v[172:175], v146 offset:17408
	ds_read_b128 v[176:179], v146 offset:18432
	ds_read_b128 v[180:183], v146 offset:19456
	ds_read_b128 v[184:187], v146 offset:20480
	ds_read_b128 v[188:191], v146 offset:21504
	ds_read_b128 v[192:195], v146 offset:22528
	ds_read_b128 v[212:215], v146 offset:23552
	global_load_lds_dwordx4 v[232:233], off
	v_lshl_add_u64 v[234:235], s[18:19], 0, v[132:133]
	s_mov_b32 m0, s27
	s_nop 0
	global_load_lds_dwordx4 v[234:235], off
	s_setprio 1
	s_barrier
	s_waitcnt lgkmcnt(0)
	v_mfma_f32_16x16x32_bf16 v[64:67], v[148:151], v[168:171], v[64:67]
	v_mfma_f32_16x16x32_bf16 v[64:67], v[152:155], v[172:175], v[64:67]
	v_mfma_f32_16x16x32_bf16 v[56:59], v[148:151], v[176:179], v[56:59]
	v_mfma_f32_16x16x32_bf16 v[56:59], v[152:155], v[180:183], v[56:59]
	v_mfma_f32_16x16x32_bf16 v[48:51], v[148:151], v[184:187], v[48:51]
	v_mfma_f32_16x16x32_bf16 v[48:51], v[152:155], v[188:191], v[48:51]
	v_mfma_f32_16x16x32_bf16 v[40:43], v[148:151], v[192:195], v[40:43]
	v_mfma_f32_16x16x32_bf16 v[40:43], v[152:155], v[212:215], v[40:43]
	v_mfma_f32_16x16x32_bf16 v[60:63], v[156:159], v[168:171], v[60:63]
	v_mfma_f32_16x16x32_bf16 v[60:63], v[160:163], v[172:175], v[60:63]
	v_mfma_f32_16x16x32_bf16 v[52:55], v[156:159], v[176:179], v[52:55]
	v_mfma_f32_16x16x32_bf16 v[52:55], v[160:163], v[180:183], v[52:55]
	v_mfma_f32_16x16x32_bf16 v[44:47], v[156:159], v[184:187], v[44:47]
	v_mfma_f32_16x16x32_bf16 v[44:47], v[160:163], v[188:191], v[44:47]
	v_mfma_f32_16x16x32_bf16 v[36:39], v[156:159], v[192:195], v[36:39]
	v_mfma_f32_16x16x32_bf16 v[36:39], v[160:163], v[212:215], v[36:39]
	s_barrier
	s_setprio 0
	s_add_u32 s40, s16, 0x80000
	s_addc_u32 s41, s17, 0
	s_add_i32 s39, s42, s25
	v_lshl_add_u64 v[148:149], s[40:41], 0, v[2:3]
	s_mov_b32 m0, s39
	s_nop 0
	global_load_lds_dwordx4 v[148:149], off
	v_lshl_add_u64 v[148:149], s[40:41], 0, v[0:1]
	s_add_i32 m0, s39, 0x2000
	s_nop 0
	global_load_lds_dwordx4 v[148:149], off
	s_waitcnt vmcnt(6)
	s_setprio 1
	s_barrier
	v_mfma_f32_16x16x32_bf16 v[32:35], v[216:219], v[168:171], v[32:35]
	v_mfma_f32_16x16x32_bf16 v[32:35], v[220:223], v[172:175], v[32:35]
	v_mfma_f32_16x16x32_bf16 v[24:27], v[216:219], v[176:179], v[24:27]
	v_mfma_f32_16x16x32_bf16 v[24:27], v[220:223], v[180:183], v[24:27]
	v_mfma_f32_16x16x32_bf16 v[16:19], v[216:219], v[184:187], v[16:19]
	v_mfma_f32_16x16x32_bf16 v[16:19], v[220:223], v[188:191], v[16:19]
	v_mfma_f32_16x16x32_bf16 v[8:11], v[216:219], v[192:195], v[8:11]
	v_mfma_f32_16x16x32_bf16 v[8:11], v[220:223], v[212:215], v[8:11]
	v_mfma_f32_16x16x32_bf16 v[28:31], v[224:227], v[168:171], v[28:31]
	v_mfma_f32_16x16x32_bf16 v[28:31], v[228:231], v[172:175], v[28:31]
	v_mfma_f32_16x16x32_bf16 v[20:23], v[224:227], v[176:179], v[20:23]
	v_mfma_f32_16x16x32_bf16 v[20:23], v[228:231], v[180:183], v[20:23]
	v_mfma_f32_16x16x32_bf16 v[12:15], v[224:227], v[184:187], v[12:15]
	v_mfma_f32_16x16x32_bf16 v[12:15], v[228:231], v[188:191], v[12:15]
	v_mfma_f32_16x16x32_bf16 v[4:7], v[224:227], v[192:195], v[4:7]
	v_mfma_f32_16x16x32_bf16 v[4:7], v[228:231], v[212:215], v[4:7]
	s_barrier
	s_setprio 0
	s_add_i32 s39, 0, 0x18000
	v_add_u32_e32 v147, s39, v144
	ds_read_b128 v[148:151], v147
	ds_read_b128 v[152:155], v147 offset:1024
	ds_read_b128 v[156:159], v147 offset:2048
	ds_read_b128 v[160:163], v147 offset:3072
	s_add_u32 s18, s18, 0x80000
	s_addc_u32 s19, s19, 0
	s_mov_b32 m0, s28
	v_lshl_add_u64 v[216:217], s[18:19], 0, v[134:135]
	ds_read_b128 v[168:171], v146 offset:32768
	ds_read_b128 v[172:175], v146 offset:33792
	ds_read_b128 v[176:179], v146 offset:34816
	ds_read_b128 v[180:183], v146 offset:35840
	ds_read_b128 v[184:187], v146 offset:36864
	ds_read_b128 v[188:191], v146 offset:37888
	ds_read_b128 v[192:195], v146 offset:38912
	ds_read_b128 v[212:215], v146 offset:39936
	global_load_lds_dwordx4 v[216:217], off
	v_lshl_add_u64 v[216:217], s[18:19], 0, v[132:133]
	s_mov_b32 m0, s29
	s_nop 0
	global_load_lds_dwordx4 v[216:217], off
	s_waitcnt lgkmcnt(8)
	s_setprio 1
	s_barrier
; #define PG8_WAIT_V(n) asm volatile("s_waitcnt vmcnt(" #n ")" ::: "memory")
; #define PG8_WAIT_L(n) asm volatile("s_waitcnt lgkmcnt(" #n ")" ::: "memory")
; #define PG8_BAR __builtin_amdgcn_s_barrier()
; #define PG8_SCHED __builtin_amdgcn_sched_barrier(0)
; template <class Epi, class AddrA, class AddrB>
; __device__ __forceinline__ void gemm_phase(const Sched S, const int lda, const int ldb, const int K, const AddrA addrA,
;                                            const AddrB addrB, const Epi E) {
;     ...
;       PG8_WAIT_L(8); PG8_BAR; PG8_WAIT_L(0); PG8_MMA(0, 0, At, B0); PG8_BAR; PG8_SCHED;
;       PG8_LDB(B1, 1, 1); PG8_STAGE(PG8_SB(1, 0), b3, voffB);
;       PG8_BAR; PG8_WAIT_L(0); PG8_MMA(0, 1, At, B1); PG8_BAR;
;       PG8_LDA(At, 1, 1); PG8_STAGE(PG8_SA(1, 0), a3, voffA);
;       PG8_BAR; PG8_WAIT_L(0); PG8_MMA(1, 0, At, B0); PG8_BAR; PG8_SCHED;
;       PG8_STAGE(PG8_SB(1, 1), b3 + hstepB, voffB);
;       PG8_WAIT_V(6); PG8_BAR; PG8_MMA(1, 1, At, B1); PG8_BAR;
	s_waitcnt lgkmcnt(0)
	v_mfma_f32_16x16x32_bf16 v[128:131], v[148:151], v[168:171], v[128:131]
	v_mfma_f32_16x16x32_bf16 v[128:131], v[152:155], v[172:175], v[128:131]
	v_mfma_f32_16x16x32_bf16 v[120:123], v[148:151], v[176:179], v[120:123]
	v_mfma_f32_16x16x32_bf16 v[120:123], v[152:155], v[180:183], v[120:123]
	v_mfma_f32_16x16x32_bf16 v[112:115], v[148:151], v[184:187], v[112:115]
	v_mfma_f32_16x16x32_bf16 v[112:115], v[152:155], v[188:191], v[112:115]
	v_mfma_f32_16x16x32_bf16 v[104:107], v[148:151], v[192:195], v[104:107]
	v_mfma_f32_16x16x32_bf16 v[104:107], v[152:155], v[212:215], v[104:107]
	v_mfma_f32_16x16x32_bf16 v[124:127], v[156:159], v[168:171], v[124:127]
	v_mfma_f32_16x16x32_bf16 v[124:127], v[160:163], v[172:175], v[124:127]
	v_mfma_f32_16x16x32_bf16 v[116:119], v[156:159], v[176:179], v[116:119]
	v_mfma_f32_16x16x32_bf16 v[116:119], v[160:163], v[180:183], v[116:119]
	v_mfma_f32_16x16x32_bf16 v[108:111], v[156:159], v[184:187], v[108:111]
	v_mfma_f32_16x16x32_bf16 v[108:111], v[160:163], v[188:191], v[108:111]
	v_mfma_f32_16x16x32_bf16 v[100:103], v[156:159], v[192:195], v[100:103]
	v_mfma_f32_16x16x32_bf16 v[100:103], v[160:163], v[212:215], v[100:103]
	s_barrier
	s_setprio 0
	s_add_i32 s18, 0, 0x1c000
	s_add_i32 s19, s39, s25
	v_add_u32_e32 v147, s18, v144
	v_lshl_add_u64 v[142:143], v[142:143], 0, s[52:53]
	s_mov_b32 m0, s19
	ds_read_b128 v[216:219], v147
	ds_read_b128 v[220:223], v147 offset:1024
	ds_read_b128 v[224:227], v147 offset:2048
	ds_read_b128 v[228:231], v147 offset:3072
	global_load_lds_dwordx4 v[142:143], off
	v_lshl_add_u64 v[142:143], v[196:197], 0, s[52:53]
	s_add_i32 m0, s19, 0x2000
	s_nop 0
	global_load_lds_dwordx4 v[142:143], off
	s_setprio 1
	s_barrier
	s_waitcnt lgkmcnt(0)
	v_mfma_f32_16x16x32_bf16 v[96:99], v[216:219], v[168:171], v[96:99]
	v_mfma_f32_16x16x32_bf16 v[96:99], v[220:223], v[172:175], v[96:99]
	v_mfma_f32_16x16x32_bf16 v[88:91], v[216:219], v[176:179], v[88:91]
	v_mfma_f32_16x16x32_bf16 v[88:91], v[220:223], v[180:183], v[88:91]
	v_mfma_f32_16x16x32_bf16 v[80:83], v[216:219], v[184:187], v[80:83]
	v_mfma_f32_16x16x32_bf16 v[80:83], v[220:223], v[188:191], v[80:83]
	v_mfma_f32_16x16x32_bf16 v[72:75], v[216:219], v[192:195], v[72:75]
	v_mfma_f32_16x16x32_bf16 v[72:75], v[220:223], v[212:215], v[72:75]
	v_mfma_f32_16x16x32_bf16 v[92:95], v[224:227], v[168:171], v[92:95]
	v_mfma_f32_16x16x32_bf16 v[92:95], v[228:231], v[172:175], v[92:95]
	v_mfma_f32_16x16x32_bf16 v[84:87], v[224:227], v[176:179], v[84:87]
	v_mfma_f32_16x16x32_bf16 v[84:87], v[228:231], v[180:183], v[84:87]
	v_mfma_f32_16x16x32_bf16 v[76:79], v[224:227], v[184:187], v[76:79]
	v_mfma_f32_16x16x32_bf16 v[76:79], v[228:231], v[188:191], v[76:79]
	v_mfma_f32_16x16x32_bf16 v[68:71], v[224:227], v[192:195], v[68:71]
	v_mfma_f32_16x16x32_bf16 v[68:71], v[228:231], v[212:215], v[68:71]
	s_barrier
	s_setprio 0
	s_mov_b32 m0, s30
	v_lshl_add_u64 v[142:143], v[232:233], 0, s[52:53]
	ds_read_b128 v[168:171], v146 offset:49152
	ds_read_b128 v[172:175], v146 offset:50176
	ds_read_b128 v[176:179], v146 offset:51200
	ds_read_b128 v[180:183], v146 offset:52224
	ds_read_b128 v[184:187], v146 offset:53248
	ds_read_b128 v[188:191], v146 offset:54272
	ds_read_b128 v[192:195], v146 offset:55296
	ds_read_b128 v[212:215], v146 offset:56320
	global_load_lds_dwordx4 v[142:143], off
	v_lshl_add_u64 v[142:143], v[234:235], 0, s[52:53]
	s_mov_b32 m0, s31
	s_nop 0
	global_load_lds_dwordx4 v[142:143], off
	s_setprio 1
	s_barrier
	s_waitcnt lgkmcnt(0)
	v_mfma_f32_16x16x32_bf16 v[64:67], v[148:151], v[168:171], v[64:67]
	v_mfma_f32_16x16x32_bf16 v[64:67], v[152:155], v[172:175], v[64:67]
	v_mfma_f32_16x16x32_bf16 v[56:59], v[148:151], v[176:179], v[56:59]
	v_mfma_f32_16x16x32_bf16 v[56:59], v[152:155], v[180:183], v[56:59]
	v_mfma_f32_16x16x32_bf16 v[48:51], v[148:151], v[184:187], v[48:51]
	v_mfma_f32_16x16x32_bf16 v[48:51], v[152:155], v[188:191], v[48:51]
	v_mfma_f32_16x16x32_bf16 v[40:43], v[148:151], v[192:195], v[40:43]
	v_mfma_f32_16x16x32_bf16 v[40:43], v[152:155], v[212:215], v[40:43]
	v_mfma_f32_16x16x32_bf16 v[60:63], v[156:159], v[168:171], v[60:63]
	v_mfma_f32_16x16x32_bf16 v[60:63], v[160:163], v[172:175], v[60:63]
	v_mfma_f32_16x16x32_bf16 v[52:55], v[156:159], v[176:179], v[52:55]
	v_mfma_f32_16x16x32_bf16 v[52:55], v[160:163], v[180:183], v[52:55]
	v_mfma_f32_16x16x32_bf16 v[44:47], v[156:159], v[184:187], v[44:47]
	v_mfma_f32_16x16x32_bf16 v[44:47], v[160:163], v[188:191], v[44:47]
	v_mfma_f32_16x16x32_bf16 v[36:39], v[156:159], v[192:195], v[36:39]
	v_mfma_f32_16x16x32_bf16 v[36:39], v[160:163], v[212:215], v[36:39]
	s_barrier
	s_setprio 0
	s_add_u32 s16, s16, 0x80080
	s_addc_u32 s17, s17, 0
	s_add_i32 s18, s18, s25
	v_lshl_add_u64 v[142:143], s[16:17], 0, v[2:3]
	s_mov_b32 m0, s18
	s_nop 0
	global_load_lds_dwordx4 v[142:143], off
	v_lshl_add_u64 v[142:143], s[16:17], 0, v[0:1]
	s_add_i32 m0, s18, 0x2000
	s_nop 0
	global_load_lds_dwordx4 v[142:143], off
	s_add_i32 s38, s38, 2
	s_add_u32 s36, s36, 0x100
	s_addc_u32 s37, s37, 0
	s_add_u32 s14, s14, 0x100
	s_addc_u32 s15, s15, 0
	s_waitcnt vmcnt(6)
	s_setprio 1
	s_barrier
; #define PG8_WAIT_V(n) asm volatile("s_waitcnt vmcnt(" #n ")" ::: "memory")
; #define PG8_BAR __builtin_amdgcn_s_barrier()
; template <class Epi, class AddrA, class AddrB>
; __device__ __forceinline__ void gemm_phase(const Sched S, const int lda, const int ldb, const int K, const AddrA addrA,
;                                            const AddrB addrB, const Epi E) {
;     ...
;       PG8_WAIT_V(6); PG8_BAR; PG8_MMA(1, 1, At, B1); PG8_BAR;
;     }
;     E(acc, cur, wr, wc, fr, fq);
;   __device__ __forceinline__ void operator()(EPI_ARGS) const {
;     ...
; #pragma unroll
;         for (int m = 0; m < 4; ++m) {
;           const size_t o = (row0 + ai * HALF + m * 16) * DM + col0 + bj * HALF;
;           x0[m] = *(const f32x4*)(xres + o);
;           x1[m] = *(const f32x4*)(xres + o + 4);
;         }
;         __builtin_amdgcn_sched_barrier(0);
; #pragma unroll
;         for (int m = 0; m < 4; ++m) {
;           const size_t o = (row0 + ai * HALF + m * 16) * DM + col0 + bj * HALF;
;           *(f32x4*)(hbuf + o) = acc[ai][bj][m][0] + x0[m] * ALPHA;
;           *(f32x4*)(hbuf + o + 4) = acc[ai][bj][m][1] + x1[m] * ALPHA;
;         }
	v_mfma_f32_16x16x32_bf16 v[32:35], v[216:219], v[168:171], v[32:35]
	v_mfma_f32_16x16x32_bf16 v[32:35], v[220:223], v[172:175], v[32:35]
	v_mfma_f32_16x16x32_bf16 v[24:27], v[216:219], v[176:179], v[24:27]
	v_mfma_f32_16x16x32_bf16 v[24:27], v[220:223], v[180:183], v[24:27]
	v_mfma_f32_16x16x32_bf16 v[16:19], v[216:219], v[184:187], v[16:19]
	v_mfma_f32_16x16x32_bf16 v[16:19], v[220:223], v[188:191], v[16:19]
	v_mfma_f32_16x16x32_bf16 v[8:11], v[216:219], v[192:195], v[8:11]
	v_mfma_f32_16x16x32_bf16 v[8:11], v[220:223], v[212:215], v[8:11]
	v_mfma_f32_16x16x32_bf16 v[28:31], v[224:227], v[168:171], v[28:31]
	v_mfma_f32_16x16x32_bf16 v[28:31], v[228:231], v[172:175], v[28:31]
	v_mfma_f32_16x16x32_bf16 v[20:23], v[224:227], v[176:179], v[20:23]
	v_mfma_f32_16x16x32_bf16 v[20:23], v[228:231], v[180:183], v[20:23]
	v_mfma_f32_16x16x32_bf16 v[12:15], v[224:227], v[184:187], v[12:15]
	v_mfma_f32_16x16x32_bf16 v[12:15], v[228:231], v[188:191], v[12:15]
	v_mfma_f32_16x16x32_bf16 v[4:7], v[224:227], v[192:195], v[4:7]
	v_mfma_f32_16x16x32_bf16 v[4:7], v[228:231], v[212:215], v[4:7]
	s_barrier
	s_setprio 0
	s_cmp_gt_u32 s38, 29
	s_cbranch_scc0 .LBB0_619
	s_ashr_i32 s13, s12, 31
	v_lshl_or_b32 v142, s34, 8, v145
	v_ashrrev_i32_e32 v143, 31, v142
	s_lshl_b64 s[12:13], s[12:13], 21
	v_lshlrev_b64 v[184:185], 2, v[142:143]
	v_lshl_add_u64 v[188:189], s[12:13], 0, v[136:137]
	v_lshl_add_u64 v[186:187], s[0:1], 0, v[184:185]
	v_or_b32_e32 v190, 0x20000, v188
	v_mov_b32_e32 v191, v189
	v_or_b32_e32 v192, 0x40000, v188
	v_mov_b32_e32 v193, v189
	v_or_b32_e32 v194, 0x60000, v188
	v_mov_b32_e32 v195, v189
	v_lshl_add_u64 v[142:143], v[186:187], 0, v[188:189]
	v_lshl_add_u64 v[160:161], v[186:187], 0, v[190:191]
	v_lshl_add_u64 v[172:173], v[186:187], 0, v[192:193]
	v_lshl_add_u64 v[180:181], v[186:187], 0, v[194:195]
	flat_load_dwordx4 v[148:151], v[142:143]
	flat_load_dwordx4 v[152:155], v[142:143] offset:16
	flat_load_dwordx4 v[156:159], v[160:161]
	s_nop 0
	flat_load_dwordx4 v[160:163], v[160:161] offset:16
	s_nop 0
	flat_load_dwordx4 v[168:171], v[172:173]
	s_nop 0
	flat_load_dwordx4 v[172:175], v[172:173] offset:16
	s_nop 0
	flat_load_dwordx4 v[176:179], v[180:181]
	s_nop 0
	flat_load_dwordx4 v[180:183], v[180:181] offset:16
	v_lshl_add_u64 v[184:185], s[48:49], 0, v[184:185]
	s_mov_b32 s14, 0x3fb504f3
	s_waitcnt vmcnt(0) lgkmcnt(0)
	v_pk_fma_f32 v[148:149], v[148:149], s[14:15], v[128:129] op_sel_hi:[1,0,1]
	v_lshl_add_u64 v[128:129], v[184:185], 0, v[188:189]
	v_pk_fma_f32 v[126:127], v[154:155], s[14:15], v[126:127] op_sel_hi:[1,0,1]
	v_pk_fma_f32 v[124:125], v[152:153], s[14:15], v[124:125] op_sel_hi:[1,0,1]
	global_store_dwordx4 v[128:129], v[124:127], off offset:16
	v_pk_fma_f32 v[118:119], v[162:163], s[14:15], v[118:119] op_sel_hi:[1,0,1]
	v_pk_fma_f32 v[116:117], v[160:161], s[14:15], v[116:117] op_sel_hi:[1,0,1]
	v_lshl_add_u64 v[124:125], v[184:185], 0, v[190:191]
	v_pk_fma_f32 v[122:123], v[158:159], s[14:15], v[122:123] op_sel_hi:[1,0,1]
	v_pk_fma_f32 v[120:121], v[156:157], s[14:15], v[120:121] op_sel_hi:[1,0,1]
	global_store_dwordx4 v[124:125], v[116:119], off offset:16
	v_pk_fma_f32 v[110:111], v[174:175], s[14:15], v[110:111] op_sel_hi:[1,0,1]
	v_pk_fma_f32 v[108:109], v[172:173], s[14:15], v[108:109] op_sel_hi:[1,0,1]
	v_lshl_add_u64 v[116:117], v[184:185], 0, v[192:193]
	s_mov_b64 s[12:13], 0x200
	v_pk_fma_f32 v[150:151], v[150:151], s[14:15], v[130:131] op_sel_hi:[1,0,1]
	global_store_dwordx4 v[124:125], v[120:123], off
	v_pk_fma_f32 v[114:115], v[170:171], s[14:15], v[114:115] op_sel_hi:[1,0,1]
	v_pk_fma_f32 v[112:113], v[168:169], s[14:15], v[112:113] op_sel_hi:[1,0,1]
	global_store_dwordx4 v[116:117], v[108:111], off offset:16
	v_pk_fma_f32 v[106:107], v[178:179], s[14:15], v[106:107] op_sel_hi:[1,0,1]
	v_pk_fma_f32 v[104:105], v[176:177], s[14:15], v[104:105] op_sel_hi:[1,0,1]
	v_lshl_add_u64 v[108:109], v[184:185], 0, v[194:195]
	v_pk_fma_f32 v[102:103], v[182:183], s[14:15], v[102:103] op_sel_hi:[1,0,1]
	v_pk_fma_f32 v[100:101], v[180:181], s[14:15], v[100:101] op_sel_hi:[1,0,1]
	v_lshl_add_u64 v[124:125], v[186:187], 0, s[12:13]
	global_store_dwordx4 v[128:129], v[148:151], off
	global_store_dwordx4 v[116:117], v[112:115], off
	global_store_dwordx4 v[108:109], v[104:107], off
	global_store_dwordx4 v[108:109], v[100:103], off offset:16
	v_lshl_add_u64 v[112:113], v[124:125], 0, v[190:191]
	v_lshl_add_u64 v[120:121], v[124:125], 0, v[192:193]
	v_lshl_add_u64 v[130:131], v[124:125], 0, v[194:195]
	flat_load_dwordx4 v[100:103], v[142:143] offset:512
	flat_load_dwordx4 v[104:107], v[142:143] offset:528
	flat_load_dwordx4 v[108:111], v[112:113]
	s_nop 0
	flat_load_dwordx4 v[112:115], v[112:113] offset:16
	s_nop 0
	flat_load_dwordx4 v[116:119], v[120:121]
	s_nop 0
	flat_load_dwordx4 v[120:123], v[120:121] offset:16
	s_nop 0
	flat_load_dwordx4 v[124:127], v[130:131]
	flat_load_dwordx4 v[148:151], v[130:131] offset:16
	s_mov_b32 s3, 0x100000
	s_waitcnt vmcnt(0) lgkmcnt(0)
;   __device__ __forceinline__ void operator()(EPI_ARGS) const {
;     ...
; #pragma unroll
;         for (int m = 0; m < 4; ++m) {
;           const size_t o = (row0 + ai * HALF + m * 16) * DM + col0 + bj * HALF;
;           x0[m] = *(const f32x4*)(xres + o);
;           x1[m] = *(const f32x4*)(xres + o + 4);
;         }
;         __builtin_amdgcn_sched_barrier(0);
; #pragma unroll
;         for (int m = 0; m < 4; ++m) {
;           const size_t o = (row0 + ai * HALF + m * 16) * DM + col0 + bj * HALF;
;           *(f32x4*)(hbuf + o) = acc[ai][bj][m][0] + x0[m] * ALPHA;
;           *(f32x4*)(hbuf + o + 4) = acc[ai][bj][m][1] + x1[m] * ALPHA;
;         }
	v_pk_fma_f32 v[96:97], v[100:101], s[14:15], v[96:97] op_sel_hi:[1,0,1]
	v_add_co_u32_e32 v100, vcc, s3, v142
	s_mov_b32 s5, 0x120000
	s_nop 0
	v_addc_co_u32_e32 v101, vcc, 0, v143, vcc
	v_pk_fma_f32 v[98:99], v[102:103], s[14:15], v[98:99] op_sel_hi:[1,0,1]
	v_add_co_u32_e32 v102, vcc, s5, v142
	v_lshl_add_u64 v[130:131], v[184:185], 0, s[12:13]
	v_pk_fma_f32 v[94:95], v[106:107], s[14:15], v[94:95] op_sel_hi:[1,0,1]
	v_pk_fma_f32 v[92:93], v[104:105], s[14:15], v[92:93] op_sel_hi:[1,0,1]
	v_addc_co_u32_e32 v103, vcc, 0, v143, vcc
	s_mov_b32 s12, 0x140000
	global_store_dwordx4 v[128:129], v[92:95], off offset:528
	v_pk_fma_f32 v[86:87], v[114:115], s[14:15], v[86:87] op_sel_hi:[1,0,1]
	v_pk_fma_f32 v[84:85], v[112:113], s[14:15], v[84:85] op_sel_hi:[1,0,1]
	v_lshl_add_u64 v[92:93], v[130:131], 0, v[190:191]
	v_add_co_u32_e32 v104, vcc, s12, v142
	global_store_dwordx4 v[92:93], v[84:87], off offset:16
	v_pk_fma_f32 v[78:79], v[122:123], s[14:15], v[78:79] op_sel_hi:[1,0,1]
	v_pk_fma_f32 v[76:77], v[120:121], s[14:15], v[76:77] op_sel_hi:[1,0,1]
	v_lshl_add_u64 v[84:85], v[130:131], 0, v[192:193]
	v_addc_co_u32_e32 v105, vcc, 0, v143, vcc
	s_mov_b32 s13, 0x160000
	v_pk_fma_f32 v[90:91], v[110:111], s[14:15], v[90:91] op_sel_hi:[1,0,1]
	v_pk_fma_f32 v[88:89], v[108:109], s[14:15], v[88:89] op_sel_hi:[1,0,1]
	v_pk_fma_f32 v[82:83], v[118:119], s[14:15], v[82:83] op_sel_hi:[1,0,1]
	v_pk_fma_f32 v[80:81], v[116:117], s[14:15], v[80:81] op_sel_hi:[1,0,1]
	global_store_dwordx4 v[84:85], v[76:79], off offset:16
	v_pk_fma_f32 v[74:75], v[126:127], s[14:15], v[74:75] op_sel_hi:[1,0,1]
	v_pk_fma_f32 v[72:73], v[124:125], s[14:15], v[72:73] op_sel_hi:[1,0,1]
	v_lshl_add_u64 v[76:77], v[130:131], 0, v[194:195]
	v_pk_fma_f32 v[70:71], v[150:151], s[14:15], v[70:71] op_sel_hi:[1,0,1]
	v_pk_fma_f32 v[68:69], v[148:149], s[14:15], v[68:69] op_sel_hi:[1,0,1]
	s_mov_b64 s[16:17], 0x100000
	s_mov_b64 s[18:19], 0x120000
	s_mov_b64 s[34:35], 0x140000
	s_mov_b64 s[36:37], 0x160000
	v_add_co_u32_e32 v106, vcc, s13, v142
	global_store_dwordx4 v[128:129], v[96:99], off offset:512
	global_store_dwordx4 v[92:93], v[88:91], off
	global_store_dwordx4 v[84:85], v[80:83], off
	global_store_dwordx4 v[76:77], v[72:75], off
	global_store_dwordx4 v[76:77], v[68:71], off offset:16
	v_lshl_add_u64 v[80:81], v[142:143], 0, s[18:19]
	v_lshl_add_u64 v[72:73], v[142:143], 0, s[16:17]
	v_lshl_add_u64 v[88:89], v[142:143], 0, s[34:35]
	v_lshl_add_u64 v[96:97], v[142:143], 0, s[36:37]
	v_addc_co_u32_e32 v107, vcc, 0, v143, vcc
	flat_load_dwordx4 v[68:71], v[100:101]
	s_nop 0
	flat_load_dwordx4 v[72:75], v[72:73] offset:16
	s_nop 0
	flat_load_dwordx4 v[76:79], v[102:103]
	s_nop 0
	flat_load_dwordx4 v[80:83], v[80:81] offset:16
	s_nop 0
	flat_load_dwordx4 v[84:87], v[104:105]
	s_nop 0
	flat_load_dwordx4 v[88:91], v[88:89] offset:16
	s_nop 0
	flat_load_dwordx4 v[92:95], v[106:107]
	s_nop 0
	flat_load_dwordx4 v[96:99], v[96:97] offset:16
	s_waitcnt vmcnt(0) lgkmcnt(0)
; #define PG8_WAIT_V(n) asm volatile("s_waitcnt vmcnt(" #n ")" ::: "memory")
; #define PG8_BAR __builtin_amdgcn_s_barrier()
; template <class Epi, class AddrA, class AddrB>
; __device__ __forceinline__ void gemm_phase(const Sched S, const int lda, const int ldb, const int K, const AddrA addrA,
;                                            const AddrB addrB, const Epi E) {
;     ...
;     E(acc, cur, wr, wc, fr, fq);
;     if (!has_next) break;
;     if (!(Epi::KEEP && cur.br + 1 < S.nbr)) {
; #pragma unroll
;       for (int a = 0; a < 2; ++a)
; #pragma unroll
;         for (int b = 0; b < 2; ++b)
; #pragma unroll
;           for (int m = 0; m < 4; ++m)
; #pragma unroll
;             for (int n = 0; n < 2; ++n) acc[a][b][m][n] = (f32x4){0.f, 0.f, 0.f, 0.f};
;     }
;     cur = nxt; cA = nA; cB = nB; ++ui;
;   }
;   PG8_WAIT_V(0);
;   if (wr == 0) PG8_BAR;
;   PG8_BAR;
;   __device__ __forceinline__ void operator()(EPI_ARGS) const {
;     ...
; #pragma unroll
;         for (int m = 0; m < 4; ++m) {
;           const size_t o = (row0 + ai * HALF + m * 16) * DM + col0 + bj * HALF;
;           x0[m] = *(const f32x4*)(xres + o);
;           x1[m] = *(const f32x4*)(xres + o + 4);
;         }
;         __builtin_amdgcn_sched_barrier(0);
; #pragma unroll
;         for (int m = 0; m < 4; ++m) {
;           const size_t o = (row0 + ai * HALF + m * 16) * DM + col0 + bj * HALF;
;           *(f32x4*)(hbuf + o) = acc[ai][bj][m][0] + x0[m] * ALPHA;
;           *(f32x4*)(hbuf + o + 4) = acc[ai][bj][m][1] + x1[m] * ALPHA;
;         }
	v_pk_fma_f32 v[66:67], v[70:71], s[14:15], v[66:67] op_sel_hi:[1,0,1]
	v_add_co_u32_e32 v70, vcc, s3, v128
	v_pk_fma_f32 v[64:65], v[68:69], s[14:15], v[64:65] op_sel_hi:[1,0,1]
	v_lshl_add_u64 v[68:69], v[128:129], 0, s[16:17]
	v_addc_co_u32_e32 v71, vcc, 0, v129, vcc
	v_pk_fma_f32 v[62:63], v[74:75], s[14:15], v[62:63] op_sel_hi:[1,0,1]
	v_pk_fma_f32 v[60:61], v[72:73], s[14:15], v[60:61] op_sel_hi:[1,0,1]
	global_store_dwordx4 v[68:69], v[60:63], off offset:16
	v_add_co_u32_e32 v68, vcc, s5, v128
	s_nop 0
	v_lshl_add_u64 v[60:61], v[128:129], 0, s[18:19]
	v_addc_co_u32_e32 v69, vcc, 0, v129, vcc
	v_add_co_u32_e32 v72, vcc, s12, v128
	v_pk_fma_f32 v[54:55], v[82:83], s[14:15], v[54:55] op_sel_hi:[1,0,1]
	v_pk_fma_f32 v[52:53], v[80:81], s[14:15], v[52:53] op_sel_hi:[1,0,1]
	v_addc_co_u32_e32 v73, vcc, 0, v129, vcc
	global_store_dwordx4 v[60:61], v[52:55], off offset:16
	v_pk_fma_f32 v[46:47], v[90:91], s[14:15], v[46:47] op_sel_hi:[1,0,1]
	v_pk_fma_f32 v[44:45], v[88:89], s[14:15], v[44:45] op_sel_hi:[1,0,1]
	v_lshl_add_u64 v[52:53], v[128:129], 0, s[34:35]
	v_add_co_u32_e32 v74, vcc, s13, v128
	v_pk_fma_f32 v[58:59], v[78:79], s[14:15], v[58:59] op_sel_hi:[1,0,1]
	v_pk_fma_f32 v[56:57], v[76:77], s[14:15], v[56:57] op_sel_hi:[1,0,1]
	v_pk_fma_f32 v[50:51], v[86:87], s[14:15], v[50:51] op_sel_hi:[1,0,1]
	v_pk_fma_f32 v[48:49], v[84:85], s[14:15], v[48:49] op_sel_hi:[1,0,1]
	global_store_dwordx4 v[52:53], v[44:47], off offset:16
	v_pk_fma_f32 v[42:43], v[94:95], s[14:15], v[42:43] op_sel_hi:[1,0,1]
	v_pk_fma_f32 v[40:41], v[92:93], s[14:15], v[40:41] op_sel_hi:[1,0,1]
	v_lshl_add_u64 v[44:45], v[128:129], 0, s[36:37]
	v_addc_co_u32_e32 v75, vcc, 0, v129, vcc
	v_pk_fma_f32 v[38:39], v[98:99], s[14:15], v[38:39] op_sel_hi:[1,0,1]
	v_pk_fma_f32 v[36:37], v[96:97], s[14:15], v[36:37] op_sel_hi:[1,0,1]
	s_mov_b64 s[12:13], 0x100200
	s_mov_b64 s[16:17], 0x120200
	s_mov_b64 s[18:19], 0x140200
	s_mov_b64 s[34:35], 0x160200
	global_store_dwordx4 v[70:71], v[64:67], off
	global_store_dwordx4 v[68:69], v[56:59], off
	global_store_dwordx4 v[72:73], v[48:51], off
	global_store_dwordx4 v[74:75], v[40:43], off
	global_store_dwordx4 v[44:45], v[36:39], off offset:16
	v_lshl_add_u64 v[44:45], v[142:143], 0, s[12:13]
	v_lshl_add_u64 v[48:49], v[142:143], 0, s[16:17]
	v_lshl_add_u64 v[60:61], v[142:143], 0, s[18:19]
	v_lshl_add_u64 v[64:65], v[142:143], 0, s[34:35]
	flat_load_dwordx4 v[36:39], v[100:101] offset:512
	flat_load_dwordx4 v[40:43], v[102:103] offset:512
	s_nop 0
	flat_load_dwordx4 v[44:47], v[44:45] offset:16
	s_nop 0
	flat_load_dwordx4 v[48:51], v[48:49] offset:16
	s_nop 0
	flat_load_dwordx4 v[52:55], v[104:105] offset:512
	flat_load_dwordx4 v[56:59], v[106:107] offset:512
	s_nop 0
	flat_load_dwordx4 v[60:63], v[60:61] offset:16
	s_nop 0
	flat_load_dwordx4 v[64:67], v[64:65] offset:16
	s_waitcnt vmcnt(0) lgkmcnt(0)
	v_pk_fma_f32 v[32:33], v[36:37], s[14:15], v[32:33] op_sel_hi:[1,0,1]
	v_lshl_add_u64 v[36:37], v[128:129], 0, s[12:13]
	v_pk_fma_f32 v[30:31], v[46:47], s[14:15], v[30:31] op_sel_hi:[1,0,1]
	v_pk_fma_f32 v[28:29], v[44:45], s[14:15], v[28:29] op_sel_hi:[1,0,1]
	global_store_dwordx4 v[36:37], v[28:31], off offset:16
	v_pk_fma_f32 v[22:23], v[50:51], s[14:15], v[22:23] op_sel_hi:[1,0,1]
	v_pk_fma_f32 v[20:21], v[48:49], s[14:15], v[20:21] op_sel_hi:[1,0,1]
	v_lshl_add_u64 v[28:29], v[128:129], 0, s[16:17]
	global_store_dwordx4 v[28:29], v[20:23], off offset:16
	v_pk_fma_f32 v[14:15], v[62:63], s[14:15], v[14:15] op_sel_hi:[1,0,1]
	v_pk_fma_f32 v[12:13], v[60:61], s[14:15], v[12:13] op_sel_hi:[1,0,1]
	v_lshl_add_u64 v[20:21], v[128:129], 0, s[18:19]
	v_pk_fma_f32 v[34:35], v[38:39], s[14:15], v[34:35] op_sel_hi:[1,0,1]
	v_pk_fma_f32 v[26:27], v[42:43], s[14:15], v[26:27] op_sel_hi:[1,0,1]
	v_pk_fma_f32 v[24:25], v[40:41], s[14:15], v[24:25] op_sel_hi:[1,0,1]
	v_pk_fma_f32 v[18:19], v[54:55], s[14:15], v[18:19] op_sel_hi:[1,0,1]
	v_pk_fma_f32 v[16:17], v[52:53], s[14:15], v[16:17] op_sel_hi:[1,0,1]
	global_store_dwordx4 v[20:21], v[12:15], off offset:16
	v_pk_fma_f32 v[10:11], v[58:59], s[14:15], v[10:11] op_sel_hi:[1,0,1]
	v_pk_fma_f32 v[8:9], v[56:57], s[14:15], v[8:9] op_sel_hi:[1,0,1]
	v_lshl_add_u64 v[12:13], v[128:129], 0, s[34:35]
	v_pk_fma_f32 v[6:7], v[66:67], s[14:15], v[6:7] op_sel_hi:[1,0,1]
	v_pk_fma_f32 v[4:5], v[64:65], s[14:15], v[4:5] op_sel_hi:[1,0,1]
	s_and_b64 vcc, exec, s[6:7]
	s_mov_b32 s34, s4
	s_mov_b32 s12, s2
	s_mov_b64 s[14:15], s[10:11]
	s_mov_b64 s[16:17], s[8:9]
	global_store_dwordx4 v[70:71], v[32:35], off offset:512
	global_store_dwordx4 v[68:69], v[24:27], off offset:512
	global_store_dwordx4 v[72:73], v[16:19], off offset:512
	global_store_dwordx4 v[74:75], v[8:11], off offset:512
	global_store_dwordx4 v[12:13], v[4:7], off offset:16
	s_cbranch_vccz .LBB0_616
	s_waitcnt vmcnt(0)
	s_cmpk_gt_u32 s20, 0xff
	s_cbranch_scc1 .LBB0_623
	s_barrier
